# speedup vs baseline: 1.0545x; 1.0077x over previous
; __device__ __forceinline__ void gemm_tile(const GemmArgs& g, bf16* shm, const int tid, const int wid, char* wsb, const float* gnext) {
;     ...
;   } else if (g.epi == EPI_RESID_N) {
;     float* C = (float*)g.C; const float* X = (const float*)g.X;
;     bf16* H = (bf16*)(wsb + WS_ATTO) + (long)g.pm * 256 * DM + g.pn * 256;
;     const float* gn = gnext + g.pn * 256 + cbase;
;     float* rss = (float*)(wsb + WS_RSS) + g.pm * 256;
; #pragma unroll
;     for (int ai = 0; ai < 2; ++ai)
; #pragma unroll
;       for (int m = 0; m < 4; ++m) {
;         const int row = ai * HALF + m * 16 + rbase;
;         float* Cr = C + (long)row * g.ldc + cbase; const float* Xr = X + (long)row * g.ldx + cbase;
;         bf16* Hr = H + (long)row * DM + cbase;
;         float ssq = 0.f;
; #pragma unroll
;         for (int bj = 0; bj < 2; ++bj)
; #pragma unroll
;           for (int n = 0; n < 2; ++n) {
;             const f32x4 r = *reinterpret_cast<const f32x4*>(Xr + bj * HALF + n * 16);
;             const f32x4 v = r + acc[ai][bj][m][n];
;             *reinterpret_cast<f32x4*>(Cr + bj * HALF + n * 16) = v;
;             const f32x4 gg = *reinterpret_cast<const f32x4*>(gn + bj * HALF + n * 16);
;             u32x2 w = {cvtpk(v[0] * gg[0], v[1] * gg[1]), cvtpk(v[2] * gg[2], v[3] * gg[3])};
;             *reinterpret_cast<u32x2*>(Hr + bj * HALF + n * 16) = w;
;             ssq += v[0] * v[0] + v[1] * v[1] + v[2] * v[2] + v[3] * v[3];
;           }
;         ssq += __shfl_xor(ssq, 16, 64); ssq += __shfl_xor(ssq, 32, 64);
;         if (fq == 0) atomicAdd(&rss[row], ssq);
;       }
.LBB0_49:
	s_ashr_i32 s75, s74, 31
	s_lshl_b64 s[0:1], s[74:75], 21
	s_add_u32 s50, s79, s0
	s_addc_u32 s51, s80, s1
	s_lshl_b32 s2, s83, 8
	s_ashr_i32 s3, s2, 31
	s_lshl_b64 s[0:1], s[2:3], 1
	s_add_u32 s50, s50, s0
	s_addc_u32 s51, s51, s1
	s_lshl_b64 s[2:3], s[2:3], 2
	s_add_u32 s48, s63, s2
	s_addc_u32 s49, s78, s3
	s_lshl_b32 s2, s74, 8
	s_ashr_i32 s3, s2, 31
	s_lshl_b64 s[2:3], s[2:3], 2
	s_add_u32 s72, s81, s2
	s_addc_u32 s73, s82, s3
	v_lshlrev_b32_e32 v2, 2, v132
	global_load_dwordx4 v[176:179], v2, s[48:49]
	global_load_dwordx4 v[180:183], v2, s[48:49] offset:64
	global_load_dwordx4 v[184:187], v2, s[48:49] offset:512
	global_load_dwordx2 v[188:189], v2, s[48:49] offset:576
	global_load_dwordx2 v[160:161], v2, s[48:49] offset:584
	v_mul_lo_u32 v133, v0, s67
	v_mul_lo_u32 v134, v0, s66
	s_lshl_b32 s0, s67, 6
	s_lshl_b32 s1, s66, 6
	v_add_lshl_u32 v133, v133, v132, 2
	v_add_lshl_u32 v134, v134, v132, 2
	v_lshlrev_b32_e32 v135, 13, v0
	v_lshl_add_u32 v135, v132, 1, v135
	v_lshlrev_b32_e32 v136, 2, v0
	s_mov_b32 s10, s70
	s_mov_b32 s11, s71
	global_load_dwordx4 v[202:205], v133, s[10:11]
	global_load_dwordx4 v[206:209], v133, s[10:11] offset:64
	global_load_dwordx4 v[210:213], v133, s[10:11] offset:512
	global_load_dwordx4 v[214:217], v133, s[10:11] offset:576
	s_mul_i32 s2, s0, 1
	s_add_u32 s10, s70, s2
	s_addc_u32 s11, s71, 0
	global_load_dwordx4 v[218:221], v133, s[10:11]
	global_load_dwordx4 v[222:225], v133, s[10:11] offset:64
	global_load_dwordx4 v[226:229], v133, s[10:11] offset:512
	global_load_dwordx4 v[230:233], v133, s[10:11] offset:576
	s_mul_i32 s2, s0, 2
	s_add_u32 s10, s70, s2
	s_addc_u32 s11, s71, 0
	global_load_dwordx4 v[234:237], v133, s[10:11]
	global_load_dwordx4 v[238:241], v133, s[10:11] offset:64
	global_load_dwordx4 v[242:245], v133, s[10:11] offset:512
	global_load_dwordx4 v[246:249], v133, s[10:11] offset:576
	s_mul_i32 s2, s0, 3
	s_add_u32 s10, s70, s2
	s_addc_u32 s11, s71, 0
	global_load_dwordx4 v[250:253], v133, s[10:11]
	global_load_dwordx4 v[164:167], v133, s[10:11] offset:64
	global_load_dwordx4 v[168:171], v133, s[10:11] offset:512
	global_load_dwordx4 v[172:175], v133, s[10:11] offset:576
	s_waitcnt vmcnt(15)
	v_pk_add_f32 v[204:205], v[126:127], v[204:205]
	v_pk_add_f32 v[202:203], v[124:125], v[202:203]
	s_mov_b32 s16, s68
	s_mov_b32 s17, s69
	s_mov_b32 s14, s50
	s_mov_b32 s15, s51
	s_mov_b32 s28, s72
	s_mov_b32 s29, s73
	global_store_dwordx4 v134, v[202:205], s[16:17]
	v_mul_f32_e32 v141, v202, v176
	v_mul_f32_e32 v142, v203, v177
	v_cvt_pk_bf16_f32 v138, v141, v142
	v_mul_f32_e32 v141, v204, v178
	v_mul_f32_e32 v142, v205, v179
	v_cvt_pk_bf16_f32 v139, v141, v142
	global_store_dwordx2 v135, v[138:139], s[14:15]
	v_mul_f32_e32 v137, v203, v203
	v_fmac_f32_e32 v137, v202, v202
	v_fmac_f32_e32 v137, v204, v204
	v_fmac_f32_e32 v137, v205, v205
	s_nop 1
	s_mul_i32 s2, s0, 8
	s_add_u32 s10, s70, s2
	s_addc_u32 s11, s71, 0
	global_load_dwordx4 v[202:205], v133, s[10:11]
	s_waitcnt vmcnt(17)
	v_pk_add_f32 v[208:209], v[118:119], v[208:209]
	v_pk_add_f32 v[206:207], v[116:117], v[206:207]
	global_store_dwordx4 v134, v[206:209], s[16:17] offset:64
	v_mul_f32_e32 v141, v206, v180
	v_mul_f32_e32 v142, v207, v181
	v_cvt_pk_bf16_f32 v146, v141, v142
	v_mul_f32_e32 v141, v208, v182
	v_mul_f32_e32 v142, v209, v183
	v_cvt_pk_bf16_f32 v147, v141, v142
	global_store_dwordx2 v135, v[146:147], s[14:15] offset:32
	v_mul_f32_e32 v140, v207, v207
	v_fmac_f32_e32 v140, v206, v206
	v_fmac_f32_e32 v140, v208, v208
	v_fmac_f32_e32 v140, v209, v209
	v_add_f32_e32 v137, v137, v140
	s_nop 1
	global_load_dwordx4 v[206:209], v133, s[10:11] offset:64
	s_waitcnt vmcnt(19)
	v_pk_add_f32 v[212:213], v[130:131], v[212:213]
	v_pk_add_f32 v[210:211], v[128:129], v[210:211]
	global_store_dwordx4 v134, v[210:213], s[16:17] offset:512
	v_mul_f32_e32 v141, v210, v184
	v_mul_f32_e32 v142, v211, v185
	v_cvt_pk_bf16_f32 v138, v141, v142
	v_mul_f32_e32 v141, v212, v186
	v_mul_f32_e32 v142, v213, v187
	v_cvt_pk_bf16_f32 v139, v141, v142
	global_store_dwordx2 v135, v[138:139], s[14:15] offset:256
	v_mul_f32_e32 v140, v211, v211
	v_fmac_f32_e32 v140, v210, v210
	v_fmac_f32_e32 v140, v212, v212
	v_fmac_f32_e32 v140, v213, v213
	v_add_f32_e32 v137, v137, v140
	s_nop 1
	global_load_dwordx4 v[210:213], v133, s[10:11] offset:512
	s_waitcnt vmcnt(21)
	v_pk_add_f32 v[216:217], v[122:123], v[216:217]
	v_pk_add_f32 v[214:215], v[120:121], v[214:215]
	global_store_dwordx4 v134, v[214:217], s[16:17] offset:576
	v_mul_f32_e32 v141, v214, v188
	v_mul_f32_e32 v142, v215, v189
	v_cvt_pk_bf16_f32 v146, v141, v142
	v_mul_f32_e32 v141, v216, v160
	v_mul_f32_e32 v142, v217, v161
	v_cvt_pk_bf16_f32 v147, v141, v142
	global_store_dwordx2 v135, v[146:147], s[14:15] offset:288
	v_mul_f32_e32 v140, v215, v215
	v_fmac_f32_e32 v140, v214, v214
	v_fmac_f32_e32 v140, v216, v216
	v_fmac_f32_e32 v140, v217, v217
	v_add_f32_e32 v137, v137, v140
	ds_bpermute_b32 v143, v158, v137
	s_waitcnt lgkmcnt(0)
	v_add_f32_e32 v137, v137, v143
	ds_bpermute_b32 v143, v159, v137
	s_waitcnt lgkmcnt(0)
	s_and_saveexec_b64 s[6:7], s[4:5]
	v_add_f32_e32 v1, v137, v143
	global_atomic_add_f32 v136, v1, s[28:29]
	s_or_b64 exec, exec, s[6:7]
	s_nop 1
	global_load_dwordx4 v[214:217], v133, s[10:11] offset:576
	s_waitcnt vmcnt(24)
; __device__ __forceinline__ void gemm_tile(const GemmArgs& g, bf16* shm, const int tid, const int wid, char* wsb, const float* gnext) {
;     ...
;   } else if (g.epi == EPI_RESID_N) {
;     float* C = (float*)g.C; const float* X = (const float*)g.X;
;     bf16* H = (bf16*)(wsb + WS_ATTO) + (long)g.pm * 256 * DM + g.pn * 256;
;     const float* gn = gnext + g.pn * 256 + cbase;
;     float* rss = (float*)(wsb + WS_RSS) + g.pm * 256;
; #pragma unroll
;     for (int ai = 0; ai < 2; ++ai)
; #pragma unroll
;       for (int m = 0; m < 4; ++m) {
;         const int row = ai * HALF + m * 16 + rbase;
;         float* Cr = C + (long)row * g.ldc + cbase; const float* Xr = X + (long)row * g.ldx + cbase;
;         bf16* Hr = H + (long)row * DM + cbase;
;         float ssq = 0.f;
; #pragma unroll
;         for (int bj = 0; bj < 2; ++bj)
; #pragma unroll
;           for (int n = 0; n < 2; ++n) {
;             const f32x4 r = *reinterpret_cast<const f32x4*>(Xr + bj * HALF + n * 16);
;             const f32x4 v = r + acc[ai][bj][m][n];
;             *reinterpret_cast<f32x4*>(Cr + bj * HALF + n * 16) = v;
;             const f32x4 gg = *reinterpret_cast<const f32x4*>(gn + bj * HALF + n * 16);
;             u32x2 w = {cvtpk(v[0] * gg[0], v[1] * gg[1]), cvtpk(v[2] * gg[2], v[3] * gg[3])};
;             *reinterpret_cast<u32x2*>(Hr + bj * HALF + n * 16) = w;
;             ssq += v[0] * v[0] + v[1] * v[1] + v[2] * v[2] + v[3] * v[3];
;           }
;         ssq += __shfl_xor(ssq, 16, 64); ssq += __shfl_xor(ssq, 32, 64);
;         if (fq == 0) atomicAdd(&rss[row], ssq);
;       }
	v_pk_add_f32 v[220:221], v[110:111], v[220:221]
	v_pk_add_f32 v[218:219], v[108:109], v[218:219]
	s_mul_i32 s2, s1, 1
	s_add_u32 s16, s68, s2
	s_addc_u32 s17, s69, 0
	s_add_u32 s14, s50, 0x20000
	s_addc_u32 s15, s51, 0
	s_add_u32 s28, s72, 64
	s_addc_u32 s29, s73, 0
	global_store_dwordx4 v134, v[218:221], s[16:17]
	v_mul_f32_e32 v141, v218, v176
	v_mul_f32_e32 v142, v219, v177
	v_cvt_pk_bf16_f32 v138, v141, v142
	v_mul_f32_e32 v141, v220, v178
	v_mul_f32_e32 v142, v221, v179
	v_cvt_pk_bf16_f32 v139, v141, v142
	global_store_dwordx2 v135, v[138:139], s[14:15]
	v_mul_f32_e32 v137, v219, v219
	v_fmac_f32_e32 v137, v218, v218
	v_fmac_f32_e32 v137, v220, v220
	v_fmac_f32_e32 v137, v221, v221
	s_nop 1
	s_mul_i32 s2, s0, 9
	s_add_u32 s10, s70, s2
	s_addc_u32 s11, s71, 0
	global_load_dwordx4 v[218:221], v133, s[10:11]
	s_waitcnt vmcnt(26)
	v_pk_add_f32 v[224:225], v[102:103], v[224:225]
	v_pk_add_f32 v[222:223], v[100:101], v[222:223]
	global_store_dwordx4 v134, v[222:225], s[16:17] offset:64
	v_mul_f32_e32 v141, v222, v180
	v_mul_f32_e32 v142, v223, v181
	v_cvt_pk_bf16_f32 v146, v141, v142
	v_mul_f32_e32 v141, v224, v182
	v_mul_f32_e32 v142, v225, v183
	v_cvt_pk_bf16_f32 v147, v141, v142
	global_store_dwordx2 v135, v[146:147], s[14:15] offset:32
	v_mul_f32_e32 v140, v223, v223
	v_fmac_f32_e32 v140, v222, v222
	v_fmac_f32_e32 v140, v224, v224
	v_fmac_f32_e32 v140, v225, v225
	v_add_f32_e32 v137, v137, v140
	s_nop 1
	global_load_dwordx4 v[222:225], v133, s[10:11] offset:64
	s_waitcnt vmcnt(28)
	v_pk_add_f32 v[228:229], v[114:115], v[228:229]
	v_pk_add_f32 v[226:227], v[112:113], v[226:227]
	global_store_dwordx4 v134, v[226:229], s[16:17] offset:512
	v_mul_f32_e32 v141, v226, v184
	v_mul_f32_e32 v142, v227, v185
	v_cvt_pk_bf16_f32 v138, v141, v142
	v_mul_f32_e32 v141, v228, v186
	v_mul_f32_e32 v142, v229, v187
	v_cvt_pk_bf16_f32 v139, v141, v142
	global_store_dwordx2 v135, v[138:139], s[14:15] offset:256
	v_mul_f32_e32 v140, v227, v227
	v_fmac_f32_e32 v140, v226, v226
	v_fmac_f32_e32 v140, v228, v228
	v_fmac_f32_e32 v140, v229, v229
	v_add_f32_e32 v137, v137, v140
	s_nop 1
	global_load_dwordx4 v[226:229], v133, s[10:11] offset:512
	s_waitcnt vmcnt(30)
	v_pk_add_f32 v[232:233], v[106:107], v[232:233]
	v_pk_add_f32 v[230:231], v[104:105], v[230:231]
	global_store_dwordx4 v134, v[230:233], s[16:17] offset:576
	v_mul_f32_e32 v141, v230, v188
	v_mul_f32_e32 v142, v231, v189
	v_cvt_pk_bf16_f32 v146, v141, v142
	v_mul_f32_e32 v141, v232, v160
	v_mul_f32_e32 v142, v233, v161
	v_cvt_pk_bf16_f32 v147, v141, v142
	global_store_dwordx2 v135, v[146:147], s[14:15] offset:288
	v_mul_f32_e32 v140, v231, v231
	v_fmac_f32_e32 v140, v230, v230
	v_fmac_f32_e32 v140, v232, v232
	v_fmac_f32_e32 v140, v233, v233
	v_add_f32_e32 v137, v137, v140
	ds_bpermute_b32 v143, v158, v137
	s_waitcnt lgkmcnt(0)
	v_add_f32_e32 v137, v137, v143
	ds_bpermute_b32 v143, v159, v137
	s_waitcnt lgkmcnt(0)
	s_and_saveexec_b64 s[6:7], s[4:5]
	v_add_f32_e32 v1, v137, v143
	global_atomic_add_f32 v136, v1, s[28:29]
	s_or_b64 exec, exec, s[6:7]
	s_nop 1
	global_load_dwordx4 v[230:233], v133, s[10:11] offset:576
	s_waitcnt vmcnt(33)
	v_pk_add_f32 v[236:237], v[94:95], v[236:237]
	v_pk_add_f32 v[234:235], v[92:93], v[234:235]
	s_mul_i32 s2, s1, 2
	s_add_u32 s16, s68, s2
	s_addc_u32 s17, s69, 0
	s_add_u32 s14, s50, 0x40000
	s_addc_u32 s15, s51, 0
	s_add_u32 s28, s72, 128
	s_addc_u32 s29, s73, 0
	global_store_dwordx4 v134, v[234:237], s[16:17]
	v_mul_f32_e32 v141, v234, v176
	v_mul_f32_e32 v142, v235, v177
	v_cvt_pk_bf16_f32 v138, v141, v142
	v_mul_f32_e32 v141, v236, v178
	v_mul_f32_e32 v142, v237, v179
	v_cvt_pk_bf16_f32 v139, v141, v142
	global_store_dwordx2 v135, v[138:139], s[14:15]
	v_mul_f32_e32 v137, v235, v235
	v_fmac_f32_e32 v137, v234, v234
	v_fmac_f32_e32 v137, v236, v236
	v_fmac_f32_e32 v137, v237, v237
	s_nop 1
	s_mul_i32 s2, s0, 10
	s_add_u32 s10, s70, s2
	s_addc_u32 s11, s71, 0
	global_load_dwordx4 v[234:237], v133, s[10:11]
	s_waitcnt vmcnt(35)
	v_pk_add_f32 v[240:241], v[86:87], v[240:241]
	v_pk_add_f32 v[238:239], v[84:85], v[238:239]
	global_store_dwordx4 v134, v[238:241], s[16:17] offset:64
	v_mul_f32_e32 v141, v238, v180
	v_mul_f32_e32 v142, v239, v181
	v_cvt_pk_bf16_f32 v146, v141, v142
	v_mul_f32_e32 v141, v240, v182
	v_mul_f32_e32 v142, v241, v183
	v_cvt_pk_bf16_f32 v147, v141, v142
	global_store_dwordx2 v135, v[146:147], s[14:15] offset:32
	v_mul_f32_e32 v140, v239, v239
	v_fmac_f32_e32 v140, v238, v238
	v_fmac_f32_e32 v140, v240, v240
	v_fmac_f32_e32 v140, v241, v241
	v_add_f32_e32 v137, v137, v140
	s_nop 1
	global_load_dwordx4 v[238:241], v133, s[10:11] offset:64
	s_waitcnt vmcnt(37)
	v_pk_add_f32 v[244:245], v[98:99], v[244:245]
	v_pk_add_f32 v[242:243], v[96:97], v[242:243]
	global_store_dwordx4 v134, v[242:245], s[16:17] offset:512
	v_mul_f32_e32 v141, v242, v184
	v_mul_f32_e32 v142, v243, v185
	v_cvt_pk_bf16_f32 v138, v141, v142
	v_mul_f32_e32 v141, v244, v186
	v_mul_f32_e32 v142, v245, v187
	v_cvt_pk_bf16_f32 v139, v141, v142
	global_store_dwordx2 v135, v[138:139], s[14:15] offset:256
	v_mul_f32_e32 v140, v243, v243
	v_fmac_f32_e32 v140, v242, v242
	v_fmac_f32_e32 v140, v244, v244
	v_fmac_f32_e32 v140, v245, v245
	v_add_f32_e32 v137, v137, v140
	s_nop 1
	global_load_dwordx4 v[242:245], v133, s[10:11] offset:512
	s_waitcnt vmcnt(39)
	v_pk_add_f32 v[248:249], v[90:91], v[248:249]
	v_pk_add_f32 v[246:247], v[88:89], v[246:247]
	global_store_dwordx4 v134, v[246:249], s[16:17] offset:576
	v_mul_f32_e32 v141, v246, v188
	v_mul_f32_e32 v142, v247, v189
	v_cvt_pk_bf16_f32 v146, v141, v142
	v_mul_f32_e32 v141, v248, v160
	v_mul_f32_e32 v142, v249, v161
	v_cvt_pk_bf16_f32 v147, v141, v142
	global_store_dwordx2 v135, v[146:147], s[14:15] offset:288
	v_mul_f32_e32 v140, v247, v247
	v_fmac_f32_e32 v140, v246, v246
	v_fmac_f32_e32 v140, v248, v248
	v_fmac_f32_e32 v140, v249, v249
	v_add_f32_e32 v137, v137, v140
	ds_bpermute_b32 v143, v158, v137
	s_waitcnt lgkmcnt(0)
; __device__ __forceinline__ void gemm_tile(const GemmArgs& g, bf16* shm, const int tid, const int wid, char* wsb, const float* gnext) {
;     ...
;   } else if (g.epi == EPI_RESID_N) {
;     float* C = (float*)g.C; const float* X = (const float*)g.X;
;     bf16* H = (bf16*)(wsb + WS_ATTO) + (long)g.pm * 256 * DM + g.pn * 256;
;     const float* gn = gnext + g.pn * 256 + cbase;
;     float* rss = (float*)(wsb + WS_RSS) + g.pm * 256;
; #pragma unroll
;     for (int ai = 0; ai < 2; ++ai)
; #pragma unroll
;       for (int m = 0; m < 4; ++m) {
;         const int row = ai * HALF + m * 16 + rbase;
;         float* Cr = C + (long)row * g.ldc + cbase; const float* Xr = X + (long)row * g.ldx + cbase;
;         bf16* Hr = H + (long)row * DM + cbase;
;         float ssq = 0.f;
; #pragma unroll
;         for (int bj = 0; bj < 2; ++bj)
; #pragma unroll
;           for (int n = 0; n < 2; ++n) {
;             const f32x4 r = *reinterpret_cast<const f32x4*>(Xr + bj * HALF + n * 16);
;             const f32x4 v = r + acc[ai][bj][m][n];
;             *reinterpret_cast<f32x4*>(Cr + bj * HALF + n * 16) = v;
;             const f32x4 gg = *reinterpret_cast<const f32x4*>(gn + bj * HALF + n * 16);
;             u32x2 w = {cvtpk(v[0] * gg[0], v[1] * gg[1]), cvtpk(v[2] * gg[2], v[3] * gg[3])};
;             *reinterpret_cast<u32x2*>(Hr + bj * HALF + n * 16) = w;
;             ssq += v[0] * v[0] + v[1] * v[1] + v[2] * v[2] + v[3] * v[3];
;           }
;         ssq += __shfl_xor(ssq, 16, 64); ssq += __shfl_xor(ssq, 32, 64);
;         if (fq == 0) atomicAdd(&rss[row], ssq);
;       }
	v_add_f32_e32 v137, v137, v143
	ds_bpermute_b32 v143, v159, v137
	s_waitcnt lgkmcnt(0)
	s_and_saveexec_b64 s[6:7], s[4:5]
	v_add_f32_e32 v1, v137, v143
	global_atomic_add_f32 v136, v1, s[28:29]
	s_or_b64 exec, exec, s[6:7]
	s_nop 1
	global_load_dwordx4 v[246:249], v133, s[10:11] offset:576
	s_waitcnt vmcnt(42)
	v_pk_add_f32 v[252:253], v[78:79], v[252:253]
	v_pk_add_f32 v[250:251], v[76:77], v[250:251]
	s_mul_i32 s2, s1, 3
	s_add_u32 s16, s68, s2
	s_addc_u32 s17, s69, 0
	s_add_u32 s14, s50, 0x60000
	s_addc_u32 s15, s51, 0
	s_add_u32 s28, s72, 192
	s_addc_u32 s29, s73, 0
	global_store_dwordx4 v134, v[250:253], s[16:17]
	v_mul_f32_e32 v141, v250, v176
	v_mul_f32_e32 v142, v251, v177
	v_cvt_pk_bf16_f32 v138, v141, v142
	v_mul_f32_e32 v141, v252, v178
	v_mul_f32_e32 v142, v253, v179
	v_cvt_pk_bf16_f32 v139, v141, v142
	global_store_dwordx2 v135, v[138:139], s[14:15]
	v_mul_f32_e32 v137, v251, v251
	v_fmac_f32_e32 v137, v250, v250
	v_fmac_f32_e32 v137, v252, v252
	v_fmac_f32_e32 v137, v253, v253
	s_nop 1
	s_mul_i32 s2, s0, 11
	s_add_u32 s10, s70, s2
	s_addc_u32 s11, s71, 0
	global_load_dwordx4 v[250:253], v133, s[10:11]
	s_waitcnt vmcnt(44)
	v_pk_add_f32 v[166:167], v[70:71], v[166:167]
	v_pk_add_f32 v[164:165], v[68:69], v[164:165]
	global_store_dwordx4 v134, v[164:167], s[16:17] offset:64
	v_mul_f32_e32 v141, v164, v180
	v_mul_f32_e32 v142, v165, v181
	v_cvt_pk_bf16_f32 v146, v141, v142
	v_mul_f32_e32 v141, v166, v182
	v_mul_f32_e32 v142, v167, v183
	v_cvt_pk_bf16_f32 v147, v141, v142
	global_store_dwordx2 v135, v[146:147], s[14:15] offset:32
	v_mul_f32_e32 v140, v165, v165
	v_fmac_f32_e32 v140, v164, v164
	v_fmac_f32_e32 v140, v166, v166
	v_fmac_f32_e32 v140, v167, v167
	v_add_f32_e32 v137, v137, v140
	s_nop 1
	global_load_dwordx4 v[164:167], v133, s[10:11] offset:64
	s_waitcnt vmcnt(46)
	v_pk_add_f32 v[170:171], v[82:83], v[170:171]
	v_pk_add_f32 v[168:169], v[80:81], v[168:169]
	global_store_dwordx4 v134, v[168:171], s[16:17] offset:512
	v_mul_f32_e32 v141, v168, v184
	v_mul_f32_e32 v142, v169, v185
	v_cvt_pk_bf16_f32 v138, v141, v142
	v_mul_f32_e32 v141, v170, v186
	v_mul_f32_e32 v142, v171, v187
	v_cvt_pk_bf16_f32 v139, v141, v142
	global_store_dwordx2 v135, v[138:139], s[14:15] offset:256
	v_mul_f32_e32 v140, v169, v169
	v_fmac_f32_e32 v140, v168, v168
	v_fmac_f32_e32 v140, v170, v170
	v_fmac_f32_e32 v140, v171, v171
	v_add_f32_e32 v137, v137, v140
	s_nop 1
	global_load_dwordx4 v[168:171], v133, s[10:11] offset:512
	s_waitcnt vmcnt(48)
	v_pk_add_f32 v[174:175], v[74:75], v[174:175]
	v_pk_add_f32 v[172:173], v[72:73], v[172:173]
	global_store_dwordx4 v134, v[172:175], s[16:17] offset:576
	v_mul_f32_e32 v141, v172, v188
	v_mul_f32_e32 v142, v173, v189
	v_cvt_pk_bf16_f32 v146, v141, v142
	v_mul_f32_e32 v141, v174, v160
	v_mul_f32_e32 v142, v175, v161
	v_cvt_pk_bf16_f32 v147, v141, v142
	global_store_dwordx2 v135, v[146:147], s[14:15] offset:288
	v_mul_f32_e32 v140, v173, v173
	v_fmac_f32_e32 v140, v172, v172
	v_fmac_f32_e32 v140, v174, v174
	v_fmac_f32_e32 v140, v175, v175
	v_add_f32_e32 v137, v137, v140
	ds_bpermute_b32 v143, v158, v137
	s_waitcnt lgkmcnt(0)
	v_add_f32_e32 v137, v137, v143
	ds_bpermute_b32 v143, v159, v137
	s_waitcnt lgkmcnt(0)
	s_and_saveexec_b64 s[6:7], s[4:5]
	v_add_f32_e32 v1, v137, v143
	global_atomic_add_f32 v136, v1, s[28:29]
	s_or_b64 exec, exec, s[6:7]
	s_nop 1
	global_load_dwordx4 v[172:175], v133, s[10:11] offset:576
	s_waitcnt vmcnt(49)
	v_pk_add_f32 v[204:205], v[66:67], v[204:205]
	v_pk_add_f32 v[202:203], v[64:65], v[202:203]
	s_mul_i32 s2, s1, 8
	s_add_u32 s16, s68, s2
	s_addc_u32 s17, s69, 0
	s_add_u32 s14, s50, 0x100000
	s_addc_u32 s15, s51, 0
	s_add_u32 s28, s72, 512
	s_addc_u32 s29, s73, 0
	global_store_dwordx4 v134, v[202:205], s[16:17]
	v_mul_f32_e32 v141, v202, v176
	v_mul_f32_e32 v142, v203, v177
	v_cvt_pk_bf16_f32 v138, v141, v142
	v_mul_f32_e32 v141, v204, v178
	v_mul_f32_e32 v142, v205, v179
	v_cvt_pk_bf16_f32 v139, v141, v142
	global_store_dwordx2 v135, v[138:139], s[14:15]
	v_mul_f32_e32 v137, v203, v203
	v_fmac_f32_e32 v137, v202, v202
	v_fmac_f32_e32 v137, v204, v204
	v_fmac_f32_e32 v137, v205, v205
	s_waitcnt vmcnt(48)
	v_pk_add_f32 v[208:209], v[58:59], v[208:209]
	v_pk_add_f32 v[206:207], v[56:57], v[206:207]
	global_store_dwordx4 v134, v[206:209], s[16:17] offset:64
	v_mul_f32_e32 v141, v206, v180
	v_mul_f32_e32 v142, v207, v181
	v_cvt_pk_bf16_f32 v146, v141, v142
	v_mul_f32_e32 v141, v208, v182
	v_mul_f32_e32 v142, v209, v183
	v_cvt_pk_bf16_f32 v147, v141, v142
	global_store_dwordx2 v135, v[146:147], s[14:15] offset:32
	v_mul_f32_e32 v140, v207, v207
	v_fmac_f32_e32 v140, v206, v206
	v_fmac_f32_e32 v140, v208, v208
	v_fmac_f32_e32 v140, v209, v209
	v_add_f32_e32 v137, v137, v140
	s_waitcnt vmcnt(47)
	v_pk_add_f32 v[212:213], v[62:63], v[212:213]
	v_pk_add_f32 v[210:211], v[60:61], v[210:211]
	global_store_dwordx4 v134, v[210:213], s[16:17] offset:512
	v_mul_f32_e32 v141, v210, v184
	v_mul_f32_e32 v142, v211, v185
	v_cvt_pk_bf16_f32 v138, v141, v142
	v_mul_f32_e32 v141, v212, v186
	v_mul_f32_e32 v142, v213, v187
	v_cvt_pk_bf16_f32 v139, v141, v142
	global_store_dwordx2 v135, v[138:139], s[14:15] offset:256
	v_mul_f32_e32 v140, v211, v211
	v_fmac_f32_e32 v140, v210, v210
	v_fmac_f32_e32 v140, v212, v212
	v_fmac_f32_e32 v140, v213, v213
	v_add_f32_e32 v137, v137, v140
	s_waitcnt vmcnt(45)
; __device__ __forceinline__ void gemm_tile(const GemmArgs& g, bf16* shm, const int tid, const int wid, char* wsb, const float* gnext) {
;     ...
;   } else if (g.epi == EPI_RESID_N) {
;     float* C = (float*)g.C; const float* X = (const float*)g.X;
;     bf16* H = (bf16*)(wsb + WS_ATTO) + (long)g.pm * 256 * DM + g.pn * 256;
;     const float* gn = gnext + g.pn * 256 + cbase;
;     float* rss = (float*)(wsb + WS_RSS) + g.pm * 256;
; #pragma unroll
;     for (int ai = 0; ai < 2; ++ai)
; #pragma unroll
;       for (int m = 0; m < 4; ++m) {
;         const int row = ai * HALF + m * 16 + rbase;
;         float* Cr = C + (long)row * g.ldc + cbase; const float* Xr = X + (long)row * g.ldx + cbase;
;         bf16* Hr = H + (long)row * DM + cbase;
;         float ssq = 0.f;
; #pragma unroll
;         for (int bj = 0; bj < 2; ++bj)
; #pragma unroll
;           for (int n = 0; n < 2; ++n) {
;             const f32x4 r = *reinterpret_cast<const f32x4*>(Xr + bj * HALF + n * 16);
;             const f32x4 v = r + acc[ai][bj][m][n];
;             *reinterpret_cast<f32x4*>(Cr + bj * HALF + n * 16) = v;
;             const f32x4 gg = *reinterpret_cast<const f32x4*>(gn + bj * HALF + n * 16);
;             u32x2 w = {cvtpk(v[0] * gg[0], v[1] * gg[1]), cvtpk(v[2] * gg[2], v[3] * gg[3])};
;             *reinterpret_cast<u32x2*>(Hr + bj * HALF + n * 16) = w;
;             ssq += v[0] * v[0] + v[1] * v[1] + v[2] * v[2] + v[3] * v[3];
;           }
;         ssq += __shfl_xor(ssq, 16, 64); ssq += __shfl_xor(ssq, 32, 64);
;         if (fq == 0) atomicAdd(&rss[row], ssq);
;       }
	v_pk_add_f32 v[216:217], v[54:55], v[216:217]
	v_pk_add_f32 v[214:215], v[52:53], v[214:215]
	global_store_dwordx4 v134, v[214:217], s[16:17] offset:576
	v_mul_f32_e32 v141, v214, v188
	v_mul_f32_e32 v142, v215, v189
	v_cvt_pk_bf16_f32 v146, v141, v142
	v_mul_f32_e32 v141, v216, v160
	v_mul_f32_e32 v142, v217, v161
	v_cvt_pk_bf16_f32 v147, v141, v142
	global_store_dwordx2 v135, v[146:147], s[14:15] offset:288
	v_mul_f32_e32 v140, v215, v215
	v_fmac_f32_e32 v140, v214, v214
	v_fmac_f32_e32 v140, v216, v216
	v_fmac_f32_e32 v140, v217, v217
	v_add_f32_e32 v137, v137, v140
	ds_bpermute_b32 v143, v158, v137
	s_waitcnt lgkmcnt(0)
	v_add_f32_e32 v137, v137, v143
	ds_bpermute_b32 v143, v159, v137
	s_waitcnt lgkmcnt(0)
	s_and_saveexec_b64 s[6:7], s[4:5]
	v_add_f32_e32 v1, v137, v143
	global_atomic_add_f32 v136, v1, s[28:29]
	s_or_b64 exec, exec, s[6:7]
	s_waitcnt vmcnt(45)
	v_pk_add_f32 v[220:221], v[50:51], v[220:221]
	v_pk_add_f32 v[218:219], v[48:49], v[218:219]
	s_mul_i32 s2, s1, 9
	s_add_u32 s16, s68, s2
	s_addc_u32 s17, s69, 0
	s_add_u32 s14, s50, 0x120000
	s_addc_u32 s15, s51, 0
	s_add_u32 s28, s72, 576
	s_addc_u32 s29, s73, 0
	global_store_dwordx4 v134, v[218:221], s[16:17]
	v_mul_f32_e32 v141, v218, v176
	v_mul_f32_e32 v142, v219, v177
	v_cvt_pk_bf16_f32 v138, v141, v142
	v_mul_f32_e32 v141, v220, v178
	v_mul_f32_e32 v142, v221, v179
	v_cvt_pk_bf16_f32 v139, v141, v142
	global_store_dwordx2 v135, v[138:139], s[14:15]
	v_mul_f32_e32 v137, v219, v219
	v_fmac_f32_e32 v137, v218, v218
	v_fmac_f32_e32 v137, v220, v220
	v_fmac_f32_e32 v137, v221, v221
	s_waitcnt vmcnt(44)
	v_pk_add_f32 v[224:225], v[42:43], v[224:225]
	v_pk_add_f32 v[222:223], v[40:41], v[222:223]
	global_store_dwordx4 v134, v[222:225], s[16:17] offset:64
	v_mul_f32_e32 v141, v222, v180
	v_mul_f32_e32 v142, v223, v181
	v_cvt_pk_bf16_f32 v146, v141, v142
	v_mul_f32_e32 v141, v224, v182
	v_mul_f32_e32 v142, v225, v183
	v_cvt_pk_bf16_f32 v147, v141, v142
	global_store_dwordx2 v135, v[146:147], s[14:15] offset:32
	v_mul_f32_e32 v140, v223, v223
	v_fmac_f32_e32 v140, v222, v222
	v_fmac_f32_e32 v140, v224, v224
	v_fmac_f32_e32 v140, v225, v225
	v_add_f32_e32 v137, v137, v140
	s_waitcnt vmcnt(43)
	v_pk_add_f32 v[228:229], v[46:47], v[228:229]
	v_pk_add_f32 v[226:227], v[44:45], v[226:227]
	global_store_dwordx4 v134, v[226:229], s[16:17] offset:512
	v_mul_f32_e32 v141, v226, v184
	v_mul_f32_e32 v142, v227, v185
	v_cvt_pk_bf16_f32 v138, v141, v142
	v_mul_f32_e32 v141, v228, v186
	v_mul_f32_e32 v142, v229, v187
	v_cvt_pk_bf16_f32 v139, v141, v142
	global_store_dwordx2 v135, v[138:139], s[14:15] offset:256
	v_mul_f32_e32 v140, v227, v227
	v_fmac_f32_e32 v140, v226, v226
	v_fmac_f32_e32 v140, v228, v228
	v_fmac_f32_e32 v140, v229, v229
	v_add_f32_e32 v137, v137, v140
	s_waitcnt vmcnt(41)
	v_pk_add_f32 v[232:233], v[38:39], v[232:233]
	v_pk_add_f32 v[230:231], v[36:37], v[230:231]
	global_store_dwordx4 v134, v[230:233], s[16:17] offset:576
	v_mul_f32_e32 v141, v230, v188
	v_mul_f32_e32 v142, v231, v189
	v_cvt_pk_bf16_f32 v146, v141, v142
	v_mul_f32_e32 v141, v232, v160
	v_mul_f32_e32 v142, v233, v161
	v_cvt_pk_bf16_f32 v147, v141, v142
	global_store_dwordx2 v135, v[146:147], s[14:15] offset:288
	v_mul_f32_e32 v140, v231, v231
	v_fmac_f32_e32 v140, v230, v230
	v_fmac_f32_e32 v140, v232, v232
	v_fmac_f32_e32 v140, v233, v233
	v_add_f32_e32 v137, v137, v140
	ds_bpermute_b32 v143, v158, v137
	s_waitcnt lgkmcnt(0)
	v_add_f32_e32 v137, v137, v143
	ds_bpermute_b32 v143, v159, v137
	s_waitcnt lgkmcnt(0)
	s_and_saveexec_b64 s[6:7], s[4:5]
	v_add_f32_e32 v1, v137, v143
	global_atomic_add_f32 v136, v1, s[28:29]
	s_or_b64 exec, exec, s[6:7]
	s_waitcnt vmcnt(41)
	v_pk_add_f32 v[236:237], v[34:35], v[236:237]
	v_pk_add_f32 v[234:235], v[32:33], v[234:235]
	s_mul_i32 s2, s1, 10
	s_add_u32 s16, s68, s2
	s_addc_u32 s17, s69, 0
	s_add_u32 s14, s50, 0x140000
	s_addc_u32 s15, s51, 0
	s_add_u32 s28, s72, 640
	s_addc_u32 s29, s73, 0
	global_store_dwordx4 v134, v[234:237], s[16:17]
	v_mul_f32_e32 v141, v234, v176
	v_mul_f32_e32 v142, v235, v177
	v_cvt_pk_bf16_f32 v138, v141, v142
	v_mul_f32_e32 v141, v236, v178
	v_mul_f32_e32 v142, v237, v179
	v_cvt_pk_bf16_f32 v139, v141, v142
	global_store_dwordx2 v135, v[138:139], s[14:15]
	v_mul_f32_e32 v137, v235, v235
	v_fmac_f32_e32 v137, v234, v234
	v_fmac_f32_e32 v137, v236, v236
	v_fmac_f32_e32 v137, v237, v237
	s_waitcnt vmcnt(40)
; __device__ __forceinline__ void gemm_tile(const GemmArgs& g, bf16* shm, const int tid, const int wid, char* wsb, const float* gnext) {
;     ...
;   } else if (g.epi == EPI_RESID_N) {
;     float* C = (float*)g.C; const float* X = (const float*)g.X;
;     bf16* H = (bf16*)(wsb + WS_ATTO) + (long)g.pm * 256 * DM + g.pn * 256;
;     const float* gn = gnext + g.pn * 256 + cbase;
;     float* rss = (float*)(wsb + WS_RSS) + g.pm * 256;
; #pragma unroll
;     for (int ai = 0; ai < 2; ++ai)
; #pragma unroll
;       for (int m = 0; m < 4; ++m) {
;         const int row = ai * HALF + m * 16 + rbase;
;         float* Cr = C + (long)row * g.ldc + cbase; const float* Xr = X + (long)row * g.ldx + cbase;
;         bf16* Hr = H + (long)row * DM + cbase;
;         float ssq = 0.f;
; #pragma unroll
;         for (int bj = 0; bj < 2; ++bj)
; #pragma unroll
;           for (int n = 0; n < 2; ++n) {
;             const f32x4 r = *reinterpret_cast<const f32x4*>(Xr + bj * HALF + n * 16);
;             const f32x4 v = r + acc[ai][bj][m][n];
;             *reinterpret_cast<f32x4*>(Cr + bj * HALF + n * 16) = v;
;             const f32x4 gg = *reinterpret_cast<const f32x4*>(gn + bj * HALF + n * 16);
;             u32x2 w = {cvtpk(v[0] * gg[0], v[1] * gg[1]), cvtpk(v[2] * gg[2], v[3] * gg[3])};
;             *reinterpret_cast<u32x2*>(Hr + bj * HALF + n * 16) = w;
;             ssq += v[0] * v[0] + v[1] * v[1] + v[2] * v[2] + v[3] * v[3];
;           }
;         ssq += __shfl_xor(ssq, 16, 64); ssq += __shfl_xor(ssq, 32, 64);
;         if (fq == 0) atomicAdd(&rss[row], ssq);
;       }
	v_pk_add_f32 v[240:241], v[26:27], v[240:241]
	v_pk_add_f32 v[238:239], v[24:25], v[238:239]
	global_store_dwordx4 v134, v[238:241], s[16:17] offset:64
	v_mul_f32_e32 v141, v238, v180
	v_mul_f32_e32 v142, v239, v181
	v_cvt_pk_bf16_f32 v146, v141, v142
	v_mul_f32_e32 v141, v240, v182
	v_mul_f32_e32 v142, v241, v183
	v_cvt_pk_bf16_f32 v147, v141, v142
	global_store_dwordx2 v135, v[146:147], s[14:15] offset:32
	v_mul_f32_e32 v140, v239, v239
	v_fmac_f32_e32 v140, v238, v238
	v_fmac_f32_e32 v140, v240, v240
	v_fmac_f32_e32 v140, v241, v241
	v_add_f32_e32 v137, v137, v140
	s_waitcnt vmcnt(39)
	v_pk_add_f32 v[244:245], v[30:31], v[244:245]
	v_pk_add_f32 v[242:243], v[28:29], v[242:243]
	global_store_dwordx4 v134, v[242:245], s[16:17] offset:512
	v_mul_f32_e32 v141, v242, v184
	v_mul_f32_e32 v142, v243, v185
	v_cvt_pk_bf16_f32 v138, v141, v142
	v_mul_f32_e32 v141, v244, v186
	v_mul_f32_e32 v142, v245, v187
	v_cvt_pk_bf16_f32 v139, v141, v142
	global_store_dwordx2 v135, v[138:139], s[14:15] offset:256
	v_mul_f32_e32 v140, v243, v243
	v_fmac_f32_e32 v140, v242, v242
	v_fmac_f32_e32 v140, v244, v244
	v_fmac_f32_e32 v140, v245, v245
	v_add_f32_e32 v137, v137, v140
	s_waitcnt vmcnt(37)
	v_pk_add_f32 v[248:249], v[22:23], v[248:249]
	v_pk_add_f32 v[246:247], v[20:21], v[246:247]
	global_store_dwordx4 v134, v[246:249], s[16:17] offset:576
	v_mul_f32_e32 v141, v246, v188
	v_mul_f32_e32 v142, v247, v189
	v_cvt_pk_bf16_f32 v146, v141, v142
	v_mul_f32_e32 v141, v248, v160
	v_mul_f32_e32 v142, v249, v161
	v_cvt_pk_bf16_f32 v147, v141, v142
	global_store_dwordx2 v135, v[146:147], s[14:15] offset:288
	v_mul_f32_e32 v140, v247, v247
	v_fmac_f32_e32 v140, v246, v246
	v_fmac_f32_e32 v140, v248, v248
	v_fmac_f32_e32 v140, v249, v249
	v_add_f32_e32 v137, v137, v140
	ds_bpermute_b32 v143, v158, v137
	s_waitcnt lgkmcnt(0)
	v_add_f32_e32 v137, v137, v143
	ds_bpermute_b32 v143, v159, v137
	s_waitcnt lgkmcnt(0)
	s_and_saveexec_b64 s[6:7], s[4:5]
	v_add_f32_e32 v1, v137, v143
	global_atomic_add_f32 v136, v1, s[28:29]
	s_or_b64 exec, exec, s[6:7]
	s_waitcnt vmcnt(37)
	v_pk_add_f32 v[252:253], v[18:19], v[252:253]
	v_pk_add_f32 v[250:251], v[16:17], v[250:251]
	s_mul_i32 s2, s1, 11
	s_add_u32 s16, s68, s2
	s_addc_u32 s17, s69, 0
	s_add_u32 s14, s50, 0x160000
	s_addc_u32 s15, s51, 0
	s_add_u32 s28, s72, 704
	s_addc_u32 s29, s73, 0
	global_store_dwordx4 v134, v[250:253], s[16:17]
	v_mul_f32_e32 v141, v250, v176
	v_mul_f32_e32 v142, v251, v177
	v_cvt_pk_bf16_f32 v138, v141, v142
	v_mul_f32_e32 v141, v252, v178
	v_mul_f32_e32 v142, v253, v179
	v_cvt_pk_bf16_f32 v139, v141, v142
	global_store_dwordx2 v135, v[138:139], s[14:15]
	v_mul_f32_e32 v137, v251, v251
	v_fmac_f32_e32 v137, v250, v250
	v_fmac_f32_e32 v137, v252, v252
	v_fmac_f32_e32 v137, v253, v253
	s_waitcnt vmcnt(36)
	v_pk_add_f32 v[166:167], v[10:11], v[166:167]
	v_pk_add_f32 v[164:165], v[8:9], v[164:165]
	global_store_dwordx4 v134, v[164:167], s[16:17] offset:64
	v_mul_f32_e32 v141, v164, v180
	v_mul_f32_e32 v142, v165, v181
	v_cvt_pk_bf16_f32 v146, v141, v142
	v_mul_f32_e32 v141, v166, v182
	v_mul_f32_e32 v142, v167, v183
	v_cvt_pk_bf16_f32 v147, v141, v142
	global_store_dwordx2 v135, v[146:147], s[14:15] offset:32
	v_mul_f32_e32 v140, v165, v165
	v_fmac_f32_e32 v140, v164, v164
	v_fmac_f32_e32 v140, v166, v166
	v_fmac_f32_e32 v140, v167, v167
	v_add_f32_e32 v137, v137, v140
	s_waitcnt vmcnt(35)
	v_pk_add_f32 v[170:171], v[14:15], v[170:171]
	v_pk_add_f32 v[168:169], v[12:13], v[168:169]
	global_store_dwordx4 v134, v[168:171], s[16:17] offset:512
	v_mul_f32_e32 v141, v168, v184
	v_mul_f32_e32 v142, v169, v185
	v_cvt_pk_bf16_f32 v138, v141, v142
	v_mul_f32_e32 v141, v170, v186
	v_mul_f32_e32 v142, v171, v187
	v_cvt_pk_bf16_f32 v139, v141, v142
	global_store_dwordx2 v135, v[138:139], s[14:15] offset:256
	v_mul_f32_e32 v140, v169, v169
	v_fmac_f32_e32 v140, v168, v168
	v_fmac_f32_e32 v140, v170, v170
	v_fmac_f32_e32 v140, v171, v171
	v_add_f32_e32 v137, v137, v140
	s_waitcnt vmcnt(33)
	v_pk_add_f32 v[174:175], v[6:7], v[174:175]
	v_pk_add_f32 v[172:173], v[4:5], v[172:173]
	global_store_dwordx4 v134, v[172:175], s[16:17] offset:576
	v_mul_f32_e32 v141, v172, v188
	v_mul_f32_e32 v142, v173, v189
	v_cvt_pk_bf16_f32 v146, v141, v142
	v_mul_f32_e32 v141, v174, v160
	v_mul_f32_e32 v142, v175, v161
	v_cvt_pk_bf16_f32 v147, v141, v142
	global_store_dwordx2 v135, v[146:147], s[14:15] offset:288
	v_mul_f32_e32 v140, v173, v173
	v_fmac_f32_e32 v140, v172, v172
	v_fmac_f32_e32 v140, v174, v174
	v_fmac_f32_e32 v140, v175, v175
	v_add_f32_e32 v137, v137, v140
	ds_bpermute_b32 v143, v158, v137
	s_waitcnt lgkmcnt(0)
	v_add_f32_e32 v137, v137, v143
	ds_bpermute_b32 v143, v159, v137
	s_waitcnt lgkmcnt(0)
	s_and_saveexec_b64 s[6:7], s[4:5]
	v_add_f32_e32 v1, v137, v143
	global_atomic_add_f32 v136, v1, s[28:29]
	s_or_b64 exec, exec, s[6:7]
	s_mov_b64 s[6:7], 0
	s_mov_b64 s[72:73], 0

; __device__ __forceinline__ float bf_lo(unsigned u) { return __uint_as_float(u << 16); }
; __device__ __forceinline__ float bf_hi(unsigned u) { return __uint_as_float(u & 0xffff0000u); }
; __device__ __forceinline__ float silu(float z) { return z / (1.f + __expf(-z)); }
; __device__ __forceinline__ void gemm_tile(const GemmArgs& g, bf16* shm, const int tid, const int wid, char* wsb, const float* gnext) {
;     ...
;   } else if (g.epi == EPI_GATE) {
;     bf16* C = (bf16*)g.C; const bf16* Z = (const bf16*)g.X;
; #pragma unroll
;     for (int ai = 0; ai < 2; ++ai)
; #pragma unroll
;       for (int m = 0; m < 4; ++m) {
;         const int row = ai * HALF + m * 16 + rbase;
;         bf16* Cr = C + (long)row * g.ldc + cbase; const bf16* Zr = Z + (long)row * g.ldx + cbase;
; #pragma unroll
;         for (int bj = 0; bj < 2; ++bj)
; #pragma unroll
;           for (int n = 0; n < 2; ++n) {
;             f32x4 v = acc[ai][bj][m][n];
;             u32x2 z = *reinterpret_cast<const u32x2*>(Zr + bj * HALF + n * 16);
;             float o0 = v[0] * silu(bf_lo(z[0])), o1 = v[1] * silu(bf_hi(z[0]));
;             float o2 = v[2] * silu(bf_lo(z[1])), o3 = v[3] * silu(bf_hi(z[1]));
;             u32x2 w = {cvtpk(o0, o1), cvtpk(o2, o3)};
;             *reinterpret_cast<u32x2*>(Cr + bj * HALF + n * 16) = w;
;           }
;       }
.LBB0_67:
	s_cmp_eq_u32 s9, 2
	s_mov_b64 s[72:73], -1
	s_cbranch_scc0 .LBB0_69
	v_mul_lo_u32 v133, v0, s67
	s_lshl_b32 s0, s67, 5
	v_add_lshl_u32 v133, v133, v132, 1
	s_mov_b32 s10, s70
	s_mov_b32 s11, s71
	global_load_dwordx2 v[202:203], v133, s[10:11]
	global_load_dwordx2 v[204:205], v133, s[10:11] offset:32
	global_load_dwordx2 v[206:207], v133, s[10:11] offset:256
	global_load_dwordx2 v[208:209], v133, s[10:11] offset:288
	s_mul_i32 s2, s0, 1
	s_add_u32 s10, s70, s2
	s_addc_u32 s11, s71, 0
	global_load_dwordx2 v[210:211], v133, s[10:11]
	global_load_dwordx2 v[212:213], v133, s[10:11] offset:32
	global_load_dwordx2 v[214:215], v133, s[10:11] offset:256
	global_load_dwordx2 v[216:217], v133, s[10:11] offset:288
	s_mul_i32 s2, s0, 2
	s_add_u32 s10, s70, s2
	s_addc_u32 s11, s71, 0
	global_load_dwordx2 v[218:219], v133, s[10:11]
	global_load_dwordx2 v[220:221], v133, s[10:11] offset:32
	global_load_dwordx2 v[222:223], v133, s[10:11] offset:256
	global_load_dwordx2 v[224:225], v133, s[10:11] offset:288
	s_mul_i32 s2, s0, 3
	s_add_u32 s10, s70, s2
	s_addc_u32 s11, s71, 0
	global_load_dwordx2 v[226:227], v133, s[10:11]
	global_load_dwordx2 v[228:229], v133, s[10:11] offset:32
	global_load_dwordx2 v[230:231], v133, s[10:11] offset:256
	global_load_dwordx2 v[232:233], v133, s[10:11] offset:288
	s_mul_i32 s2, s0, 8
	s_add_u32 s10, s70, s2
	s_addc_u32 s11, s71, 0
	global_load_dwordx2 v[234:235], v133, s[10:11]
	global_load_dwordx2 v[236:237], v133, s[10:11] offset:32
	global_load_dwordx2 v[238:239], v133, s[10:11] offset:256
	global_load_dwordx2 v[240:241], v133, s[10:11] offset:288
	s_mul_i32 s2, s0, 9
	s_add_u32 s10, s70, s2
	s_addc_u32 s11, s71, 0
	global_load_dwordx2 v[242:243], v133, s[10:11]
	global_load_dwordx2 v[244:245], v133, s[10:11] offset:32
	global_load_dwordx2 v[246:247], v133, s[10:11] offset:256
	global_load_dwordx2 v[248:249], v133, s[10:11] offset:288
	s_mul_i32 s2, s0, 10
	s_add_u32 s10, s70, s2
	s_addc_u32 s11, s71, 0
	global_load_dwordx2 v[250:251], v133, s[10:11]
	global_load_dwordx2 v[252:253], v133, s[10:11] offset:32
	global_load_dwordx2 v[164:165], v133, s[10:11] offset:256
	global_load_dwordx2 v[166:167], v133, s[10:11] offset:288
	s_mul_i32 s2, s0, 11
	s_add_u32 s10, s70, s2
	s_addc_u32 s11, s71, 0
	global_load_dwordx2 v[168:169], v133, s[10:11]
	global_load_dwordx2 v[170:171], v133, s[10:11] offset:32
	global_load_dwordx2 v[172:173], v133, s[10:11] offset:256
	global_load_dwordx2 v[174:175], v133, s[10:11] offset:288
	v_ashrrev_i32_e32 v133, 31, v132
	v_lshlrev_b64 v[134:135], 1, v[132:133]
	v_lshl_add_u64 v[136:137], s[68:69], 0, v[134:135]
	v_lshl_add_u64 v[134:135], s[70:71], 0, v[134:135]
	v_mad_i64_i32 v[140:141], s[0:1], v0, s67, 0
	v_lshl_add_u64 v[140:141], v[140:141], 1, v[134:135]
	s_waitcnt vmcnt(31)
	v_mov_b32_e32 v142, v202
	v_mov_b32_e32 v143, v203
	v_mad_i64_i32 v[138:139], s[0:1], v0, s66, 0
	v_lshl_add_u64 v[138:139], v[138:139], 1, v[136:137]
	s_mov_b64 s[72:73], 0
	v_lshlrev_b32_e32 v1, 16, v142
	v_mul_f32_e32 v2, 0xbfb8aa3b, v1
	v_exp_f32_e32 v2, v2
	s_nop 0
	v_add_f32_e32 v2, 1.0, v2
	v_div_scale_f32 v133, s[0:1], v2, v2, v1
	v_rcp_f32_e32 v146, v133
	s_nop 0
	v_fma_f32 v147, -v133, v146, 1.0
	v_fmac_f32_e32 v146, v147, v146
	v_div_scale_f32 v147, vcc, v1, v2, v1
	v_mul_f32_e32 v148, v147, v146
	v_fma_f32 v149, -v133, v148, v147
	v_fmac_f32_e32 v148, v149, v146
	v_fma_f32 v133, -v133, v148, v147
	v_div_fmas_f32 v133, v133, v146, v148
	v_div_fixup_f32 v1, v133, v2, v1
	v_and_b32_e32 v2, 0xffff0000, v142
	v_mul_f32_e32 v133, 0xbfb8aa3b, v2
	v_exp_f32_e32 v133, v133
	v_mul_f32_e32 v1, v124, v1
	v_add_f32_e32 v133, 1.0, v133
	v_div_scale_f32 v142, s[0:1], v133, v133, v2
	v_rcp_f32_e32 v146, v142
	s_nop 0
	v_fma_f32 v147, -v142, v146, 1.0
	v_fmac_f32_e32 v146, v147, v146
	v_div_scale_f32 v147, vcc, v2, v133, v2
	v_mul_f32_e32 v148, v147, v146
	v_fma_f32 v149, -v142, v148, v147
	v_fmac_f32_e32 v148, v149, v146
	v_fma_f32 v142, -v142, v148, v147
	v_div_fmas_f32 v142, v142, v146, v148
	v_div_fixup_f32 v2, v142, v133, v2
	v_lshlrev_b32_e32 v133, 16, v143
	v_mul_f32_e32 v142, 0xbfb8aa3b, v133
	v_exp_f32_e32 v142, v142
	v_mul_f32_e32 v2, v125, v2
	v_add_f32_e32 v142, 1.0, v142
	v_div_scale_f32 v146, s[0:1], v142, v142, v133
	v_rcp_f32_e32 v147, v146
	s_nop 0
	v_fma_f32 v148, -v146, v147, 1.0
	v_fmac_f32_e32 v147, v148, v147
	v_div_scale_f32 v148, vcc, v133, v142, v133
	v_mul_f32_e32 v149, v148, v147
	v_fma_f32 v160, -v146, v149, v148
	v_fmac_f32_e32 v149, v160, v147
	v_fma_f32 v146, -v146, v149, v148
	v_div_fmas_f32 v146, v146, v147, v149
	v_div_fixup_f32 v133, v146, v142, v133
	v_and_b32_e32 v142, 0xffff0000, v143
	v_mul_f32_e32 v143, 0xbfb8aa3b, v142
	v_exp_f32_e32 v143, v143
	v_mul_f32_e32 v133, v126, v133
	v_add_f32_e32 v143, 1.0, v143
	v_div_scale_f32 v146, s[0:1], v143, v143, v142
	v_rcp_f32_e32 v147, v146
	s_nop 0
	v_fma_f32 v148, -v146, v147, 1.0
	v_fmac_f32_e32 v147, v148, v147
	v_div_scale_f32 v148, vcc, v142, v143, v142
	v_mul_f32_e32 v149, v148, v147
	v_fma_f32 v160, -v146, v149, v148
	v_fmac_f32_e32 v149, v160, v147
	v_fma_f32 v146, -v146, v149, v148
	v_div_fmas_f32 v146, v146, v147, v149
	v_div_fixup_f32 v142, v146, v143, v142
	v_mul_f32_e32 v143, v127, v142
	v_cvt_pk_bf16_f32 v142, v1, v2
	v_cvt_pk_bf16_f32 v143, v133, v143
	flat_store_dwordx2 v[138:139], v[142:143]
	s_waitcnt vmcnt(31)
; __device__ __forceinline__ float bf_lo(unsigned u) { return __uint_as_float(u << 16); }
; __device__ __forceinline__ float bf_hi(unsigned u) { return __uint_as_float(u & 0xffff0000u); }
; __device__ __forceinline__ float silu(float z) { return z / (1.f + __expf(-z)); }
; __device__ __forceinline__ void gemm_tile(const GemmArgs& g, bf16* shm, const int tid, const int wid, char* wsb, const float* gnext) {
;     ...
;   } else if (g.epi == EPI_GATE) {
;     bf16* C = (bf16*)g.C; const bf16* Z = (const bf16*)g.X;
; #pragma unroll
;     for (int ai = 0; ai < 2; ++ai)
; #pragma unroll
;       for (int m = 0; m < 4; ++m) {
;         const int row = ai * HALF + m * 16 + rbase;
;         bf16* Cr = C + (long)row * g.ldc + cbase; const bf16* Zr = Z + (long)row * g.ldx + cbase;
; #pragma unroll
;         for (int bj = 0; bj < 2; ++bj)
; #pragma unroll
;           for (int n = 0; n < 2; ++n) {
;             f32x4 v = acc[ai][bj][m][n];
;             u32x2 z = *reinterpret_cast<const u32x2*>(Zr + bj * HALF + n * 16);
;             float o0 = v[0] * silu(bf_lo(z[0])), o1 = v[1] * silu(bf_hi(z[0]));
;             float o2 = v[2] * silu(bf_lo(z[1])), o3 = v[3] * silu(bf_hi(z[1]));
;             u32x2 w = {cvtpk(o0, o1), cvtpk(o2, o3)};
;             *reinterpret_cast<u32x2*>(Cr + bj * HALF + n * 16) = w;
;           }
;       }
	v_mov_b32_e32 v142, v204
	v_mov_b32_e32 v143, v205
	v_lshlrev_b32_e32 v1, 16, v142
	v_mul_f32_e32 v2, 0xbfb8aa3b, v1
	v_exp_f32_e32 v2, v2
	s_nop 0
	v_add_f32_e32 v2, 1.0, v2
	v_div_scale_f32 v133, s[0:1], v2, v2, v1
	v_rcp_f32_e32 v146, v133
	s_nop 0
	v_fma_f32 v147, -v133, v146, 1.0
	v_fmac_f32_e32 v146, v147, v146
	v_div_scale_f32 v147, vcc, v1, v2, v1
	v_mul_f32_e32 v148, v147, v146
	v_fma_f32 v149, -v133, v148, v147
	v_fmac_f32_e32 v148, v149, v146
	v_fma_f32 v133, -v133, v148, v147
	v_div_fmas_f32 v133, v133, v146, v148
	v_div_fixup_f32 v1, v133, v2, v1
	v_and_b32_e32 v2, 0xffff0000, v142
	v_mul_f32_e32 v133, 0xbfb8aa3b, v2
	v_exp_f32_e32 v133, v133
	v_mul_f32_e32 v1, v116, v1
	v_add_f32_e32 v133, 1.0, v133
	v_div_scale_f32 v142, s[0:1], v133, v133, v2
	v_rcp_f32_e32 v146, v142
	s_nop 0
	v_fma_f32 v147, -v142, v146, 1.0
	v_fmac_f32_e32 v146, v147, v146
	v_div_scale_f32 v147, vcc, v2, v133, v2
	v_mul_f32_e32 v148, v147, v146
	v_fma_f32 v149, -v142, v148, v147
	v_fmac_f32_e32 v148, v149, v146
	v_fma_f32 v142, -v142, v148, v147
	v_div_fmas_f32 v142, v142, v146, v148
	v_div_fixup_f32 v2, v142, v133, v2
	v_lshlrev_b32_e32 v133, 16, v143
	v_mul_f32_e32 v142, 0xbfb8aa3b, v133
	v_exp_f32_e32 v142, v142
	v_mul_f32_e32 v2, v117, v2
	v_add_f32_e32 v142, 1.0, v142
	v_div_scale_f32 v146, s[0:1], v142, v142, v133
	v_rcp_f32_e32 v147, v146
	s_nop 0
	v_fma_f32 v148, -v146, v147, 1.0
	v_fmac_f32_e32 v147, v148, v147
	v_div_scale_f32 v148, vcc, v133, v142, v133
	v_mul_f32_e32 v149, v148, v147
	v_fma_f32 v160, -v146, v149, v148
	v_fmac_f32_e32 v149, v160, v147
	v_fma_f32 v146, -v146, v149, v148
	v_div_fmas_f32 v146, v146, v147, v149
	v_div_fixup_f32 v133, v146, v142, v133
	v_and_b32_e32 v142, 0xffff0000, v143
	v_mul_f32_e32 v143, 0xbfb8aa3b, v142
	v_exp_f32_e32 v143, v143
	v_mul_f32_e32 v133, v118, v133
	v_add_f32_e32 v143, 1.0, v143
	v_div_scale_f32 v146, s[0:1], v143, v143, v142
	v_rcp_f32_e32 v147, v146
	s_nop 0
	v_fma_f32 v148, -v146, v147, 1.0
	v_fmac_f32_e32 v147, v148, v147
	v_div_scale_f32 v148, vcc, v142, v143, v142
	v_mul_f32_e32 v149, v148, v147
	v_fma_f32 v160, -v146, v149, v148
	v_fmac_f32_e32 v149, v160, v147
	v_fma_f32 v146, -v146, v149, v148
	v_div_fmas_f32 v146, v146, v147, v149
	v_div_fixup_f32 v142, v146, v143, v142
	v_mul_f32_e32 v143, v119, v142
	v_cvt_pk_bf16_f32 v142, v1, v2
	v_cvt_pk_bf16_f32 v143, v133, v143
	flat_store_dwordx2 v[138:139], v[142:143] offset:32
	s_waitcnt vmcnt(31)
	v_mov_b32_e32 v142, v206
	v_mov_b32_e32 v143, v207
	v_lshlrev_b32_e32 v1, 16, v142
	v_mul_f32_e32 v2, 0xbfb8aa3b, v1
	v_exp_f32_e32 v2, v2
	s_nop 0
	v_add_f32_e32 v2, 1.0, v2
	v_div_scale_f32 v133, s[0:1], v2, v2, v1
	v_rcp_f32_e32 v146, v133
	s_nop 0
	v_fma_f32 v147, -v133, v146, 1.0
	v_fmac_f32_e32 v146, v147, v146
	v_div_scale_f32 v147, vcc, v1, v2, v1
	v_mul_f32_e32 v148, v147, v146
	v_fma_f32 v149, -v133, v148, v147
	v_fmac_f32_e32 v148, v149, v146
	v_fma_f32 v133, -v133, v148, v147
	v_div_fmas_f32 v133, v133, v146, v148
	v_div_fixup_f32 v1, v133, v2, v1
	v_and_b32_e32 v2, 0xffff0000, v142
	v_mul_f32_e32 v133, 0xbfb8aa3b, v2
	v_exp_f32_e32 v133, v133
	v_mul_f32_e32 v1, v128, v1
	v_add_f32_e32 v133, 1.0, v133
	v_div_scale_f32 v142, s[0:1], v133, v133, v2
	v_rcp_f32_e32 v146, v142
	s_nop 0
	v_fma_f32 v147, -v142, v146, 1.0
	v_fmac_f32_e32 v146, v147, v146
	v_div_scale_f32 v147, vcc, v2, v133, v2
	v_mul_f32_e32 v148, v147, v146
	v_fma_f32 v149, -v142, v148, v147
	v_fmac_f32_e32 v148, v149, v146
	v_fma_f32 v142, -v142, v148, v147
	v_div_fmas_f32 v142, v142, v146, v148
	v_div_fixup_f32 v2, v142, v133, v2
	v_lshlrev_b32_e32 v133, 16, v143
	v_mul_f32_e32 v142, 0xbfb8aa3b, v133
	v_exp_f32_e32 v142, v142
	v_mul_f32_e32 v2, v129, v2
	v_add_f32_e32 v142, 1.0, v142
	v_div_scale_f32 v146, s[0:1], v142, v142, v133
	v_rcp_f32_e32 v147, v146
	s_nop 0
	v_fma_f32 v148, -v146, v147, 1.0
	v_fmac_f32_e32 v147, v148, v147
	v_div_scale_f32 v148, vcc, v133, v142, v133
	v_mul_f32_e32 v149, v148, v147
	v_fma_f32 v160, -v146, v149, v148
	v_fmac_f32_e32 v149, v160, v147
	v_fma_f32 v146, -v146, v149, v148
	v_div_fmas_f32 v146, v146, v147, v149
	v_div_fixup_f32 v133, v146, v142, v133
	v_and_b32_e32 v142, 0xffff0000, v143
	v_mul_f32_e32 v143, 0xbfb8aa3b, v142
	v_exp_f32_e32 v143, v143
	v_mul_f32_e32 v133, v130, v133
	v_add_f32_e32 v143, 1.0, v143
	v_div_scale_f32 v146, s[0:1], v143, v143, v142
	v_rcp_f32_e32 v147, v146
	s_nop 0
	v_fma_f32 v148, -v146, v147, 1.0
	v_fmac_f32_e32 v147, v148, v147
	v_div_scale_f32 v148, vcc, v142, v143, v142
	v_mul_f32_e32 v149, v148, v147
	v_fma_f32 v160, -v146, v149, v148
	v_fmac_f32_e32 v149, v160, v147
	v_fma_f32 v146, -v146, v149, v148
	v_div_fmas_f32 v146, v146, v147, v149
	v_div_fixup_f32 v142, v146, v143, v142
	v_mul_f32_e32 v143, v131, v142
	v_cvt_pk_bf16_f32 v142, v1, v2
	v_cvt_pk_bf16_f32 v143, v133, v143
	flat_store_dwordx2 v[138:139], v[142:143] offset:256
	s_waitcnt vmcnt(31)
; __device__ __forceinline__ float bf_lo(unsigned u) { return __uint_as_float(u << 16); }
; __device__ __forceinline__ float bf_hi(unsigned u) { return __uint_as_float(u & 0xffff0000u); }
; __device__ __forceinline__ float silu(float z) { return z / (1.f + __expf(-z)); }
; __device__ __forceinline__ void gemm_tile(const GemmArgs& g, bf16* shm, const int tid, const int wid, char* wsb, const float* gnext) {
;     ...
;   } else if (g.epi == EPI_GATE) {
;     bf16* C = (bf16*)g.C; const bf16* Z = (const bf16*)g.X;
; #pragma unroll
;     for (int ai = 0; ai < 2; ++ai)
; #pragma unroll
;       for (int m = 0; m < 4; ++m) {
;         const int row = ai * HALF + m * 16 + rbase;
;         bf16* Cr = C + (long)row * g.ldc + cbase; const bf16* Zr = Z + (long)row * g.ldx + cbase;
; #pragma unroll
;         for (int bj = 0; bj < 2; ++bj)
; #pragma unroll
;           for (int n = 0; n < 2; ++n) {
;             f32x4 v = acc[ai][bj][m][n];
;             u32x2 z = *reinterpret_cast<const u32x2*>(Zr + bj * HALF + n * 16);
;             float o0 = v[0] * silu(bf_lo(z[0])), o1 = v[1] * silu(bf_hi(z[0]));
;             float o2 = v[2] * silu(bf_lo(z[1])), o3 = v[3] * silu(bf_hi(z[1]));
;             u32x2 w = {cvtpk(o0, o1), cvtpk(o2, o3)};
;             *reinterpret_cast<u32x2*>(Cr + bj * HALF + n * 16) = w;
;           }
;       }
	v_mov_b32_e32 v140, v208
	v_mov_b32_e32 v141, v209
	v_lshlrev_b32_e32 v1, 16, v140
	v_mul_f32_e32 v2, 0xbfb8aa3b, v1
	v_exp_f32_e32 v2, v2
	s_nop 0
	v_add_f32_e32 v2, 1.0, v2
	v_div_scale_f32 v133, s[0:1], v2, v2, v1
	v_rcp_f32_e32 v142, v133
	s_nop 0
	v_fma_f32 v143, -v133, v142, 1.0
	v_fmac_f32_e32 v142, v143, v142
	v_div_scale_f32 v143, vcc, v1, v2, v1
	v_mul_f32_e32 v146, v143, v142
	v_fma_f32 v147, -v133, v146, v143
	v_fmac_f32_e32 v146, v147, v142
	v_fma_f32 v133, -v133, v146, v143
	v_div_fmas_f32 v133, v133, v142, v146
	v_div_fixup_f32 v1, v133, v2, v1
	v_and_b32_e32 v2, 0xffff0000, v140
	v_mul_f32_e32 v133, 0xbfb8aa3b, v2
	v_exp_f32_e32 v133, v133
	v_mul_f32_e32 v1, v120, v1
	v_add_f32_e32 v133, 1.0, v133
	v_div_scale_f32 v140, s[0:1], v133, v133, v2
	v_rcp_f32_e32 v142, v140
	s_nop 0
	v_fma_f32 v143, -v140, v142, 1.0
	v_fmac_f32_e32 v142, v143, v142
	v_div_scale_f32 v143, vcc, v2, v133, v2
	v_mul_f32_e32 v146, v143, v142
	v_fma_f32 v147, -v140, v146, v143
	v_fmac_f32_e32 v146, v147, v142
	v_fma_f32 v140, -v140, v146, v143
	v_div_fmas_f32 v140, v140, v142, v146
	v_div_fixup_f32 v2, v140, v133, v2
	v_lshlrev_b32_e32 v133, 16, v141
	v_mul_f32_e32 v140, 0xbfb8aa3b, v133
	v_exp_f32_e32 v140, v140
	v_mul_f32_e32 v2, v121, v2
	v_add_f32_e32 v140, 1.0, v140
	v_div_scale_f32 v142, s[0:1], v140, v140, v133
	v_rcp_f32_e32 v143, v142
	s_nop 0
	v_fma_f32 v146, -v142, v143, 1.0
	v_fmac_f32_e32 v143, v146, v143
	v_div_scale_f32 v146, vcc, v133, v140, v133
	v_mul_f32_e32 v147, v146, v143
	v_fma_f32 v148, -v142, v147, v146
	v_fmac_f32_e32 v147, v148, v143
	v_fma_f32 v142, -v142, v147, v146
	v_div_fmas_f32 v142, v142, v143, v147
	v_div_fixup_f32 v133, v142, v140, v133
	v_and_b32_e32 v140, 0xffff0000, v141
	v_mul_f32_e32 v141, 0xbfb8aa3b, v140
	v_exp_f32_e32 v141, v141
	v_mul_f32_e32 v133, v122, v133
	v_add_f32_e32 v141, 1.0, v141
	v_div_scale_f32 v142, s[0:1], v141, v141, v140
	v_rcp_f32_e32 v143, v142
	s_nop 0
	v_fma_f32 v146, -v142, v143, 1.0
	v_fmac_f32_e32 v143, v146, v143
	v_div_scale_f32 v146, vcc, v140, v141, v140
	v_mul_f32_e32 v147, v146, v143
	v_fma_f32 v148, -v142, v147, v146
	v_fmac_f32_e32 v147, v148, v143
	v_fma_f32 v142, -v142, v147, v146
	v_div_fmas_f32 v142, v142, v143, v147
	v_div_fixup_f32 v140, v142, v141, v140
	v_mul_f32_e32 v141, v123, v140
	v_cvt_pk_bf16_f32 v140, v1, v2
	v_cvt_pk_bf16_f32 v141, v133, v141
	v_add_u32_e32 v1, 16, v0
	flat_store_dwordx2 v[138:139], v[140:141] offset:288
	v_mad_i64_i32 v[140:141], s[0:1], v1, s67, 0
	v_lshl_add_u64 v[140:141], v[140:141], 1, v[134:135]
	s_waitcnt vmcnt(31)
	v_mov_b32_e32 v142, v210
	v_mov_b32_e32 v143, v211
	v_mad_i64_i32 v[138:139], s[0:1], v1, s66, 0
	v_lshl_add_u64 v[138:139], v[138:139], 1, v[136:137]
	v_lshlrev_b32_e32 v1, 16, v142
	v_mul_f32_e32 v2, 0xbfb8aa3b, v1
	v_exp_f32_e32 v2, v2
	s_nop 0
	v_add_f32_e32 v2, 1.0, v2
	v_div_scale_f32 v133, s[0:1], v2, v2, v1
	v_rcp_f32_e32 v146, v133
	s_nop 0
	v_fma_f32 v147, -v133, v146, 1.0
	v_fmac_f32_e32 v146, v147, v146
	v_div_scale_f32 v147, vcc, v1, v2, v1
	v_mul_f32_e32 v148, v147, v146
	v_fma_f32 v149, -v133, v148, v147
	v_fmac_f32_e32 v148, v149, v146
	v_fma_f32 v133, -v133, v148, v147
	v_div_fmas_f32 v133, v133, v146, v148
	v_div_fixup_f32 v1, v133, v2, v1
	v_and_b32_e32 v2, 0xffff0000, v142
	v_mul_f32_e32 v133, 0xbfb8aa3b, v2
	v_exp_f32_e32 v133, v133
	v_mul_f32_e32 v1, v108, v1
	v_add_f32_e32 v133, 1.0, v133
	v_div_scale_f32 v142, s[0:1], v133, v133, v2
	v_rcp_f32_e32 v146, v142
	s_nop 0
	v_fma_f32 v147, -v142, v146, 1.0
	v_fmac_f32_e32 v146, v147, v146
	v_div_scale_f32 v147, vcc, v2, v133, v2
	v_mul_f32_e32 v148, v147, v146
	v_fma_f32 v149, -v142, v148, v147
	v_fmac_f32_e32 v148, v149, v146
	v_fma_f32 v142, -v142, v148, v147
	v_div_fmas_f32 v142, v142, v146, v148
	v_div_fixup_f32 v2, v142, v133, v2
	v_lshlrev_b32_e32 v133, 16, v143
	v_mul_f32_e32 v142, 0xbfb8aa3b, v133
	v_exp_f32_e32 v142, v142
	v_mul_f32_e32 v2, v109, v2
	v_add_f32_e32 v142, 1.0, v142
	v_div_scale_f32 v146, s[0:1], v142, v142, v133
	v_rcp_f32_e32 v147, v146
	s_nop 0
	v_fma_f32 v148, -v146, v147, 1.0
	v_fmac_f32_e32 v147, v148, v147
	v_div_scale_f32 v148, vcc, v133, v142, v133
	v_mul_f32_e32 v149, v148, v147
	v_fma_f32 v160, -v146, v149, v148
	v_fmac_f32_e32 v149, v160, v147
	v_fma_f32 v146, -v146, v149, v148
	v_div_fmas_f32 v146, v146, v147, v149
	v_div_fixup_f32 v133, v146, v142, v133
	v_and_b32_e32 v142, 0xffff0000, v143
	v_mul_f32_e32 v143, 0xbfb8aa3b, v142
	v_exp_f32_e32 v143, v143
	v_mul_f32_e32 v133, v110, v133
	v_add_f32_e32 v143, 1.0, v143
	v_div_scale_f32 v146, s[0:1], v143, v143, v142
	v_rcp_f32_e32 v147, v146
	s_nop 0
	v_fma_f32 v148, -v146, v147, 1.0
	v_fmac_f32_e32 v147, v148, v147
	v_div_scale_f32 v148, vcc, v142, v143, v142
	v_mul_f32_e32 v149, v148, v147
	v_fma_f32 v160, -v146, v149, v148
	v_fmac_f32_e32 v149, v160, v147
	v_fma_f32 v146, -v146, v149, v148
	v_div_fmas_f32 v146, v146, v147, v149
	v_div_fixup_f32 v142, v146, v143, v142
	v_mul_f32_e32 v143, v111, v142
	v_cvt_pk_bf16_f32 v142, v1, v2
	v_cvt_pk_bf16_f32 v143, v133, v143
	flat_store_dwordx2 v[138:139], v[142:143]
	s_waitcnt vmcnt(31)
; __device__ __forceinline__ float bf_lo(unsigned u) { return __uint_as_float(u << 16); }
; __device__ __forceinline__ float bf_hi(unsigned u) { return __uint_as_float(u & 0xffff0000u); }
; __device__ __forceinline__ float silu(float z) { return z / (1.f + __expf(-z)); }
; __device__ __forceinline__ void gemm_tile(const GemmArgs& g, bf16* shm, const int tid, const int wid, char* wsb, const float* gnext) {
;     ...
;   } else if (g.epi == EPI_GATE) {
;     bf16* C = (bf16*)g.C; const bf16* Z = (const bf16*)g.X;
; #pragma unroll
;     for (int ai = 0; ai < 2; ++ai)
; #pragma unroll
;       for (int m = 0; m < 4; ++m) {
;         const int row = ai * HALF + m * 16 + rbase;
;         bf16* Cr = C + (long)row * g.ldc + cbase; const bf16* Zr = Z + (long)row * g.ldx + cbase;
; #pragma unroll
;         for (int bj = 0; bj < 2; ++bj)
; #pragma unroll
;           for (int n = 0; n < 2; ++n) {
;             f32x4 v = acc[ai][bj][m][n];
;             u32x2 z = *reinterpret_cast<const u32x2*>(Zr + bj * HALF + n * 16);
;             float o0 = v[0] * silu(bf_lo(z[0])), o1 = v[1] * silu(bf_hi(z[0]));
;             float o2 = v[2] * silu(bf_lo(z[1])), o3 = v[3] * silu(bf_hi(z[1]));
;             u32x2 w = {cvtpk(o0, o1), cvtpk(o2, o3)};
;             *reinterpret_cast<u32x2*>(Cr + bj * HALF + n * 16) = w;
;           }
;       }
	v_mov_b32_e32 v142, v212
	v_mov_b32_e32 v143, v213
	v_lshlrev_b32_e32 v1, 16, v142
	v_mul_f32_e32 v2, 0xbfb8aa3b, v1
	v_exp_f32_e32 v2, v2
	s_nop 0
	v_add_f32_e32 v2, 1.0, v2
	v_div_scale_f32 v133, s[0:1], v2, v2, v1
	v_rcp_f32_e32 v146, v133
	s_nop 0
	v_fma_f32 v147, -v133, v146, 1.0
	v_fmac_f32_e32 v146, v147, v146
	v_div_scale_f32 v147, vcc, v1, v2, v1
	v_mul_f32_e32 v148, v147, v146
	v_fma_f32 v149, -v133, v148, v147
	v_fmac_f32_e32 v148, v149, v146
	v_fma_f32 v133, -v133, v148, v147
	v_div_fmas_f32 v133, v133, v146, v148
	v_div_fixup_f32 v1, v133, v2, v1
	v_and_b32_e32 v2, 0xffff0000, v142
	v_mul_f32_e32 v133, 0xbfb8aa3b, v2
	v_exp_f32_e32 v133, v133
	v_mul_f32_e32 v1, v100, v1
	v_add_f32_e32 v133, 1.0, v133
	v_div_scale_f32 v142, s[0:1], v133, v133, v2
	v_rcp_f32_e32 v146, v142
	s_nop 0
	v_fma_f32 v147, -v142, v146, 1.0
	v_fmac_f32_e32 v146, v147, v146
	v_div_scale_f32 v147, vcc, v2, v133, v2
	v_mul_f32_e32 v148, v147, v146
	v_fma_f32 v149, -v142, v148, v147
	v_fmac_f32_e32 v148, v149, v146
	v_fma_f32 v142, -v142, v148, v147
	v_div_fmas_f32 v142, v142, v146, v148
	v_div_fixup_f32 v2, v142, v133, v2
	v_lshlrev_b32_e32 v133, 16, v143
	v_mul_f32_e32 v142, 0xbfb8aa3b, v133
	v_exp_f32_e32 v142, v142
	v_mul_f32_e32 v2, v101, v2
	v_add_f32_e32 v142, 1.0, v142
	v_div_scale_f32 v146, s[0:1], v142, v142, v133
	v_rcp_f32_e32 v147, v146
	s_nop 0
	v_fma_f32 v148, -v146, v147, 1.0
	v_fmac_f32_e32 v147, v148, v147
	v_div_scale_f32 v148, vcc, v133, v142, v133
	v_mul_f32_e32 v149, v148, v147
	v_fma_f32 v160, -v146, v149, v148
	v_fmac_f32_e32 v149, v160, v147
	v_fma_f32 v146, -v146, v149, v148
	v_div_fmas_f32 v146, v146, v147, v149
	v_div_fixup_f32 v133, v146, v142, v133
	v_and_b32_e32 v142, 0xffff0000, v143
	v_mul_f32_e32 v143, 0xbfb8aa3b, v142
	v_exp_f32_e32 v143, v143
	v_mul_f32_e32 v133, v102, v133
	v_add_f32_e32 v143, 1.0, v143
	v_div_scale_f32 v146, s[0:1], v143, v143, v142
	v_rcp_f32_e32 v147, v146
	s_nop 0
	v_fma_f32 v148, -v146, v147, 1.0
	v_fmac_f32_e32 v147, v148, v147
	v_div_scale_f32 v148, vcc, v142, v143, v142
	v_mul_f32_e32 v149, v148, v147
	v_fma_f32 v160, -v146, v149, v148
	v_fmac_f32_e32 v149, v160, v147
	v_fma_f32 v146, -v146, v149, v148
	v_div_fmas_f32 v146, v146, v147, v149
	v_div_fixup_f32 v142, v146, v143, v142
	v_mul_f32_e32 v143, v103, v142
	v_cvt_pk_bf16_f32 v142, v1, v2
	v_cvt_pk_bf16_f32 v143, v133, v143
	flat_store_dwordx2 v[138:139], v[142:143] offset:32
	s_waitcnt vmcnt(31)
	v_mov_b32_e32 v142, v214
	v_mov_b32_e32 v143, v215
	v_lshlrev_b32_e32 v1, 16, v142
	v_mul_f32_e32 v2, 0xbfb8aa3b, v1
	v_exp_f32_e32 v2, v2
	s_nop 0
	v_add_f32_e32 v2, 1.0, v2
	v_div_scale_f32 v133, s[0:1], v2, v2, v1
	v_rcp_f32_e32 v146, v133
	s_nop 0
	v_fma_f32 v147, -v133, v146, 1.0
	v_fmac_f32_e32 v146, v147, v146
	v_div_scale_f32 v147, vcc, v1, v2, v1
	v_mul_f32_e32 v148, v147, v146
	v_fma_f32 v149, -v133, v148, v147
	v_fmac_f32_e32 v148, v149, v146
	v_fma_f32 v133, -v133, v148, v147
	v_div_fmas_f32 v133, v133, v146, v148
	v_div_fixup_f32 v1, v133, v2, v1
	v_and_b32_e32 v2, 0xffff0000, v142
	v_mul_f32_e32 v133, 0xbfb8aa3b, v2
	v_exp_f32_e32 v133, v133
	v_mul_f32_e32 v1, v112, v1
	v_add_f32_e32 v133, 1.0, v133
	v_div_scale_f32 v142, s[0:1], v133, v133, v2
	v_rcp_f32_e32 v146, v142
	s_nop 0
	v_fma_f32 v147, -v142, v146, 1.0
	v_fmac_f32_e32 v146, v147, v146
	v_div_scale_f32 v147, vcc, v2, v133, v2
	v_mul_f32_e32 v148, v147, v146
	v_fma_f32 v149, -v142, v148, v147
	v_fmac_f32_e32 v148, v149, v146
	v_fma_f32 v142, -v142, v148, v147
	v_div_fmas_f32 v142, v142, v146, v148
	v_div_fixup_f32 v2, v142, v133, v2
	v_lshlrev_b32_e32 v133, 16, v143
	v_mul_f32_e32 v142, 0xbfb8aa3b, v133
	v_exp_f32_e32 v142, v142
	v_mul_f32_e32 v2, v113, v2
	v_add_f32_e32 v142, 1.0, v142
	v_div_scale_f32 v146, s[0:1], v142, v142, v133
	v_rcp_f32_e32 v147, v146
	s_nop 0
	v_fma_f32 v148, -v146, v147, 1.0
	v_fmac_f32_e32 v147, v148, v147
	v_div_scale_f32 v148, vcc, v133, v142, v133
	v_mul_f32_e32 v149, v148, v147
	v_fma_f32 v160, -v146, v149, v148
	v_fmac_f32_e32 v149, v160, v147
	v_fma_f32 v146, -v146, v149, v148
	v_div_fmas_f32 v146, v146, v147, v149
	v_div_fixup_f32 v133, v146, v142, v133
	v_and_b32_e32 v142, 0xffff0000, v143
	v_mul_f32_e32 v143, 0xbfb8aa3b, v142
	v_exp_f32_e32 v143, v143
	v_mul_f32_e32 v133, v114, v133
	v_add_f32_e32 v143, 1.0, v143
	v_div_scale_f32 v146, s[0:1], v143, v143, v142
	v_rcp_f32_e32 v147, v146
	s_nop 0
	v_fma_f32 v148, -v146, v147, 1.0
	v_fmac_f32_e32 v147, v148, v147
	v_div_scale_f32 v148, vcc, v142, v143, v142
	v_mul_f32_e32 v149, v148, v147
	v_fma_f32 v160, -v146, v149, v148
	v_fmac_f32_e32 v149, v160, v147
	v_fma_f32 v146, -v146, v149, v148
	v_div_fmas_f32 v146, v146, v147, v149
	v_div_fixup_f32 v142, v146, v143, v142
	v_mul_f32_e32 v143, v115, v142
	v_cvt_pk_bf16_f32 v142, v1, v2
	v_cvt_pk_bf16_f32 v143, v133, v143
	flat_store_dwordx2 v[138:139], v[142:143] offset:256
	s_waitcnt vmcnt(31)
; __device__ __forceinline__ float bf_lo(unsigned u) { return __uint_as_float(u << 16); }
; __device__ __forceinline__ float bf_hi(unsigned u) { return __uint_as_float(u & 0xffff0000u); }
; __device__ __forceinline__ float silu(float z) { return z / (1.f + __expf(-z)); }
; __device__ __forceinline__ void gemm_tile(const GemmArgs& g, bf16* shm, const int tid, const int wid, char* wsb, const float* gnext) {
;     ...
;     for (int ai = 0; ai < 2; ++ai)
; #pragma unroll
;       for (int m = 0; m < 4; ++m) {
;         const int row = ai * HALF + m * 16 + rbase;
;         bf16* Cr = C + (long)row * g.ldc + cbase; const bf16* Zr = Z + (long)row * g.ldx + cbase;
; #pragma unroll
;         for (int bj = 0; bj < 2; ++bj)
; #pragma unroll
;           for (int n = 0; n < 2; ++n) {
;             f32x4 v = acc[ai][bj][m][n];
;             u32x2 z = *reinterpret_cast<const u32x2*>(Zr + bj * HALF + n * 16);
;             float o0 = v[0] * silu(bf_lo(z[0])), o1 = v[1] * silu(bf_hi(z[0]));
;             float o2 = v[2] * silu(bf_lo(z[1])), o3 = v[3] * silu(bf_hi(z[1]));
;             u32x2 w = {cvtpk(o0, o1), cvtpk(o2, o3)};
;             *reinterpret_cast<u32x2*>(Cr + bj * HALF + n * 16) = w;
;           }
	v_mov_b32_e32 v140, v216
	v_mov_b32_e32 v141, v217
	v_lshlrev_b32_e32 v1, 16, v140
	v_mul_f32_e32 v2, 0xbfb8aa3b, v1
	v_exp_f32_e32 v2, v2
	s_nop 0
	v_add_f32_e32 v2, 1.0, v2
	v_div_scale_f32 v133, s[0:1], v2, v2, v1
	v_rcp_f32_e32 v142, v133
	s_nop 0
	v_fma_f32 v143, -v133, v142, 1.0
	v_fmac_f32_e32 v142, v143, v142
	v_div_scale_f32 v143, vcc, v1, v2, v1
	v_mul_f32_e32 v146, v143, v142
	v_fma_f32 v147, -v133, v146, v143
	v_fmac_f32_e32 v146, v147, v142
	v_fma_f32 v133, -v133, v146, v143
	v_div_fmas_f32 v133, v133, v142, v146
	v_div_fixup_f32 v1, v133, v2, v1
	v_and_b32_e32 v2, 0xffff0000, v140
	v_mul_f32_e32 v133, 0xbfb8aa3b, v2
	v_exp_f32_e32 v133, v133
	v_mul_f32_e32 v1, v104, v1
	v_add_f32_e32 v133, 1.0, v133
	v_div_scale_f32 v140, s[0:1], v133, v133, v2
	v_rcp_f32_e32 v142, v140
	s_nop 0
	v_fma_f32 v143, -v140, v142, 1.0
	v_fmac_f32_e32 v142, v143, v142
	v_div_scale_f32 v143, vcc, v2, v133, v2
	v_mul_f32_e32 v146, v143, v142
	v_fma_f32 v147, -v140, v146, v143
	v_fmac_f32_e32 v146, v147, v142
	v_fma_f32 v140, -v140, v146, v143
	v_div_fmas_f32 v140, v140, v142, v146
	v_div_fixup_f32 v2, v140, v133, v2
	v_lshlrev_b32_e32 v133, 16, v141
	v_mul_f32_e32 v140, 0xbfb8aa3b, v133
	v_exp_f32_e32 v140, v140
	v_mul_f32_e32 v2, v105, v2
	v_add_f32_e32 v140, 1.0, v140
	v_div_scale_f32 v142, s[0:1], v140, v140, v133
	v_rcp_f32_e32 v143, v142
	s_nop 0
	v_fma_f32 v146, -v142, v143, 1.0
	v_fmac_f32_e32 v143, v146, v143
	v_div_scale_f32 v146, vcc, v133, v140, v133
	v_mul_f32_e32 v147, v146, v143
	v_fma_f32 v148, -v142, v147, v146
	v_fmac_f32_e32 v147, v148, v143
	v_fma_f32 v142, -v142, v147, v146
	v_div_fmas_f32 v142, v142, v143, v147
	v_div_fixup_f32 v133, v142, v140, v133
	v_and_b32_e32 v140, 0xffff0000, v141
	v_mul_f32_e32 v141, 0xbfb8aa3b, v140
	v_exp_f32_e32 v141, v141
	v_mul_f32_e32 v133, v106, v133
	v_add_f32_e32 v141, 1.0, v141
	v_div_scale_f32 v142, s[0:1], v141, v141, v140
	v_rcp_f32_e32 v143, v142
	s_nop 0
	v_fma_f32 v146, -v142, v143, 1.0
	v_fmac_f32_e32 v143, v146, v143
	v_div_scale_f32 v146, vcc, v140, v141, v140
	v_mul_f32_e32 v147, v146, v143
	v_fma_f32 v148, -v142, v147, v146
	v_fmac_f32_e32 v147, v148, v143
	v_fma_f32 v142, -v142, v147, v146
	v_div_fmas_f32 v142, v142, v143, v147
	v_div_fixup_f32 v140, v142, v141, v140
	v_mul_f32_e32 v141, v107, v140
	v_cvt_pk_bf16_f32 v140, v1, v2
	v_cvt_pk_bf16_f32 v141, v133, v141
	v_add_u32_e32 v1, 32, v0
	flat_store_dwordx2 v[138:139], v[140:141] offset:288
	v_mad_i64_i32 v[140:141], s[0:1], v1, s67, 0
	v_lshl_add_u64 v[140:141], v[140:141], 1, v[134:135]
	s_waitcnt vmcnt(31)
	v_mov_b32_e32 v142, v218
	v_mov_b32_e32 v143, v219
	v_mad_i64_i32 v[138:139], s[0:1], v1, s66, 0
	v_lshl_add_u64 v[138:139], v[138:139], 1, v[136:137]
	v_lshlrev_b32_e32 v1, 16, v142
	v_mul_f32_e32 v2, 0xbfb8aa3b, v1
	v_exp_f32_e32 v2, v2
	s_nop 0
	v_add_f32_e32 v2, 1.0, v2
	v_div_scale_f32 v133, s[0:1], v2, v2, v1
	v_rcp_f32_e32 v146, v133
	s_nop 0
	v_fma_f32 v147, -v133, v146, 1.0
	v_fmac_f32_e32 v146, v147, v146
	v_div_scale_f32 v147, vcc, v1, v2, v1
	v_mul_f32_e32 v148, v147, v146
	v_fma_f32 v149, -v133, v148, v147
	v_fmac_f32_e32 v148, v149, v146
	v_fma_f32 v133, -v133, v148, v147
	v_div_fmas_f32 v133, v133, v146, v148
	v_div_fixup_f32 v1, v133, v2, v1
	v_and_b32_e32 v2, 0xffff0000, v142
	v_mul_f32_e32 v133, 0xbfb8aa3b, v2
	v_exp_f32_e32 v133, v133
	v_mul_f32_e32 v1, v92, v1
	v_add_f32_e32 v133, 1.0, v133
	v_div_scale_f32 v142, s[0:1], v133, v133, v2
	v_rcp_f32_e32 v146, v142
	s_nop 0
	v_fma_f32 v147, -v142, v146, 1.0
	v_fmac_f32_e32 v146, v147, v146
	v_div_scale_f32 v147, vcc, v2, v133, v2
	v_mul_f32_e32 v148, v147, v146
	v_fma_f32 v149, -v142, v148, v147
	v_fmac_f32_e32 v148, v149, v146
	v_fma_f32 v142, -v142, v148, v147
	v_div_fmas_f32 v142, v142, v146, v148
	v_div_fixup_f32 v2, v142, v133, v2
	v_lshlrev_b32_e32 v133, 16, v143
	v_mul_f32_e32 v142, 0xbfb8aa3b, v133
	v_exp_f32_e32 v142, v142
	v_mul_f32_e32 v2, v93, v2
	v_add_f32_e32 v142, 1.0, v142
	v_div_scale_f32 v146, s[0:1], v142, v142, v133
	v_rcp_f32_e32 v147, v146
	s_nop 0
	v_fma_f32 v148, -v146, v147, 1.0
	v_fmac_f32_e32 v147, v148, v147
	v_div_scale_f32 v148, vcc, v133, v142, v133
	v_mul_f32_e32 v149, v148, v147
	v_fma_f32 v160, -v146, v149, v148
	v_fmac_f32_e32 v149, v160, v147
	v_fma_f32 v146, -v146, v149, v148
	v_div_fmas_f32 v146, v146, v147, v149
	v_div_fixup_f32 v133, v146, v142, v133
	v_and_b32_e32 v142, 0xffff0000, v143
	v_mul_f32_e32 v143, 0xbfb8aa3b, v142
	v_exp_f32_e32 v143, v143
	v_mul_f32_e32 v133, v94, v133
	v_add_f32_e32 v143, 1.0, v143
	v_div_scale_f32 v146, s[0:1], v143, v143, v142
	v_rcp_f32_e32 v147, v146
	s_nop 0
	v_fma_f32 v148, -v146, v147, 1.0
	v_fmac_f32_e32 v147, v148, v147
	v_div_scale_f32 v148, vcc, v142, v143, v142
	v_mul_f32_e32 v149, v148, v147
	v_fma_f32 v160, -v146, v149, v148
	v_fmac_f32_e32 v149, v160, v147
	v_fma_f32 v146, -v146, v149, v148
	v_div_fmas_f32 v146, v146, v147, v149
	v_div_fixup_f32 v142, v146, v143, v142
	v_mul_f32_e32 v143, v95, v142
	v_cvt_pk_bf16_f32 v142, v1, v2
	v_cvt_pk_bf16_f32 v143, v133, v143
	flat_store_dwordx2 v[138:139], v[142:143]
	s_waitcnt vmcnt(31)
; __device__ __forceinline__ float bf_lo(unsigned u) { return __uint_as_float(u << 16); }
; __device__ __forceinline__ float bf_hi(unsigned u) { return __uint_as_float(u & 0xffff0000u); }
; __device__ __forceinline__ float silu(float z) { return z / (1.f + __expf(-z)); }
; __device__ __forceinline__ void gemm_tile(const GemmArgs& g, bf16* shm, const int tid, const int wid, char* wsb, const float* gnext) {
;     ...
;     for (int ai = 0; ai < 2; ++ai)
; #pragma unroll
;       for (int m = 0; m < 4; ++m) {
;         const int row = ai * HALF + m * 16 + rbase;
;         bf16* Cr = C + (long)row * g.ldc + cbase; const bf16* Zr = Z + (long)row * g.ldx + cbase;
; #pragma unroll
;         for (int bj = 0; bj < 2; ++bj)
; #pragma unroll
;           for (int n = 0; n < 2; ++n) {
;             f32x4 v = acc[ai][bj][m][n];
;             u32x2 z = *reinterpret_cast<const u32x2*>(Zr + bj * HALF + n * 16);
;             float o0 = v[0] * silu(bf_lo(z[0])), o1 = v[1] * silu(bf_hi(z[0]));
;             float o2 = v[2] * silu(bf_lo(z[1])), o3 = v[3] * silu(bf_hi(z[1]));
;             u32x2 w = {cvtpk(o0, o1), cvtpk(o2, o3)};
;             *reinterpret_cast<u32x2*>(Cr + bj * HALF + n * 16) = w;
;           }
	v_mov_b32_e32 v142, v220
	v_mov_b32_e32 v143, v221
	v_lshlrev_b32_e32 v1, 16, v142
	v_mul_f32_e32 v2, 0xbfb8aa3b, v1
	v_exp_f32_e32 v2, v2
	s_nop 0
	v_add_f32_e32 v2, 1.0, v2
	v_div_scale_f32 v133, s[0:1], v2, v2, v1
	v_rcp_f32_e32 v146, v133
	s_nop 0
	v_fma_f32 v147, -v133, v146, 1.0
	v_fmac_f32_e32 v146, v147, v146
	v_div_scale_f32 v147, vcc, v1, v2, v1
	v_mul_f32_e32 v148, v147, v146
	v_fma_f32 v149, -v133, v148, v147
	v_fmac_f32_e32 v148, v149, v146
	v_fma_f32 v133, -v133, v148, v147
	v_div_fmas_f32 v133, v133, v146, v148
	v_div_fixup_f32 v1, v133, v2, v1
	v_and_b32_e32 v2, 0xffff0000, v142
	v_mul_f32_e32 v133, 0xbfb8aa3b, v2
	v_exp_f32_e32 v133, v133
	v_mul_f32_e32 v1, v84, v1
	v_add_f32_e32 v133, 1.0, v133
	v_div_scale_f32 v142, s[0:1], v133, v133, v2
	v_rcp_f32_e32 v146, v142
	s_nop 0
	v_fma_f32 v147, -v142, v146, 1.0
	v_fmac_f32_e32 v146, v147, v146
	v_div_scale_f32 v147, vcc, v2, v133, v2
	v_mul_f32_e32 v148, v147, v146
	v_fma_f32 v149, -v142, v148, v147
	v_fmac_f32_e32 v148, v149, v146
	v_fma_f32 v142, -v142, v148, v147
	v_div_fmas_f32 v142, v142, v146, v148
	v_div_fixup_f32 v2, v142, v133, v2
	v_lshlrev_b32_e32 v133, 16, v143
	v_mul_f32_e32 v142, 0xbfb8aa3b, v133
	v_exp_f32_e32 v142, v142
	v_mul_f32_e32 v2, v85, v2
	v_add_f32_e32 v142, 1.0, v142
	v_div_scale_f32 v146, s[0:1], v142, v142, v133
	v_rcp_f32_e32 v147, v146
	s_nop 0
	v_fma_f32 v148, -v146, v147, 1.0
	v_fmac_f32_e32 v147, v148, v147
	v_div_scale_f32 v148, vcc, v133, v142, v133
	v_mul_f32_e32 v149, v148, v147
	v_fma_f32 v160, -v146, v149, v148
	v_fmac_f32_e32 v149, v160, v147
	v_fma_f32 v146, -v146, v149, v148
	v_div_fmas_f32 v146, v146, v147, v149
	v_div_fixup_f32 v133, v146, v142, v133
	v_and_b32_e32 v142, 0xffff0000, v143
	v_mul_f32_e32 v143, 0xbfb8aa3b, v142
	v_exp_f32_e32 v143, v143
	v_mul_f32_e32 v133, v86, v133
	v_add_f32_e32 v143, 1.0, v143
	v_div_scale_f32 v146, s[0:1], v143, v143, v142
	v_rcp_f32_e32 v147, v146
	s_nop 0
	v_fma_f32 v148, -v146, v147, 1.0
	v_fmac_f32_e32 v147, v148, v147
	v_div_scale_f32 v148, vcc, v142, v143, v142
	v_mul_f32_e32 v149, v148, v147
	v_fma_f32 v160, -v146, v149, v148
	v_fmac_f32_e32 v149, v160, v147
	v_fma_f32 v146, -v146, v149, v148
	v_div_fmas_f32 v146, v146, v147, v149
	v_div_fixup_f32 v142, v146, v143, v142
	v_mul_f32_e32 v143, v87, v142
	v_cvt_pk_bf16_f32 v142, v1, v2
	v_cvt_pk_bf16_f32 v143, v133, v143
	flat_store_dwordx2 v[138:139], v[142:143] offset:32
	s_waitcnt vmcnt(31)
	v_mov_b32_e32 v142, v222
	v_mov_b32_e32 v143, v223
	v_lshlrev_b32_e32 v1, 16, v142
	v_mul_f32_e32 v2, 0xbfb8aa3b, v1
	v_exp_f32_e32 v2, v2
	s_nop 0
	v_add_f32_e32 v2, 1.0, v2
	v_div_scale_f32 v133, s[0:1], v2, v2, v1
	v_rcp_f32_e32 v146, v133
	s_nop 0
	v_fma_f32 v147, -v133, v146, 1.0
	v_fmac_f32_e32 v146, v147, v146
	v_div_scale_f32 v147, vcc, v1, v2, v1
	v_mul_f32_e32 v148, v147, v146
	v_fma_f32 v149, -v133, v148, v147
	v_fmac_f32_e32 v148, v149, v146
	v_fma_f32 v133, -v133, v148, v147
	v_div_fmas_f32 v133, v133, v146, v148
	v_div_fixup_f32 v1, v133, v2, v1
	v_and_b32_e32 v2, 0xffff0000, v142
	v_mul_f32_e32 v133, 0xbfb8aa3b, v2
	v_exp_f32_e32 v133, v133
	v_mul_f32_e32 v1, v96, v1
	v_add_f32_e32 v133, 1.0, v133
	v_div_scale_f32 v142, s[0:1], v133, v133, v2
	v_rcp_f32_e32 v146, v142
	s_nop 0
	v_fma_f32 v147, -v142, v146, 1.0
	v_fmac_f32_e32 v146, v147, v146
	v_div_scale_f32 v147, vcc, v2, v133, v2
	v_mul_f32_e32 v148, v147, v146
	v_fma_f32 v149, -v142, v148, v147
	v_fmac_f32_e32 v148, v149, v146
	v_fma_f32 v142, -v142, v148, v147
	v_div_fmas_f32 v142, v142, v146, v148
	v_div_fixup_f32 v2, v142, v133, v2
	v_lshlrev_b32_e32 v133, 16, v143
	v_mul_f32_e32 v142, 0xbfb8aa3b, v133
	v_exp_f32_e32 v142, v142
	v_mul_f32_e32 v2, v97, v2
	v_add_f32_e32 v142, 1.0, v142
	v_div_scale_f32 v146, s[0:1], v142, v142, v133
	v_rcp_f32_e32 v147, v146
	s_nop 0
	v_fma_f32 v148, -v146, v147, 1.0
	v_fmac_f32_e32 v147, v148, v147
	v_div_scale_f32 v148, vcc, v133, v142, v133
	v_mul_f32_e32 v149, v148, v147
	v_fma_f32 v160, -v146, v149, v148
	v_fmac_f32_e32 v149, v160, v147
	v_fma_f32 v146, -v146, v149, v148
	v_div_fmas_f32 v146, v146, v147, v149
	v_div_fixup_f32 v133, v146, v142, v133
	v_and_b32_e32 v142, 0xffff0000, v143
	v_mul_f32_e32 v143, 0xbfb8aa3b, v142
	v_exp_f32_e32 v143, v143
	v_mul_f32_e32 v133, v98, v133
	v_add_f32_e32 v143, 1.0, v143
	v_div_scale_f32 v146, s[0:1], v143, v143, v142
	v_rcp_f32_e32 v147, v146
	s_nop 0
	v_fma_f32 v148, -v146, v147, 1.0
	v_fmac_f32_e32 v147, v148, v147
	v_div_scale_f32 v148, vcc, v142, v143, v142
	v_mul_f32_e32 v149, v148, v147
	v_fma_f32 v160, -v146, v149, v148
	v_fmac_f32_e32 v149, v160, v147
	v_fma_f32 v146, -v146, v149, v148
	v_div_fmas_f32 v146, v146, v147, v149
	v_div_fixup_f32 v142, v146, v143, v142
	v_mul_f32_e32 v143, v99, v142
	v_cvt_pk_bf16_f32 v142, v1, v2
	v_cvt_pk_bf16_f32 v143, v133, v143
	flat_store_dwordx2 v[138:139], v[142:143] offset:256
	s_waitcnt vmcnt(31)
; __device__ __forceinline__ float bf_lo(unsigned u) { return __uint_as_float(u << 16); }
; __device__ __forceinline__ float bf_hi(unsigned u) { return __uint_as_float(u & 0xffff0000u); }
; __device__ __forceinline__ float silu(float z) { return z / (1.f + __expf(-z)); }
; __device__ __forceinline__ void gemm_tile(const GemmArgs& g, bf16* shm, const int tid, const int wid, char* wsb, const float* gnext) {
;     ...
;     for (int ai = 0; ai < 2; ++ai)
; #pragma unroll
;       for (int m = 0; m < 4; ++m) {
;         const int row = ai * HALF + m * 16 + rbase;
;         bf16* Cr = C + (long)row * g.ldc + cbase; const bf16* Zr = Z + (long)row * g.ldx + cbase;
; #pragma unroll
;         for (int bj = 0; bj < 2; ++bj)
; #pragma unroll
;           for (int n = 0; n < 2; ++n) {
;             f32x4 v = acc[ai][bj][m][n];
;             u32x2 z = *reinterpret_cast<const u32x2*>(Zr + bj * HALF + n * 16);
;             float o0 = v[0] * silu(bf_lo(z[0])), o1 = v[1] * silu(bf_hi(z[0]));
;             float o2 = v[2] * silu(bf_lo(z[1])), o3 = v[3] * silu(bf_hi(z[1]));
;             u32x2 w = {cvtpk(o0, o1), cvtpk(o2, o3)};
;             *reinterpret_cast<u32x2*>(Cr + bj * HALF + n * 16) = w;
;           }
	v_mov_b32_e32 v140, v224
	v_mov_b32_e32 v141, v225
	v_lshlrev_b32_e32 v1, 16, v140
	v_mul_f32_e32 v2, 0xbfb8aa3b, v1
	v_exp_f32_e32 v2, v2
	s_nop 0
	v_add_f32_e32 v2, 1.0, v2
	v_div_scale_f32 v133, s[0:1], v2, v2, v1
	v_rcp_f32_e32 v142, v133
	s_nop 0
	v_fma_f32 v143, -v133, v142, 1.0
	v_fmac_f32_e32 v142, v143, v142
	v_div_scale_f32 v143, vcc, v1, v2, v1
	v_mul_f32_e32 v146, v143, v142
	v_fma_f32 v147, -v133, v146, v143
	v_fmac_f32_e32 v146, v147, v142
	v_fma_f32 v133, -v133, v146, v143
	v_div_fmas_f32 v133, v133, v142, v146
	v_div_fixup_f32 v1, v133, v2, v1
	v_and_b32_e32 v2, 0xffff0000, v140
	v_mul_f32_e32 v133, 0xbfb8aa3b, v2
	v_exp_f32_e32 v133, v133
	v_mul_f32_e32 v1, v88, v1
	v_add_f32_e32 v133, 1.0, v133
	v_div_scale_f32 v140, s[0:1], v133, v133, v2
	v_rcp_f32_e32 v142, v140
	s_nop 0
	v_fma_f32 v143, -v140, v142, 1.0
	v_fmac_f32_e32 v142, v143, v142
	v_div_scale_f32 v143, vcc, v2, v133, v2
	v_mul_f32_e32 v146, v143, v142
	v_fma_f32 v147, -v140, v146, v143
	v_fmac_f32_e32 v146, v147, v142
	v_fma_f32 v140, -v140, v146, v143
	v_div_fmas_f32 v140, v140, v142, v146
	v_div_fixup_f32 v2, v140, v133, v2
	v_lshlrev_b32_e32 v133, 16, v141
	v_mul_f32_e32 v140, 0xbfb8aa3b, v133
	v_exp_f32_e32 v140, v140
	v_mul_f32_e32 v2, v89, v2
	v_add_f32_e32 v140, 1.0, v140
	v_div_scale_f32 v142, s[0:1], v140, v140, v133
	v_rcp_f32_e32 v143, v142
	s_nop 0
	v_fma_f32 v146, -v142, v143, 1.0
	v_fmac_f32_e32 v143, v146, v143
	v_div_scale_f32 v146, vcc, v133, v140, v133
	v_mul_f32_e32 v147, v146, v143
	v_fma_f32 v148, -v142, v147, v146
	v_fmac_f32_e32 v147, v148, v143
	v_fma_f32 v142, -v142, v147, v146
	v_div_fmas_f32 v142, v142, v143, v147
	v_div_fixup_f32 v133, v142, v140, v133
	v_and_b32_e32 v140, 0xffff0000, v141
	v_mul_f32_e32 v141, 0xbfb8aa3b, v140
	v_exp_f32_e32 v141, v141
	v_mul_f32_e32 v133, v90, v133
	v_add_f32_e32 v141, 1.0, v141
	v_div_scale_f32 v142, s[0:1], v141, v141, v140
	v_rcp_f32_e32 v143, v142
	s_nop 0
	v_fma_f32 v146, -v142, v143, 1.0
	v_fmac_f32_e32 v143, v146, v143
	v_div_scale_f32 v146, vcc, v140, v141, v140
	v_mul_f32_e32 v147, v146, v143
	v_fma_f32 v148, -v142, v147, v146
	v_fmac_f32_e32 v147, v148, v143
	v_fma_f32 v142, -v142, v147, v146
	v_div_fmas_f32 v142, v142, v143, v147
	v_div_fixup_f32 v140, v142, v141, v140
	v_mul_f32_e32 v141, v91, v140
	v_cvt_pk_bf16_f32 v140, v1, v2
	v_cvt_pk_bf16_f32 v141, v133, v141
	v_add_u32_e32 v1, 48, v0
	flat_store_dwordx2 v[138:139], v[140:141] offset:288
	v_mad_i64_i32 v[140:141], s[0:1], v1, s67, 0
	v_lshl_add_u64 v[140:141], v[140:141], 1, v[134:135]
	s_waitcnt vmcnt(31)
	v_mov_b32_e32 v142, v226
	v_mov_b32_e32 v143, v227
	v_mad_i64_i32 v[138:139], s[0:1], v1, s66, 0
	v_lshl_add_u64 v[138:139], v[138:139], 1, v[136:137]
	v_lshlrev_b32_e32 v1, 16, v142
	v_mul_f32_e32 v2, 0xbfb8aa3b, v1
	v_exp_f32_e32 v2, v2
	s_nop 0
	v_add_f32_e32 v2, 1.0, v2
	v_div_scale_f32 v133, s[0:1], v2, v2, v1
	v_rcp_f32_e32 v146, v133
	s_nop 0
	v_fma_f32 v147, -v133, v146, 1.0
	v_fmac_f32_e32 v146, v147, v146
	v_div_scale_f32 v147, vcc, v1, v2, v1
	v_mul_f32_e32 v148, v147, v146
	v_fma_f32 v149, -v133, v148, v147
	v_fmac_f32_e32 v148, v149, v146
	v_fma_f32 v133, -v133, v148, v147
	v_div_fmas_f32 v133, v133, v146, v148
	v_div_fixup_f32 v1, v133, v2, v1
	v_and_b32_e32 v2, 0xffff0000, v142
	v_mul_f32_e32 v133, 0xbfb8aa3b, v2
	v_exp_f32_e32 v133, v133
	v_mul_f32_e32 v1, v76, v1
	v_add_f32_e32 v133, 1.0, v133
	v_div_scale_f32 v142, s[0:1], v133, v133, v2
	v_rcp_f32_e32 v146, v142
	s_nop 0
	v_fma_f32 v147, -v142, v146, 1.0
	v_fmac_f32_e32 v146, v147, v146
	v_div_scale_f32 v147, vcc, v2, v133, v2
	v_mul_f32_e32 v148, v147, v146
	v_fma_f32 v149, -v142, v148, v147
	v_fmac_f32_e32 v148, v149, v146
	v_fma_f32 v142, -v142, v148, v147
	v_div_fmas_f32 v142, v142, v146, v148
	v_div_fixup_f32 v2, v142, v133, v2
	v_lshlrev_b32_e32 v133, 16, v143
	v_mul_f32_e32 v142, 0xbfb8aa3b, v133
	v_exp_f32_e32 v142, v142
	v_mul_f32_e32 v2, v77, v2
	v_add_f32_e32 v142, 1.0, v142
	v_div_scale_f32 v146, s[0:1], v142, v142, v133
	v_rcp_f32_e32 v147, v146
	s_nop 0
	v_fma_f32 v148, -v146, v147, 1.0
	v_fmac_f32_e32 v147, v148, v147
	v_div_scale_f32 v148, vcc, v133, v142, v133
	v_mul_f32_e32 v149, v148, v147
	v_fma_f32 v160, -v146, v149, v148
	v_fmac_f32_e32 v149, v160, v147
	v_fma_f32 v146, -v146, v149, v148
	v_div_fmas_f32 v146, v146, v147, v149
	v_div_fixup_f32 v133, v146, v142, v133
	v_and_b32_e32 v142, 0xffff0000, v143
	v_mul_f32_e32 v143, 0xbfb8aa3b, v142
	v_exp_f32_e32 v143, v143
	v_mul_f32_e32 v133, v78, v133
	v_add_f32_e32 v143, 1.0, v143
	v_div_scale_f32 v146, s[0:1], v143, v143, v142
	v_rcp_f32_e32 v147, v146
	s_nop 0
	v_fma_f32 v148, -v146, v147, 1.0
	v_fmac_f32_e32 v147, v148, v147
	v_div_scale_f32 v148, vcc, v142, v143, v142
	v_mul_f32_e32 v149, v148, v147
	v_fma_f32 v160, -v146, v149, v148
	v_fmac_f32_e32 v149, v160, v147
	v_fma_f32 v146, -v146, v149, v148
	v_div_fmas_f32 v146, v146, v147, v149
	v_div_fixup_f32 v142, v146, v143, v142
	v_mul_f32_e32 v143, v79, v142
	v_cvt_pk_bf16_f32 v142, v1, v2
	v_cvt_pk_bf16_f32 v143, v133, v143
	flat_store_dwordx2 v[138:139], v[142:143]
	s_waitcnt vmcnt(31)
; __device__ __forceinline__ float bf_lo(unsigned u) { return __uint_as_float(u << 16); }
; __device__ __forceinline__ float bf_hi(unsigned u) { return __uint_as_float(u & 0xffff0000u); }
; __device__ __forceinline__ float silu(float z) { return z / (1.f + __expf(-z)); }
; __device__ __forceinline__ void gemm_tile(const GemmArgs& g, bf16* shm, const int tid, const int wid, char* wsb, const float* gnext) {
;     ...
;     for (int ai = 0; ai < 2; ++ai)
; #pragma unroll
;       for (int m = 0; m < 4; ++m) {
;         const int row = ai * HALF + m * 16 + rbase;
;         bf16* Cr = C + (long)row * g.ldc + cbase; const bf16* Zr = Z + (long)row * g.ldx + cbase;
; #pragma unroll
;         for (int bj = 0; bj < 2; ++bj)
; #pragma unroll
;           for (int n = 0; n < 2; ++n) {
;             f32x4 v = acc[ai][bj][m][n];
;             u32x2 z = *reinterpret_cast<const u32x2*>(Zr + bj * HALF + n * 16);
;             float o0 = v[0] * silu(bf_lo(z[0])), o1 = v[1] * silu(bf_hi(z[0]));
;             float o2 = v[2] * silu(bf_lo(z[1])), o3 = v[3] * silu(bf_hi(z[1]));
;             u32x2 w = {cvtpk(o0, o1), cvtpk(o2, o3)};
;             *reinterpret_cast<u32x2*>(Cr + bj * HALF + n * 16) = w;
;           }
	v_mov_b32_e32 v142, v228
	v_mov_b32_e32 v143, v229
	v_lshlrev_b32_e32 v1, 16, v142
	v_mul_f32_e32 v2, 0xbfb8aa3b, v1
	v_exp_f32_e32 v2, v2
	s_nop 0
	v_add_f32_e32 v2, 1.0, v2
	v_div_scale_f32 v133, s[0:1], v2, v2, v1
	v_rcp_f32_e32 v146, v133
	s_nop 0
	v_fma_f32 v147, -v133, v146, 1.0
	v_fmac_f32_e32 v146, v147, v146
	v_div_scale_f32 v147, vcc, v1, v2, v1
	v_mul_f32_e32 v148, v147, v146
	v_fma_f32 v149, -v133, v148, v147
	v_fmac_f32_e32 v148, v149, v146
	v_fma_f32 v133, -v133, v148, v147
	v_div_fmas_f32 v133, v133, v146, v148
	v_div_fixup_f32 v1, v133, v2, v1
	v_and_b32_e32 v2, 0xffff0000, v142
	v_mul_f32_e32 v133, 0xbfb8aa3b, v2
	v_exp_f32_e32 v133, v133
	v_mul_f32_e32 v1, v68, v1
	v_add_f32_e32 v133, 1.0, v133
	v_div_scale_f32 v142, s[0:1], v133, v133, v2
	v_rcp_f32_e32 v146, v142
	s_nop 0
	v_fma_f32 v147, -v142, v146, 1.0
	v_fmac_f32_e32 v146, v147, v146
	v_div_scale_f32 v147, vcc, v2, v133, v2
	v_mul_f32_e32 v148, v147, v146
	v_fma_f32 v149, -v142, v148, v147
	v_fmac_f32_e32 v148, v149, v146
	v_fma_f32 v142, -v142, v148, v147
	v_div_fmas_f32 v142, v142, v146, v148
	v_div_fixup_f32 v2, v142, v133, v2
	v_lshlrev_b32_e32 v133, 16, v143
	v_mul_f32_e32 v142, 0xbfb8aa3b, v133
	v_exp_f32_e32 v142, v142
	v_mul_f32_e32 v2, v69, v2
	v_add_f32_e32 v142, 1.0, v142
	v_div_scale_f32 v146, s[0:1], v142, v142, v133
	v_rcp_f32_e32 v147, v146
	s_nop 0
	v_fma_f32 v148, -v146, v147, 1.0
	v_fmac_f32_e32 v147, v148, v147
	v_div_scale_f32 v148, vcc, v133, v142, v133
	v_mul_f32_e32 v149, v148, v147
	v_fma_f32 v160, -v146, v149, v148
	v_fmac_f32_e32 v149, v160, v147
	v_fma_f32 v146, -v146, v149, v148
	v_div_fmas_f32 v146, v146, v147, v149
	v_div_fixup_f32 v133, v146, v142, v133
	v_and_b32_e32 v142, 0xffff0000, v143
	v_mul_f32_e32 v143, 0xbfb8aa3b, v142
	v_exp_f32_e32 v143, v143
	v_mul_f32_e32 v133, v70, v133
	v_add_f32_e32 v143, 1.0, v143
	v_div_scale_f32 v146, s[0:1], v143, v143, v142
	v_rcp_f32_e32 v147, v146
	s_nop 0
	v_fma_f32 v148, -v146, v147, 1.0
	v_fmac_f32_e32 v147, v148, v147
	v_div_scale_f32 v148, vcc, v142, v143, v142
	v_mul_f32_e32 v149, v148, v147
	v_fma_f32 v160, -v146, v149, v148
	v_fmac_f32_e32 v149, v160, v147
	v_fma_f32 v146, -v146, v149, v148
	v_div_fmas_f32 v146, v146, v147, v149
	v_div_fixup_f32 v142, v146, v143, v142
	v_mul_f32_e32 v143, v71, v142
	v_cvt_pk_bf16_f32 v142, v1, v2
	v_cvt_pk_bf16_f32 v143, v133, v143
	flat_store_dwordx2 v[138:139], v[142:143] offset:32
	s_waitcnt vmcnt(31)
	v_mov_b32_e32 v142, v230
	v_mov_b32_e32 v143, v231
	v_lshlrev_b32_e32 v1, 16, v142
	v_mul_f32_e32 v2, 0xbfb8aa3b, v1
	v_exp_f32_e32 v2, v2
	s_nop 0
	v_add_f32_e32 v2, 1.0, v2
	v_div_scale_f32 v133, s[0:1], v2, v2, v1
	v_rcp_f32_e32 v146, v133
	s_nop 0
	v_fma_f32 v147, -v133, v146, 1.0
	v_fmac_f32_e32 v146, v147, v146
	v_div_scale_f32 v147, vcc, v1, v2, v1
	v_mul_f32_e32 v148, v147, v146
	v_fma_f32 v149, -v133, v148, v147
	v_fmac_f32_e32 v148, v149, v146
	v_fma_f32 v133, -v133, v148, v147
	v_div_fmas_f32 v133, v133, v146, v148
	v_div_fixup_f32 v1, v133, v2, v1
	v_and_b32_e32 v2, 0xffff0000, v142
	v_mul_f32_e32 v133, 0xbfb8aa3b, v2
	v_exp_f32_e32 v133, v133
	v_mul_f32_e32 v1, v80, v1
	v_add_f32_e32 v133, 1.0, v133
	v_div_scale_f32 v142, s[0:1], v133, v133, v2
	v_rcp_f32_e32 v146, v142
	s_nop 0
	v_fma_f32 v147, -v142, v146, 1.0
	v_fmac_f32_e32 v146, v147, v146
	v_div_scale_f32 v147, vcc, v2, v133, v2
	v_mul_f32_e32 v148, v147, v146
	v_fma_f32 v149, -v142, v148, v147
	v_fmac_f32_e32 v148, v149, v146
	v_fma_f32 v142, -v142, v148, v147
	v_div_fmas_f32 v142, v142, v146, v148
	v_div_fixup_f32 v2, v142, v133, v2
	v_lshlrev_b32_e32 v133, 16, v143
	v_mul_f32_e32 v142, 0xbfb8aa3b, v133
	v_exp_f32_e32 v142, v142
	v_mul_f32_e32 v2, v81, v2
	v_add_f32_e32 v142, 1.0, v142
	v_div_scale_f32 v146, s[0:1], v142, v142, v133
	v_rcp_f32_e32 v147, v146
	s_nop 0
	v_fma_f32 v148, -v146, v147, 1.0
	v_fmac_f32_e32 v147, v148, v147
	v_div_scale_f32 v148, vcc, v133, v142, v133
	v_mul_f32_e32 v149, v148, v147
	v_fma_f32 v160, -v146, v149, v148
	v_fmac_f32_e32 v149, v160, v147
	v_fma_f32 v146, -v146, v149, v148
	v_div_fmas_f32 v146, v146, v147, v149
	v_div_fixup_f32 v133, v146, v142, v133
	v_and_b32_e32 v142, 0xffff0000, v143
	v_mul_f32_e32 v143, 0xbfb8aa3b, v142
	v_exp_f32_e32 v143, v143
	v_mul_f32_e32 v133, v82, v133
	v_add_f32_e32 v143, 1.0, v143
	v_div_scale_f32 v146, s[0:1], v143, v143, v142
	v_rcp_f32_e32 v147, v146
	s_nop 0
	v_fma_f32 v148, -v146, v147, 1.0
	v_fmac_f32_e32 v147, v148, v147
	v_div_scale_f32 v148, vcc, v142, v143, v142
	v_mul_f32_e32 v149, v148, v147
	v_fma_f32 v160, -v146, v149, v148
	v_fmac_f32_e32 v149, v160, v147
	v_fma_f32 v146, -v146, v149, v148
	v_div_fmas_f32 v146, v146, v147, v149
	v_div_fixup_f32 v142, v146, v143, v142
	v_mul_f32_e32 v143, v83, v142
	v_cvt_pk_bf16_f32 v142, v1, v2
	v_cvt_pk_bf16_f32 v143, v133, v143
	flat_store_dwordx2 v[138:139], v[142:143] offset:256
	s_waitcnt vmcnt(31)
; __device__ __forceinline__ float bf_lo(unsigned u) { return __uint_as_float(u << 16); }
; __device__ __forceinline__ float bf_hi(unsigned u) { return __uint_as_float(u & 0xffff0000u); }
; __device__ __forceinline__ float silu(float z) { return z / (1.f + __expf(-z)); }
; __device__ __forceinline__ void gemm_tile(const GemmArgs& g, bf16* shm, const int tid, const int wid, char* wsb, const float* gnext) {
;     ...
;     for (int ai = 0; ai < 2; ++ai)
; #pragma unroll
;       for (int m = 0; m < 4; ++m) {
;         const int row = ai * HALF + m * 16 + rbase;
;         bf16* Cr = C + (long)row * g.ldc + cbase; const bf16* Zr = Z + (long)row * g.ldx + cbase;
; #pragma unroll
;         for (int bj = 0; bj < 2; ++bj)
; #pragma unroll
;           for (int n = 0; n < 2; ++n) {
;             f32x4 v = acc[ai][bj][m][n];
;             u32x2 z = *reinterpret_cast<const u32x2*>(Zr + bj * HALF + n * 16);
;             float o0 = v[0] * silu(bf_lo(z[0])), o1 = v[1] * silu(bf_hi(z[0]));
;             float o2 = v[2] * silu(bf_lo(z[1])), o3 = v[3] * silu(bf_hi(z[1]));
;             u32x2 w = {cvtpk(o0, o1), cvtpk(o2, o3)};
;             *reinterpret_cast<u32x2*>(Cr + bj * HALF + n * 16) = w;
;           }
	v_mov_b32_e32 v140, v232
	v_mov_b32_e32 v141, v233
	v_lshlrev_b32_e32 v1, 16, v140
	v_mul_f32_e32 v2, 0xbfb8aa3b, v1
	v_exp_f32_e32 v2, v2
	s_nop 0
	v_add_f32_e32 v2, 1.0, v2
	v_div_scale_f32 v133, s[0:1], v2, v2, v1
	v_rcp_f32_e32 v142, v133
	s_nop 0
	v_fma_f32 v143, -v133, v142, 1.0
	v_fmac_f32_e32 v142, v143, v142
	v_div_scale_f32 v143, vcc, v1, v2, v1
	v_mul_f32_e32 v146, v143, v142
	v_fma_f32 v147, -v133, v146, v143
	v_fmac_f32_e32 v146, v147, v142
	v_fma_f32 v133, -v133, v146, v143
	v_div_fmas_f32 v133, v133, v142, v146
	v_div_fixup_f32 v1, v133, v2, v1
	v_and_b32_e32 v2, 0xffff0000, v140
	v_mul_f32_e32 v133, 0xbfb8aa3b, v2
	v_exp_f32_e32 v133, v133
	v_mul_f32_e32 v1, v72, v1
	v_add_f32_e32 v133, 1.0, v133
	v_div_scale_f32 v140, s[0:1], v133, v133, v2
	v_rcp_f32_e32 v142, v140
	s_nop 0
	v_fma_f32 v143, -v140, v142, 1.0
	v_fmac_f32_e32 v142, v143, v142
	v_div_scale_f32 v143, vcc, v2, v133, v2
	v_mul_f32_e32 v146, v143, v142
	v_fma_f32 v147, -v140, v146, v143
	v_fmac_f32_e32 v146, v147, v142
	v_fma_f32 v140, -v140, v146, v143
	v_div_fmas_f32 v140, v140, v142, v146
	v_div_fixup_f32 v2, v140, v133, v2
	v_lshlrev_b32_e32 v133, 16, v141
	v_mul_f32_e32 v140, 0xbfb8aa3b, v133
	v_exp_f32_e32 v140, v140
	v_mul_f32_e32 v2, v73, v2
	v_add_f32_e32 v140, 1.0, v140
	v_div_scale_f32 v142, s[0:1], v140, v140, v133
	v_rcp_f32_e32 v143, v142
	s_nop 0
	v_fma_f32 v146, -v142, v143, 1.0
	v_fmac_f32_e32 v143, v146, v143
	v_div_scale_f32 v146, vcc, v133, v140, v133
	v_mul_f32_e32 v147, v146, v143
	v_fma_f32 v148, -v142, v147, v146
	v_fmac_f32_e32 v147, v148, v143
	v_fma_f32 v142, -v142, v147, v146
	v_div_fmas_f32 v142, v142, v143, v147
	v_div_fixup_f32 v133, v142, v140, v133
	v_and_b32_e32 v140, 0xffff0000, v141
	v_mul_f32_e32 v141, 0xbfb8aa3b, v140
	v_exp_f32_e32 v141, v141
	v_mul_f32_e32 v133, v74, v133
	v_add_f32_e32 v141, 1.0, v141
	v_div_scale_f32 v142, s[0:1], v141, v141, v140
	v_rcp_f32_e32 v143, v142
	s_nop 0
	v_fma_f32 v146, -v142, v143, 1.0
	v_fmac_f32_e32 v143, v146, v143
	v_div_scale_f32 v146, vcc, v140, v141, v140
	v_mul_f32_e32 v147, v146, v143
	v_fma_f32 v148, -v142, v147, v146
	v_fmac_f32_e32 v147, v148, v143
	v_fma_f32 v142, -v142, v147, v146
	v_div_fmas_f32 v142, v142, v143, v147
	v_div_fixup_f32 v140, v142, v141, v140
	v_mul_f32_e32 v141, v75, v140
	v_cvt_pk_bf16_f32 v140, v1, v2
	v_cvt_pk_bf16_f32 v141, v133, v141
	v_add_u32_e32 v1, 0x80, v0
	flat_store_dwordx2 v[138:139], v[140:141] offset:288
	v_mad_i64_i32 v[140:141], s[0:1], v1, s67, 0
	v_lshl_add_u64 v[140:141], v[140:141], 1, v[134:135]
	s_waitcnt vmcnt(31)
	v_mov_b32_e32 v142, v234
	v_mov_b32_e32 v143, v235
	v_mad_i64_i32 v[138:139], s[0:1], v1, s66, 0
	v_lshl_add_u64 v[138:139], v[138:139], 1, v[136:137]
	v_lshlrev_b32_e32 v1, 16, v142
	v_mul_f32_e32 v2, 0xbfb8aa3b, v1
	v_exp_f32_e32 v2, v2
	s_nop 0
	v_add_f32_e32 v2, 1.0, v2
	v_div_scale_f32 v133, s[0:1], v2, v2, v1
	v_rcp_f32_e32 v146, v133
	s_nop 0
	v_fma_f32 v147, -v133, v146, 1.0
	v_fmac_f32_e32 v146, v147, v146
	v_div_scale_f32 v147, vcc, v1, v2, v1
	v_mul_f32_e32 v148, v147, v146
	v_fma_f32 v149, -v133, v148, v147
	v_fmac_f32_e32 v148, v149, v146
	v_fma_f32 v133, -v133, v148, v147
	v_div_fmas_f32 v133, v133, v146, v148
	v_div_fixup_f32 v1, v133, v2, v1
	v_and_b32_e32 v2, 0xffff0000, v142
	v_mul_f32_e32 v133, 0xbfb8aa3b, v2
	v_exp_f32_e32 v133, v133
	v_mul_f32_e32 v1, v64, v1
	v_add_f32_e32 v133, 1.0, v133
	v_div_scale_f32 v142, s[0:1], v133, v133, v2
	v_rcp_f32_e32 v146, v142
	s_nop 0
	v_fma_f32 v147, -v142, v146, 1.0
	v_fmac_f32_e32 v146, v147, v146
	v_div_scale_f32 v147, vcc, v2, v133, v2
	v_mul_f32_e32 v148, v147, v146
	v_fma_f32 v149, -v142, v148, v147
	v_fmac_f32_e32 v148, v149, v146
	v_fma_f32 v142, -v142, v148, v147
	v_div_fmas_f32 v142, v142, v146, v148
	v_div_fixup_f32 v2, v142, v133, v2
	v_lshlrev_b32_e32 v133, 16, v143
	v_mul_f32_e32 v142, 0xbfb8aa3b, v133
	v_exp_f32_e32 v142, v142
	v_mul_f32_e32 v2, v65, v2
	v_add_f32_e32 v142, 1.0, v142
	v_div_scale_f32 v146, s[0:1], v142, v142, v133
	v_rcp_f32_e32 v147, v146
	s_nop 0
	v_fma_f32 v148, -v146, v147, 1.0
	v_fmac_f32_e32 v147, v148, v147
	v_div_scale_f32 v148, vcc, v133, v142, v133
	v_mul_f32_e32 v149, v148, v147
	v_fma_f32 v160, -v146, v149, v148
	v_fmac_f32_e32 v149, v160, v147
	v_fma_f32 v146, -v146, v149, v148
	v_div_fmas_f32 v146, v146, v147, v149
	v_div_fixup_f32 v133, v146, v142, v133
	v_and_b32_e32 v142, 0xffff0000, v143
	v_mul_f32_e32 v143, 0xbfb8aa3b, v142
	v_exp_f32_e32 v143, v143
	v_mul_f32_e32 v133, v66, v133
	v_add_f32_e32 v143, 1.0, v143
	v_div_scale_f32 v146, s[0:1], v143, v143, v142
	v_rcp_f32_e32 v147, v146
	s_nop 0
	v_fma_f32 v148, -v146, v147, 1.0
	v_fmac_f32_e32 v147, v148, v147
	v_div_scale_f32 v148, vcc, v142, v143, v142
	v_mul_f32_e32 v149, v148, v147
	v_fma_f32 v160, -v146, v149, v148
	v_fmac_f32_e32 v149, v160, v147
	v_fma_f32 v146, -v146, v149, v148
	v_div_fmas_f32 v146, v146, v147, v149
	v_div_fixup_f32 v142, v146, v143, v142
	v_mul_f32_e32 v143, v67, v142
	v_cvt_pk_bf16_f32 v142, v1, v2
	v_cvt_pk_bf16_f32 v143, v133, v143
	flat_store_dwordx2 v[138:139], v[142:143]
	s_waitcnt vmcnt(31)
; __device__ __forceinline__ float bf_lo(unsigned u) { return __uint_as_float(u << 16); }
; __device__ __forceinline__ float bf_hi(unsigned u) { return __uint_as_float(u & 0xffff0000u); }
; __device__ __forceinline__ float silu(float z) { return z / (1.f + __expf(-z)); }
; __device__ __forceinline__ void gemm_tile(const GemmArgs& g, bf16* shm, const int tid, const int wid, char* wsb, const float* gnext) {
;     ...
;     for (int ai = 0; ai < 2; ++ai)
; #pragma unroll
;       for (int m = 0; m < 4; ++m) {
;         const int row = ai * HALF + m * 16 + rbase;
;         bf16* Cr = C + (long)row * g.ldc + cbase; const bf16* Zr = Z + (long)row * g.ldx + cbase;
; #pragma unroll
;         for (int bj = 0; bj < 2; ++bj)
; #pragma unroll
;           for (int n = 0; n < 2; ++n) {
;             f32x4 v = acc[ai][bj][m][n];
;             u32x2 z = *reinterpret_cast<const u32x2*>(Zr + bj * HALF + n * 16);
;             float o0 = v[0] * silu(bf_lo(z[0])), o1 = v[1] * silu(bf_hi(z[0]));
;             float o2 = v[2] * silu(bf_lo(z[1])), o3 = v[3] * silu(bf_hi(z[1]));
;             u32x2 w = {cvtpk(o0, o1), cvtpk(o2, o3)};
;             *reinterpret_cast<u32x2*>(Cr + bj * HALF + n * 16) = w;
;           }
	v_mov_b32_e32 v142, v236
	v_mov_b32_e32 v143, v237
	v_lshlrev_b32_e32 v1, 16, v142
	v_mul_f32_e32 v2, 0xbfb8aa3b, v1
	v_exp_f32_e32 v2, v2
	s_nop 0
	v_add_f32_e32 v2, 1.0, v2
	v_div_scale_f32 v133, s[0:1], v2, v2, v1
	v_rcp_f32_e32 v146, v133
	s_nop 0
	v_fma_f32 v147, -v133, v146, 1.0
	v_fmac_f32_e32 v146, v147, v146
	v_div_scale_f32 v147, vcc, v1, v2, v1
	v_mul_f32_e32 v148, v147, v146
	v_fma_f32 v149, -v133, v148, v147
	v_fmac_f32_e32 v148, v149, v146
	v_fma_f32 v133, -v133, v148, v147
	v_div_fmas_f32 v133, v133, v146, v148
	v_div_fixup_f32 v1, v133, v2, v1
	v_and_b32_e32 v2, 0xffff0000, v142
	v_mul_f32_e32 v133, 0xbfb8aa3b, v2
	v_exp_f32_e32 v133, v133
	v_mul_f32_e32 v1, v56, v1
	v_add_f32_e32 v133, 1.0, v133
	v_div_scale_f32 v142, s[0:1], v133, v133, v2
	v_rcp_f32_e32 v146, v142
	s_nop 0
	v_fma_f32 v147, -v142, v146, 1.0
	v_fmac_f32_e32 v146, v147, v146
	v_div_scale_f32 v147, vcc, v2, v133, v2
	v_mul_f32_e32 v148, v147, v146
	v_fma_f32 v149, -v142, v148, v147
	v_fmac_f32_e32 v148, v149, v146
	v_fma_f32 v142, -v142, v148, v147
	v_div_fmas_f32 v142, v142, v146, v148
	v_div_fixup_f32 v2, v142, v133, v2
	v_lshlrev_b32_e32 v133, 16, v143
	v_mul_f32_e32 v142, 0xbfb8aa3b, v133
	v_exp_f32_e32 v142, v142
	v_mul_f32_e32 v2, v57, v2
	v_add_f32_e32 v142, 1.0, v142
	v_div_scale_f32 v146, s[0:1], v142, v142, v133
	v_rcp_f32_e32 v147, v146
	s_nop 0
	v_fma_f32 v148, -v146, v147, 1.0
	v_fmac_f32_e32 v147, v148, v147
	v_div_scale_f32 v148, vcc, v133, v142, v133
	v_mul_f32_e32 v149, v148, v147
	v_fma_f32 v160, -v146, v149, v148
	v_fmac_f32_e32 v149, v160, v147
	v_fma_f32 v146, -v146, v149, v148
	v_div_fmas_f32 v146, v146, v147, v149
	v_div_fixup_f32 v133, v146, v142, v133
	v_and_b32_e32 v142, 0xffff0000, v143
	v_mul_f32_e32 v143, 0xbfb8aa3b, v142
	v_exp_f32_e32 v143, v143
	v_mul_f32_e32 v133, v58, v133
	v_add_f32_e32 v143, 1.0, v143
	v_div_scale_f32 v146, s[0:1], v143, v143, v142
	v_rcp_f32_e32 v147, v146
	s_nop 0
	v_fma_f32 v148, -v146, v147, 1.0
	v_fmac_f32_e32 v147, v148, v147
	v_div_scale_f32 v148, vcc, v142, v143, v142
	v_mul_f32_e32 v149, v148, v147
	v_fma_f32 v160, -v146, v149, v148
	v_fmac_f32_e32 v149, v160, v147
	v_fma_f32 v146, -v146, v149, v148
	v_div_fmas_f32 v146, v146, v147, v149
	v_div_fixup_f32 v142, v146, v143, v142
	v_mul_f32_e32 v143, v59, v142
	v_cvt_pk_bf16_f32 v142, v1, v2
	v_cvt_pk_bf16_f32 v143, v133, v143
	flat_store_dwordx2 v[138:139], v[142:143] offset:32
	s_waitcnt vmcnt(31)
	v_mov_b32_e32 v142, v238
	v_mov_b32_e32 v143, v239
	v_lshlrev_b32_e32 v1, 16, v142
	v_mul_f32_e32 v2, 0xbfb8aa3b, v1
	v_exp_f32_e32 v2, v2
	s_nop 0
	v_add_f32_e32 v2, 1.0, v2
	v_div_scale_f32 v133, s[0:1], v2, v2, v1
	v_rcp_f32_e32 v146, v133
	s_nop 0
	v_fma_f32 v147, -v133, v146, 1.0
	v_fmac_f32_e32 v146, v147, v146
	v_div_scale_f32 v147, vcc, v1, v2, v1
	v_mul_f32_e32 v148, v147, v146
	v_fma_f32 v149, -v133, v148, v147
	v_fmac_f32_e32 v148, v149, v146
	v_fma_f32 v133, -v133, v148, v147
	v_div_fmas_f32 v133, v133, v146, v148
	v_div_fixup_f32 v1, v133, v2, v1
	v_and_b32_e32 v2, 0xffff0000, v142
	v_mul_f32_e32 v133, 0xbfb8aa3b, v2
	v_exp_f32_e32 v133, v133
	v_mul_f32_e32 v1, v60, v1
	v_add_f32_e32 v133, 1.0, v133
	v_div_scale_f32 v142, s[0:1], v133, v133, v2
	v_rcp_f32_e32 v146, v142
	s_nop 0
	v_fma_f32 v147, -v142, v146, 1.0
	v_fmac_f32_e32 v146, v147, v146
	v_div_scale_f32 v147, vcc, v2, v133, v2
	v_mul_f32_e32 v148, v147, v146
	v_fma_f32 v149, -v142, v148, v147
	v_fmac_f32_e32 v148, v149, v146
	v_fma_f32 v142, -v142, v148, v147
	v_div_fmas_f32 v142, v142, v146, v148
	v_div_fixup_f32 v2, v142, v133, v2
	v_lshlrev_b32_e32 v133, 16, v143
	v_mul_f32_e32 v142, 0xbfb8aa3b, v133
	v_exp_f32_e32 v142, v142
	v_mul_f32_e32 v2, v61, v2
	v_add_f32_e32 v142, 1.0, v142
	v_div_scale_f32 v146, s[0:1], v142, v142, v133
	v_rcp_f32_e32 v147, v146
	s_nop 0
	v_fma_f32 v148, -v146, v147, 1.0
	v_fmac_f32_e32 v147, v148, v147
	v_div_scale_f32 v148, vcc, v133, v142, v133
	v_mul_f32_e32 v149, v148, v147
	v_fma_f32 v160, -v146, v149, v148
	v_fmac_f32_e32 v149, v160, v147
	v_fma_f32 v146, -v146, v149, v148
	v_div_fmas_f32 v146, v146, v147, v149
	v_div_fixup_f32 v133, v146, v142, v133
	v_and_b32_e32 v142, 0xffff0000, v143
	v_mul_f32_e32 v143, 0xbfb8aa3b, v142
	v_exp_f32_e32 v143, v143
	v_mul_f32_e32 v133, v62, v133
	v_add_f32_e32 v143, 1.0, v143
	v_div_scale_f32 v146, s[0:1], v143, v143, v142
	v_rcp_f32_e32 v147, v146
	s_nop 0
	v_fma_f32 v148, -v146, v147, 1.0
	v_fmac_f32_e32 v147, v148, v147
	v_div_scale_f32 v148, vcc, v142, v143, v142
	v_mul_f32_e32 v149, v148, v147
	v_fma_f32 v160, -v146, v149, v148
	v_fmac_f32_e32 v149, v160, v147
	v_fma_f32 v146, -v146, v149, v148
	v_div_fmas_f32 v146, v146, v147, v149
	v_div_fixup_f32 v142, v146, v143, v142
	v_mul_f32_e32 v143, v63, v142
	v_cvt_pk_bf16_f32 v142, v1, v2
	v_cvt_pk_bf16_f32 v143, v133, v143
	flat_store_dwordx2 v[138:139], v[142:143] offset:256
	s_waitcnt vmcnt(31)
; __device__ __forceinline__ float bf_lo(unsigned u) { return __uint_as_float(u << 16); }
; __device__ __forceinline__ float bf_hi(unsigned u) { return __uint_as_float(u & 0xffff0000u); }
; __device__ __forceinline__ float silu(float z) { return z / (1.f + __expf(-z)); }
; __device__ __forceinline__ void gemm_tile(const GemmArgs& g, bf16* shm, const int tid, const int wid, char* wsb, const float* gnext) {
;     ...
;     for (int ai = 0; ai < 2; ++ai)
; #pragma unroll
;       for (int m = 0; m < 4; ++m) {
;         const int row = ai * HALF + m * 16 + rbase;
;         bf16* Cr = C + (long)row * g.ldc + cbase; const bf16* Zr = Z + (long)row * g.ldx + cbase;
; #pragma unroll
;         for (int bj = 0; bj < 2; ++bj)
; #pragma unroll
;           for (int n = 0; n < 2; ++n) {
;             f32x4 v = acc[ai][bj][m][n];
;             u32x2 z = *reinterpret_cast<const u32x2*>(Zr + bj * HALF + n * 16);
;             float o0 = v[0] * silu(bf_lo(z[0])), o1 = v[1] * silu(bf_hi(z[0]));
;             float o2 = v[2] * silu(bf_lo(z[1])), o3 = v[3] * silu(bf_hi(z[1]));
;             u32x2 w = {cvtpk(o0, o1), cvtpk(o2, o3)};
;             *reinterpret_cast<u32x2*>(Cr + bj * HALF + n * 16) = w;
;           }
	v_mov_b32_e32 v140, v240
	v_mov_b32_e32 v141, v241
	v_lshlrev_b32_e32 v1, 16, v140
	v_mul_f32_e32 v2, 0xbfb8aa3b, v1
	v_exp_f32_e32 v2, v2
	s_nop 0
	v_add_f32_e32 v2, 1.0, v2
	v_div_scale_f32 v133, s[0:1], v2, v2, v1
	v_rcp_f32_e32 v142, v133
	s_nop 0
	v_fma_f32 v143, -v133, v142, 1.0
	v_fmac_f32_e32 v142, v143, v142
	v_div_scale_f32 v143, vcc, v1, v2, v1
	v_mul_f32_e32 v146, v143, v142
	v_fma_f32 v147, -v133, v146, v143
	v_fmac_f32_e32 v146, v147, v142
	v_fma_f32 v133, -v133, v146, v143
	v_div_fmas_f32 v133, v133, v142, v146
	v_div_fixup_f32 v1, v133, v2, v1
	v_and_b32_e32 v2, 0xffff0000, v140
	v_mul_f32_e32 v133, 0xbfb8aa3b, v2
	v_exp_f32_e32 v133, v133
	v_mul_f32_e32 v1, v52, v1
	v_add_f32_e32 v133, 1.0, v133
	v_div_scale_f32 v140, s[0:1], v133, v133, v2
	v_rcp_f32_e32 v142, v140
	s_nop 0
	v_fma_f32 v143, -v140, v142, 1.0
	v_fmac_f32_e32 v142, v143, v142
	v_div_scale_f32 v143, vcc, v2, v133, v2
	v_mul_f32_e32 v146, v143, v142
	v_fma_f32 v147, -v140, v146, v143
	v_fmac_f32_e32 v146, v147, v142
	v_fma_f32 v140, -v140, v146, v143
	v_div_fmas_f32 v140, v140, v142, v146
	v_div_fixup_f32 v2, v140, v133, v2
	v_lshlrev_b32_e32 v133, 16, v141
	v_mul_f32_e32 v140, 0xbfb8aa3b, v133
	v_exp_f32_e32 v140, v140
	v_mul_f32_e32 v2, v53, v2
	v_add_f32_e32 v140, 1.0, v140
	v_div_scale_f32 v142, s[0:1], v140, v140, v133
	v_rcp_f32_e32 v143, v142
	s_nop 0
	v_fma_f32 v146, -v142, v143, 1.0
	v_fmac_f32_e32 v143, v146, v143
	v_div_scale_f32 v146, vcc, v133, v140, v133
	v_mul_f32_e32 v147, v146, v143
	v_fma_f32 v148, -v142, v147, v146
	v_fmac_f32_e32 v147, v148, v143
	v_fma_f32 v142, -v142, v147, v146
	v_div_fmas_f32 v142, v142, v143, v147
	v_div_fixup_f32 v133, v142, v140, v133
	v_and_b32_e32 v140, 0xffff0000, v141
	v_mul_f32_e32 v141, 0xbfb8aa3b, v140
	v_exp_f32_e32 v141, v141
	v_mul_f32_e32 v133, v54, v133
	v_add_f32_e32 v141, 1.0, v141
	v_div_scale_f32 v142, s[0:1], v141, v141, v140
	v_rcp_f32_e32 v143, v142
	s_nop 0
	v_fma_f32 v146, -v142, v143, 1.0
	v_fmac_f32_e32 v143, v146, v143
	v_div_scale_f32 v146, vcc, v140, v141, v140
	v_mul_f32_e32 v147, v146, v143
	v_fma_f32 v148, -v142, v147, v146
	v_fmac_f32_e32 v147, v148, v143
	v_fma_f32 v142, -v142, v147, v146
	v_div_fmas_f32 v142, v142, v143, v147
	v_div_fixup_f32 v140, v142, v141, v140
	v_mul_f32_e32 v141, v55, v140
	v_cvt_pk_bf16_f32 v140, v1, v2
	v_cvt_pk_bf16_f32 v141, v133, v141
	v_add_u32_e32 v1, 0x90, v0
	flat_store_dwordx2 v[138:139], v[140:141] offset:288
	v_mad_i64_i32 v[140:141], s[0:1], v1, s67, 0
	v_lshl_add_u64 v[140:141], v[140:141], 1, v[134:135]
	s_waitcnt vmcnt(31)
	v_mov_b32_e32 v142, v242
	v_mov_b32_e32 v143, v243
	v_mad_i64_i32 v[138:139], s[0:1], v1, s66, 0
	v_lshl_add_u64 v[138:139], v[138:139], 1, v[136:137]
	v_lshlrev_b32_e32 v1, 16, v142
	v_mul_f32_e32 v2, 0xbfb8aa3b, v1
	v_exp_f32_e32 v2, v2
	s_nop 0
	v_add_f32_e32 v2, 1.0, v2
	v_div_scale_f32 v133, s[0:1], v2, v2, v1
	v_rcp_f32_e32 v146, v133
	s_nop 0
	v_fma_f32 v147, -v133, v146, 1.0
	v_fmac_f32_e32 v146, v147, v146
	v_div_scale_f32 v147, vcc, v1, v2, v1
	v_mul_f32_e32 v148, v147, v146
	v_fma_f32 v149, -v133, v148, v147
	v_fmac_f32_e32 v148, v149, v146
	v_fma_f32 v133, -v133, v148, v147
	v_div_fmas_f32 v133, v133, v146, v148
	v_div_fixup_f32 v1, v133, v2, v1
	v_and_b32_e32 v2, 0xffff0000, v142
	v_mul_f32_e32 v133, 0xbfb8aa3b, v2
	v_exp_f32_e32 v133, v133
	v_mul_f32_e32 v1, v48, v1
	v_add_f32_e32 v133, 1.0, v133
	v_div_scale_f32 v142, s[0:1], v133, v133, v2
	v_rcp_f32_e32 v146, v142
	s_nop 0
	v_fma_f32 v147, -v142, v146, 1.0
	v_fmac_f32_e32 v146, v147, v146
	v_div_scale_f32 v147, vcc, v2, v133, v2
	v_mul_f32_e32 v148, v147, v146
	v_fma_f32 v149, -v142, v148, v147
	v_fmac_f32_e32 v148, v149, v146
	v_fma_f32 v142, -v142, v148, v147
	v_div_fmas_f32 v142, v142, v146, v148
	v_div_fixup_f32 v2, v142, v133, v2
	v_lshlrev_b32_e32 v133, 16, v143
	v_mul_f32_e32 v142, 0xbfb8aa3b, v133
	v_exp_f32_e32 v142, v142
	v_mul_f32_e32 v2, v49, v2
	v_add_f32_e32 v142, 1.0, v142
	v_div_scale_f32 v146, s[0:1], v142, v142, v133
	v_rcp_f32_e32 v147, v146
	s_nop 0
	v_fma_f32 v148, -v146, v147, 1.0
	v_fmac_f32_e32 v147, v148, v147
	v_div_scale_f32 v148, vcc, v133, v142, v133
	v_mul_f32_e32 v149, v148, v147
	v_fma_f32 v160, -v146, v149, v148
	v_fmac_f32_e32 v149, v160, v147
	v_fma_f32 v146, -v146, v149, v148
	v_div_fmas_f32 v146, v146, v147, v149
	v_div_fixup_f32 v133, v146, v142, v133
	v_and_b32_e32 v142, 0xffff0000, v143
	v_mul_f32_e32 v143, 0xbfb8aa3b, v142
	v_exp_f32_e32 v143, v143
	v_mul_f32_e32 v133, v50, v133
	v_add_f32_e32 v143, 1.0, v143
	v_div_scale_f32 v146, s[0:1], v143, v143, v142
	v_rcp_f32_e32 v147, v146
	s_nop 0
	v_fma_f32 v148, -v146, v147, 1.0
	v_fmac_f32_e32 v147, v148, v147
	v_div_scale_f32 v148, vcc, v142, v143, v142
	v_mul_f32_e32 v149, v148, v147
	v_fma_f32 v160, -v146, v149, v148
	v_fmac_f32_e32 v149, v160, v147
	v_fma_f32 v146, -v146, v149, v148
	v_div_fmas_f32 v146, v146, v147, v149
	v_div_fixup_f32 v142, v146, v143, v142
	v_mul_f32_e32 v143, v51, v142
	v_cvt_pk_bf16_f32 v142, v1, v2
	v_cvt_pk_bf16_f32 v143, v133, v143
	flat_store_dwordx2 v[138:139], v[142:143]
	s_waitcnt vmcnt(31)
; __device__ __forceinline__ float bf_lo(unsigned u) { return __uint_as_float(u << 16); }
; __device__ __forceinline__ float bf_hi(unsigned u) { return __uint_as_float(u & 0xffff0000u); }
; __device__ __forceinline__ float silu(float z) { return z / (1.f + __expf(-z)); }
; __device__ __forceinline__ void gemm_tile(const GemmArgs& g, bf16* shm, const int tid, const int wid, char* wsb, const float* gnext) {
;     ...
;     for (int ai = 0; ai < 2; ++ai)
; #pragma unroll
;       for (int m = 0; m < 4; ++m) {
;         const int row = ai * HALF + m * 16 + rbase;
;         bf16* Cr = C + (long)row * g.ldc + cbase; const bf16* Zr = Z + (long)row * g.ldx + cbase;
; #pragma unroll
;         for (int bj = 0; bj < 2; ++bj)
; #pragma unroll
;           for (int n = 0; n < 2; ++n) {
;             f32x4 v = acc[ai][bj][m][n];
;             u32x2 z = *reinterpret_cast<const u32x2*>(Zr + bj * HALF + n * 16);
;             float o0 = v[0] * silu(bf_lo(z[0])), o1 = v[1] * silu(bf_hi(z[0]));
;             float o2 = v[2] * silu(bf_lo(z[1])), o3 = v[3] * silu(bf_hi(z[1]));
;             u32x2 w = {cvtpk(o0, o1), cvtpk(o2, o3)};
;             *reinterpret_cast<u32x2*>(Cr + bj * HALF + n * 16) = w;
;           }
	v_mov_b32_e32 v142, v244
	v_mov_b32_e32 v143, v245
	v_lshlrev_b32_e32 v1, 16, v142
	v_mul_f32_e32 v2, 0xbfb8aa3b, v1
	v_exp_f32_e32 v2, v2
	s_nop 0
	v_add_f32_e32 v2, 1.0, v2
	v_div_scale_f32 v133, s[0:1], v2, v2, v1
	v_rcp_f32_e32 v146, v133
	s_nop 0
	v_fma_f32 v147, -v133, v146, 1.0
	v_fmac_f32_e32 v146, v147, v146
	v_div_scale_f32 v147, vcc, v1, v2, v1
	v_mul_f32_e32 v148, v147, v146
	v_fma_f32 v149, -v133, v148, v147
	v_fmac_f32_e32 v148, v149, v146
	v_fma_f32 v133, -v133, v148, v147
	v_div_fmas_f32 v133, v133, v146, v148
	v_div_fixup_f32 v1, v133, v2, v1
	v_and_b32_e32 v2, 0xffff0000, v142
	v_mul_f32_e32 v133, 0xbfb8aa3b, v2
	v_exp_f32_e32 v133, v133
	v_mul_f32_e32 v1, v40, v1
	v_add_f32_e32 v133, 1.0, v133
	v_div_scale_f32 v142, s[0:1], v133, v133, v2
	v_rcp_f32_e32 v146, v142
	s_nop 0
	v_fma_f32 v147, -v142, v146, 1.0
	v_fmac_f32_e32 v146, v147, v146
	v_div_scale_f32 v147, vcc, v2, v133, v2
	v_mul_f32_e32 v148, v147, v146
	v_fma_f32 v149, -v142, v148, v147
	v_fmac_f32_e32 v148, v149, v146
	v_fma_f32 v142, -v142, v148, v147
	v_div_fmas_f32 v142, v142, v146, v148
	v_div_fixup_f32 v2, v142, v133, v2
	v_lshlrev_b32_e32 v133, 16, v143
	v_mul_f32_e32 v142, 0xbfb8aa3b, v133
	v_exp_f32_e32 v142, v142
	v_mul_f32_e32 v2, v41, v2
	v_add_f32_e32 v142, 1.0, v142
	v_div_scale_f32 v146, s[0:1], v142, v142, v133
	v_rcp_f32_e32 v147, v146
	s_nop 0
	v_fma_f32 v148, -v146, v147, 1.0
	v_fmac_f32_e32 v147, v148, v147
	v_div_scale_f32 v148, vcc, v133, v142, v133
	v_mul_f32_e32 v149, v148, v147
	v_fma_f32 v160, -v146, v149, v148
	v_fmac_f32_e32 v149, v160, v147
	v_fma_f32 v146, -v146, v149, v148
	v_div_fmas_f32 v146, v146, v147, v149
	v_div_fixup_f32 v133, v146, v142, v133
	v_and_b32_e32 v142, 0xffff0000, v143
	v_mul_f32_e32 v143, 0xbfb8aa3b, v142
	v_exp_f32_e32 v143, v143
	v_mul_f32_e32 v133, v42, v133
	v_add_f32_e32 v143, 1.0, v143
	v_div_scale_f32 v146, s[0:1], v143, v143, v142
	v_rcp_f32_e32 v147, v146
	s_nop 0
	v_fma_f32 v148, -v146, v147, 1.0
	v_fmac_f32_e32 v147, v148, v147
	v_div_scale_f32 v148, vcc, v142, v143, v142
	v_mul_f32_e32 v149, v148, v147
	v_fma_f32 v160, -v146, v149, v148
	v_fmac_f32_e32 v149, v160, v147
	v_fma_f32 v146, -v146, v149, v148
	v_div_fmas_f32 v146, v146, v147, v149
	v_div_fixup_f32 v142, v146, v143, v142
	v_mul_f32_e32 v143, v43, v142
	v_cvt_pk_bf16_f32 v142, v1, v2
	v_cvt_pk_bf16_f32 v143, v133, v143
	flat_store_dwordx2 v[138:139], v[142:143] offset:32
	s_waitcnt vmcnt(31)
	v_mov_b32_e32 v142, v246
	v_mov_b32_e32 v143, v247
	v_lshlrev_b32_e32 v1, 16, v142
	v_mul_f32_e32 v2, 0xbfb8aa3b, v1
	v_exp_f32_e32 v2, v2
	s_nop 0
	v_add_f32_e32 v2, 1.0, v2
	v_div_scale_f32 v133, s[0:1], v2, v2, v1
	v_rcp_f32_e32 v146, v133
	s_nop 0
	v_fma_f32 v147, -v133, v146, 1.0
	v_fmac_f32_e32 v146, v147, v146
	v_div_scale_f32 v147, vcc, v1, v2, v1
	v_mul_f32_e32 v148, v147, v146
	v_fma_f32 v149, -v133, v148, v147
	v_fmac_f32_e32 v148, v149, v146
	v_fma_f32 v133, -v133, v148, v147
	v_div_fmas_f32 v133, v133, v146, v148
	v_div_fixup_f32 v1, v133, v2, v1
	v_and_b32_e32 v2, 0xffff0000, v142
	v_mul_f32_e32 v133, 0xbfb8aa3b, v2
	v_exp_f32_e32 v133, v133
	v_mul_f32_e32 v1, v44, v1
	v_add_f32_e32 v133, 1.0, v133
	v_div_scale_f32 v142, s[0:1], v133, v133, v2
	v_rcp_f32_e32 v146, v142
	s_nop 0
	v_fma_f32 v147, -v142, v146, 1.0
	v_fmac_f32_e32 v146, v147, v146
	v_div_scale_f32 v147, vcc, v2, v133, v2
	v_mul_f32_e32 v148, v147, v146
	v_fma_f32 v149, -v142, v148, v147
	v_fmac_f32_e32 v148, v149, v146
	v_fma_f32 v142, -v142, v148, v147
	v_div_fmas_f32 v142, v142, v146, v148
	v_div_fixup_f32 v2, v142, v133, v2
	v_lshlrev_b32_e32 v133, 16, v143
	v_mul_f32_e32 v142, 0xbfb8aa3b, v133
	v_exp_f32_e32 v142, v142
	v_mul_f32_e32 v2, v45, v2
	v_add_f32_e32 v142, 1.0, v142
	v_div_scale_f32 v146, s[0:1], v142, v142, v133
	v_rcp_f32_e32 v147, v146
	s_nop 0
	v_fma_f32 v148, -v146, v147, 1.0
	v_fmac_f32_e32 v147, v148, v147
	v_div_scale_f32 v148, vcc, v133, v142, v133
	v_mul_f32_e32 v149, v148, v147
	v_fma_f32 v160, -v146, v149, v148
	v_fmac_f32_e32 v149, v160, v147
	v_fma_f32 v146, -v146, v149, v148
	v_div_fmas_f32 v146, v146, v147, v149
	v_div_fixup_f32 v133, v146, v142, v133
	v_and_b32_e32 v142, 0xffff0000, v143
	v_mul_f32_e32 v143, 0xbfb8aa3b, v142
	v_exp_f32_e32 v143, v143
	v_mul_f32_e32 v133, v46, v133
	v_add_f32_e32 v143, 1.0, v143
	v_div_scale_f32 v146, s[0:1], v143, v143, v142
	v_rcp_f32_e32 v147, v146
	s_nop 0
	v_fma_f32 v148, -v146, v147, 1.0
	v_fmac_f32_e32 v147, v148, v147
	v_div_scale_f32 v148, vcc, v142, v143, v142
	v_mul_f32_e32 v149, v148, v147
	v_fma_f32 v160, -v146, v149, v148
	v_fmac_f32_e32 v149, v160, v147
	v_fma_f32 v146, -v146, v149, v148
	v_div_fmas_f32 v146, v146, v147, v149
	v_div_fixup_f32 v142, v146, v143, v142
	v_mul_f32_e32 v143, v47, v142
	v_cvt_pk_bf16_f32 v142, v1, v2
	v_cvt_pk_bf16_f32 v143, v133, v143
	flat_store_dwordx2 v[138:139], v[142:143] offset:256
	s_waitcnt vmcnt(31)
; __device__ __forceinline__ float bf_lo(unsigned u) { return __uint_as_float(u << 16); }
; __device__ __forceinline__ float bf_hi(unsigned u) { return __uint_as_float(u & 0xffff0000u); }
; __device__ __forceinline__ float silu(float z) { return z / (1.f + __expf(-z)); }
; __device__ __forceinline__ void gemm_tile(const GemmArgs& g, bf16* shm, const int tid, const int wid, char* wsb, const float* gnext) {
;     ...
;     for (int ai = 0; ai < 2; ++ai)
; #pragma unroll
;       for (int m = 0; m < 4; ++m) {
;         const int row = ai * HALF + m * 16 + rbase;
;         bf16* Cr = C + (long)row * g.ldc + cbase; const bf16* Zr = Z + (long)row * g.ldx + cbase;
; #pragma unroll
;         for (int bj = 0; bj < 2; ++bj)
; #pragma unroll
;           for (int n = 0; n < 2; ++n) {
;             f32x4 v = acc[ai][bj][m][n];
;             u32x2 z = *reinterpret_cast<const u32x2*>(Zr + bj * HALF + n * 16);
;             float o0 = v[0] * silu(bf_lo(z[0])), o1 = v[1] * silu(bf_hi(z[0]));
;             float o2 = v[2] * silu(bf_lo(z[1])), o3 = v[3] * silu(bf_hi(z[1]));
;             u32x2 w = {cvtpk(o0, o1), cvtpk(o2, o3)};
;             *reinterpret_cast<u32x2*>(Cr + bj * HALF + n * 16) = w;
;           }
	v_mov_b32_e32 v140, v248
	v_mov_b32_e32 v141, v249
	v_lshlrev_b32_e32 v1, 16, v140
	v_mul_f32_e32 v2, 0xbfb8aa3b, v1
	v_exp_f32_e32 v2, v2
	s_nop 0
	v_add_f32_e32 v2, 1.0, v2
	v_div_scale_f32 v133, s[0:1], v2, v2, v1
	v_rcp_f32_e32 v142, v133
	s_nop 0
	v_fma_f32 v143, -v133, v142, 1.0
	v_fmac_f32_e32 v142, v143, v142
	v_div_scale_f32 v143, vcc, v1, v2, v1
	v_mul_f32_e32 v146, v143, v142
	v_fma_f32 v147, -v133, v146, v143
	v_fmac_f32_e32 v146, v147, v142
	v_fma_f32 v133, -v133, v146, v143
	v_div_fmas_f32 v133, v133, v142, v146
	v_div_fixup_f32 v1, v133, v2, v1
	v_and_b32_e32 v2, 0xffff0000, v140
	v_mul_f32_e32 v133, 0xbfb8aa3b, v2
	v_exp_f32_e32 v133, v133
	v_mul_f32_e32 v1, v36, v1
	v_add_f32_e32 v133, 1.0, v133
	v_div_scale_f32 v140, s[0:1], v133, v133, v2
	v_rcp_f32_e32 v142, v140
	s_nop 0
	v_fma_f32 v143, -v140, v142, 1.0
	v_fmac_f32_e32 v142, v143, v142
	v_div_scale_f32 v143, vcc, v2, v133, v2
	v_mul_f32_e32 v146, v143, v142
	v_fma_f32 v147, -v140, v146, v143
	v_fmac_f32_e32 v146, v147, v142
	v_fma_f32 v140, -v140, v146, v143
	v_div_fmas_f32 v140, v140, v142, v146
	v_div_fixup_f32 v2, v140, v133, v2
	v_lshlrev_b32_e32 v133, 16, v141
	v_mul_f32_e32 v140, 0xbfb8aa3b, v133
	v_exp_f32_e32 v140, v140
	v_mul_f32_e32 v2, v37, v2
	v_add_f32_e32 v140, 1.0, v140
	v_div_scale_f32 v142, s[0:1], v140, v140, v133
	v_rcp_f32_e32 v143, v142
	s_nop 0
	v_fma_f32 v146, -v142, v143, 1.0
	v_fmac_f32_e32 v143, v146, v143
	v_div_scale_f32 v146, vcc, v133, v140, v133
	v_mul_f32_e32 v147, v146, v143
	v_fma_f32 v148, -v142, v147, v146
	v_fmac_f32_e32 v147, v148, v143
	v_fma_f32 v142, -v142, v147, v146
	v_div_fmas_f32 v142, v142, v143, v147
	v_div_fixup_f32 v133, v142, v140, v133
	v_and_b32_e32 v140, 0xffff0000, v141
	v_mul_f32_e32 v141, 0xbfb8aa3b, v140
	v_exp_f32_e32 v141, v141
	v_mul_f32_e32 v133, v38, v133
	v_add_f32_e32 v141, 1.0, v141
	v_div_scale_f32 v142, s[0:1], v141, v141, v140
	v_rcp_f32_e32 v143, v142
	s_nop 0
	v_fma_f32 v146, -v142, v143, 1.0
	v_fmac_f32_e32 v143, v146, v143
	v_div_scale_f32 v146, vcc, v140, v141, v140
	v_mul_f32_e32 v147, v146, v143
	v_fma_f32 v148, -v142, v147, v146
	v_fmac_f32_e32 v147, v148, v143
	v_fma_f32 v142, -v142, v147, v146
	v_div_fmas_f32 v142, v142, v143, v147
	v_div_fixup_f32 v140, v142, v141, v140
	v_mul_f32_e32 v141, v39, v140
	v_cvt_pk_bf16_f32 v140, v1, v2
	v_cvt_pk_bf16_f32 v141, v133, v141
	v_add_u32_e32 v1, 0xa0, v0
	flat_store_dwordx2 v[138:139], v[140:141] offset:288
	v_mad_i64_i32 v[140:141], s[0:1], v1, s67, 0
	v_lshl_add_u64 v[140:141], v[140:141], 1, v[134:135]
	s_waitcnt vmcnt(31)
	v_mov_b32_e32 v142, v250
	v_mov_b32_e32 v143, v251
	v_mad_i64_i32 v[138:139], s[0:1], v1, s66, 0
	v_lshl_add_u64 v[138:139], v[138:139], 1, v[136:137]
	v_lshlrev_b32_e32 v1, 16, v142
	v_mul_f32_e32 v2, 0xbfb8aa3b, v1
	v_exp_f32_e32 v2, v2
	s_nop 0
	v_add_f32_e32 v2, 1.0, v2
	v_div_scale_f32 v133, s[0:1], v2, v2, v1
	v_rcp_f32_e32 v146, v133
	s_nop 0
	v_fma_f32 v147, -v133, v146, 1.0
	v_fmac_f32_e32 v146, v147, v146
	v_div_scale_f32 v147, vcc, v1, v2, v1
	v_mul_f32_e32 v148, v147, v146
	v_fma_f32 v149, -v133, v148, v147
	v_fmac_f32_e32 v148, v149, v146
	v_fma_f32 v133, -v133, v148, v147
	v_div_fmas_f32 v133, v133, v146, v148
	v_div_fixup_f32 v1, v133, v2, v1
	v_and_b32_e32 v2, 0xffff0000, v142
	v_mul_f32_e32 v133, 0xbfb8aa3b, v2
	v_exp_f32_e32 v133, v133
	v_mul_f32_e32 v1, v32, v1
	v_add_f32_e32 v133, 1.0, v133
	v_div_scale_f32 v142, s[0:1], v133, v133, v2
	v_rcp_f32_e32 v146, v142
	s_nop 0
	v_fma_f32 v147, -v142, v146, 1.0
	v_fmac_f32_e32 v146, v147, v146
	v_div_scale_f32 v147, vcc, v2, v133, v2
	v_mul_f32_e32 v148, v147, v146
	v_fma_f32 v149, -v142, v148, v147
	v_fmac_f32_e32 v148, v149, v146
	v_fma_f32 v142, -v142, v148, v147
	v_div_fmas_f32 v142, v142, v146, v148
	v_div_fixup_f32 v2, v142, v133, v2
	v_lshlrev_b32_e32 v133, 16, v143
	v_mul_f32_e32 v142, 0xbfb8aa3b, v133
	v_exp_f32_e32 v142, v142
	v_mul_f32_e32 v2, v33, v2
	v_add_f32_e32 v142, 1.0, v142
	v_div_scale_f32 v146, s[0:1], v142, v142, v133
	v_rcp_f32_e32 v147, v146
	s_nop 0
	v_fma_f32 v148, -v146, v147, 1.0
	v_fmac_f32_e32 v147, v148, v147
	v_div_scale_f32 v148, vcc, v133, v142, v133
	v_mul_f32_e32 v149, v148, v147
	v_fma_f32 v160, -v146, v149, v148
	v_fmac_f32_e32 v149, v160, v147
	v_fma_f32 v146, -v146, v149, v148
	v_div_fmas_f32 v146, v146, v147, v149
	v_div_fixup_f32 v133, v146, v142, v133
	v_and_b32_e32 v142, 0xffff0000, v143
	v_mul_f32_e32 v143, 0xbfb8aa3b, v142
	v_exp_f32_e32 v143, v143
	v_mul_f32_e32 v133, v34, v133
	v_add_f32_e32 v143, 1.0, v143
	v_div_scale_f32 v146, s[0:1], v143, v143, v142
	v_rcp_f32_e32 v147, v146
	s_nop 0
	v_fma_f32 v148, -v146, v147, 1.0
	v_fmac_f32_e32 v147, v148, v147
	v_div_scale_f32 v148, vcc, v142, v143, v142
	v_mul_f32_e32 v149, v148, v147
	v_fma_f32 v160, -v146, v149, v148
	v_fmac_f32_e32 v149, v160, v147
	v_fma_f32 v146, -v146, v149, v148
	v_div_fmas_f32 v146, v146, v147, v149
	v_div_fixup_f32 v142, v146, v143, v142
	v_mul_f32_e32 v143, v35, v142
	v_cvt_pk_bf16_f32 v142, v1, v2
	v_cvt_pk_bf16_f32 v143, v133, v143
	flat_store_dwordx2 v[138:139], v[142:143]
	s_waitcnt vmcnt(31)
; __device__ __forceinline__ float bf_lo(unsigned u) { return __uint_as_float(u << 16); }
; __device__ __forceinline__ float bf_hi(unsigned u) { return __uint_as_float(u & 0xffff0000u); }
; __device__ __forceinline__ float silu(float z) { return z / (1.f + __expf(-z)); }
; __device__ __forceinline__ void gemm_tile(const GemmArgs& g, bf16* shm, const int tid, const int wid, char* wsb, const float* gnext) {
;     ...
;     for (int ai = 0; ai < 2; ++ai)
; #pragma unroll
;       for (int m = 0; m < 4; ++m) {
;         const int row = ai * HALF + m * 16 + rbase;
;         bf16* Cr = C + (long)row * g.ldc + cbase; const bf16* Zr = Z + (long)row * g.ldx + cbase;
; #pragma unroll
;         for (int bj = 0; bj < 2; ++bj)
; #pragma unroll
;           for (int n = 0; n < 2; ++n) {
;             f32x4 v = acc[ai][bj][m][n];
;             u32x2 z = *reinterpret_cast<const u32x2*>(Zr + bj * HALF + n * 16);
;             float o0 = v[0] * silu(bf_lo(z[0])), o1 = v[1] * silu(bf_hi(z[0]));
;             float o2 = v[2] * silu(bf_lo(z[1])), o3 = v[3] * silu(bf_hi(z[1]));
;             u32x2 w = {cvtpk(o0, o1), cvtpk(o2, o3)};
;             *reinterpret_cast<u32x2*>(Cr + bj * HALF + n * 16) = w;
;           }
	v_mov_b32_e32 v142, v252
	v_mov_b32_e32 v143, v253
	v_lshlrev_b32_e32 v1, 16, v142
	v_mul_f32_e32 v2, 0xbfb8aa3b, v1
	v_exp_f32_e32 v2, v2
	s_nop 0
	v_add_f32_e32 v2, 1.0, v2
	v_div_scale_f32 v133, s[0:1], v2, v2, v1
	v_rcp_f32_e32 v146, v133
	s_nop 0
	v_fma_f32 v147, -v133, v146, 1.0
	v_fmac_f32_e32 v146, v147, v146
	v_div_scale_f32 v147, vcc, v1, v2, v1
	v_mul_f32_e32 v148, v147, v146
	v_fma_f32 v149, -v133, v148, v147
	v_fmac_f32_e32 v148, v149, v146
	v_fma_f32 v133, -v133, v148, v147
	v_div_fmas_f32 v133, v133, v146, v148
	v_div_fixup_f32 v1, v133, v2, v1
	v_and_b32_e32 v2, 0xffff0000, v142
	v_mul_f32_e32 v133, 0xbfb8aa3b, v2
	v_exp_f32_e32 v133, v133
	v_mul_f32_e32 v1, v24, v1
	v_add_f32_e32 v133, 1.0, v133
	v_div_scale_f32 v142, s[0:1], v133, v133, v2
	v_rcp_f32_e32 v146, v142
	s_nop 0
	v_fma_f32 v147, -v142, v146, 1.0
	v_fmac_f32_e32 v146, v147, v146
	v_div_scale_f32 v147, vcc, v2, v133, v2
	v_mul_f32_e32 v148, v147, v146
	v_fma_f32 v149, -v142, v148, v147
	v_fmac_f32_e32 v148, v149, v146
	v_fma_f32 v142, -v142, v148, v147
	v_div_fmas_f32 v142, v142, v146, v148
	v_div_fixup_f32 v2, v142, v133, v2
	v_lshlrev_b32_e32 v133, 16, v143
	v_mul_f32_e32 v142, 0xbfb8aa3b, v133
	v_exp_f32_e32 v142, v142
	v_mul_f32_e32 v2, v25, v2
	v_add_f32_e32 v142, 1.0, v142
	v_div_scale_f32 v146, s[0:1], v142, v142, v133
	v_rcp_f32_e32 v147, v146
	s_nop 0
	v_fma_f32 v148, -v146, v147, 1.0
	v_fmac_f32_e32 v147, v148, v147
	v_div_scale_f32 v148, vcc, v133, v142, v133
	v_mul_f32_e32 v149, v148, v147
	v_fma_f32 v160, -v146, v149, v148
	v_fmac_f32_e32 v149, v160, v147
	v_fma_f32 v146, -v146, v149, v148
	v_div_fmas_f32 v146, v146, v147, v149
	v_div_fixup_f32 v133, v146, v142, v133
	v_and_b32_e32 v142, 0xffff0000, v143
	v_mul_f32_e32 v143, 0xbfb8aa3b, v142
	v_exp_f32_e32 v143, v143
	v_mul_f32_e32 v133, v26, v133
	v_add_f32_e32 v143, 1.0, v143
	v_div_scale_f32 v146, s[0:1], v143, v143, v142
	v_rcp_f32_e32 v147, v146
	s_nop 0
	v_fma_f32 v148, -v146, v147, 1.0
	v_fmac_f32_e32 v147, v148, v147
	v_div_scale_f32 v148, vcc, v142, v143, v142
	v_mul_f32_e32 v149, v148, v147
	v_fma_f32 v160, -v146, v149, v148
	v_fmac_f32_e32 v149, v160, v147
	v_fma_f32 v146, -v146, v149, v148
	v_div_fmas_f32 v146, v146, v147, v149
	v_div_fixup_f32 v142, v146, v143, v142
	v_mul_f32_e32 v143, v27, v142
	v_cvt_pk_bf16_f32 v142, v1, v2
	v_cvt_pk_bf16_f32 v143, v133, v143
	flat_store_dwordx2 v[138:139], v[142:143] offset:32
	s_waitcnt vmcnt(31)
	v_mov_b32_e32 v142, v164
	v_mov_b32_e32 v143, v165
	v_lshlrev_b32_e32 v1, 16, v142
	v_mul_f32_e32 v2, 0xbfb8aa3b, v1
	v_exp_f32_e32 v2, v2
	s_nop 0
	v_add_f32_e32 v2, 1.0, v2
	v_div_scale_f32 v133, s[0:1], v2, v2, v1
	v_rcp_f32_e32 v146, v133
	s_nop 0
	v_fma_f32 v147, -v133, v146, 1.0
	v_fmac_f32_e32 v146, v147, v146
	v_div_scale_f32 v147, vcc, v1, v2, v1
	v_mul_f32_e32 v148, v147, v146
	v_fma_f32 v149, -v133, v148, v147
	v_fmac_f32_e32 v148, v149, v146
	v_fma_f32 v133, -v133, v148, v147
	v_div_fmas_f32 v133, v133, v146, v148
	v_div_fixup_f32 v1, v133, v2, v1
	v_and_b32_e32 v2, 0xffff0000, v142
	v_mul_f32_e32 v133, 0xbfb8aa3b, v2
	v_exp_f32_e32 v133, v133
	v_mul_f32_e32 v1, v28, v1
	v_add_f32_e32 v133, 1.0, v133
	v_div_scale_f32 v142, s[0:1], v133, v133, v2
	v_rcp_f32_e32 v146, v142
	s_nop 0
	v_fma_f32 v147, -v142, v146, 1.0
	v_fmac_f32_e32 v146, v147, v146
	v_div_scale_f32 v147, vcc, v2, v133, v2
	v_mul_f32_e32 v148, v147, v146
	v_fma_f32 v149, -v142, v148, v147
	v_fmac_f32_e32 v148, v149, v146
	v_fma_f32 v142, -v142, v148, v147
	v_div_fmas_f32 v142, v142, v146, v148
	v_div_fixup_f32 v2, v142, v133, v2
	v_lshlrev_b32_e32 v133, 16, v143
	v_mul_f32_e32 v142, 0xbfb8aa3b, v133
	v_exp_f32_e32 v142, v142
	v_mul_f32_e32 v2, v29, v2
	v_add_f32_e32 v142, 1.0, v142
	v_div_scale_f32 v146, s[0:1], v142, v142, v133
	v_rcp_f32_e32 v147, v146
	s_nop 0
	v_fma_f32 v148, -v146, v147, 1.0
	v_fmac_f32_e32 v147, v148, v147
	v_div_scale_f32 v148, vcc, v133, v142, v133
	v_mul_f32_e32 v149, v148, v147
	v_fma_f32 v160, -v146, v149, v148
	v_fmac_f32_e32 v149, v160, v147
	v_fma_f32 v146, -v146, v149, v148
	v_div_fmas_f32 v146, v146, v147, v149
	v_div_fixup_f32 v133, v146, v142, v133
	v_and_b32_e32 v142, 0xffff0000, v143
	v_mul_f32_e32 v143, 0xbfb8aa3b, v142
	v_exp_f32_e32 v143, v143
	v_mul_f32_e32 v133, v30, v133
	v_add_f32_e32 v143, 1.0, v143
	v_div_scale_f32 v146, s[0:1], v143, v143, v142
	v_rcp_f32_e32 v147, v146
	s_nop 0
	v_fma_f32 v148, -v146, v147, 1.0
	v_fmac_f32_e32 v147, v148, v147
	v_div_scale_f32 v148, vcc, v142, v143, v142
	v_mul_f32_e32 v149, v148, v147
	v_fma_f32 v160, -v146, v149, v148
	v_fmac_f32_e32 v149, v160, v147
	v_fma_f32 v146, -v146, v149, v148
	v_div_fmas_f32 v146, v146, v147, v149
	v_div_fixup_f32 v142, v146, v143, v142
	v_mul_f32_e32 v143, v31, v142
	v_cvt_pk_bf16_f32 v142, v1, v2
	v_cvt_pk_bf16_f32 v143, v133, v143
	flat_store_dwordx2 v[138:139], v[142:143] offset:256
	s_waitcnt vmcnt(31)
; __device__ __forceinline__ float bf_lo(unsigned u) { return __uint_as_float(u << 16); }
; __device__ __forceinline__ float bf_hi(unsigned u) { return __uint_as_float(u & 0xffff0000u); }
; __device__ __forceinline__ float silu(float z) { return z / (1.f + __expf(-z)); }
; __device__ __forceinline__ void gemm_tile(const GemmArgs& g, bf16* shm, const int tid, const int wid, char* wsb, const float* gnext) {
;     ...
;     for (int ai = 0; ai < 2; ++ai)
; #pragma unroll
;       for (int m = 0; m < 4; ++m) {
;         const int row = ai * HALF + m * 16 + rbase;
;         bf16* Cr = C + (long)row * g.ldc + cbase; const bf16* Zr = Z + (long)row * g.ldx + cbase;
; #pragma unroll
;         for (int bj = 0; bj < 2; ++bj)
; #pragma unroll
;           for (int n = 0; n < 2; ++n) {
;             f32x4 v = acc[ai][bj][m][n];
;             u32x2 z = *reinterpret_cast<const u32x2*>(Zr + bj * HALF + n * 16);
;             float o0 = v[0] * silu(bf_lo(z[0])), o1 = v[1] * silu(bf_hi(z[0]));
;             float o2 = v[2] * silu(bf_lo(z[1])), o3 = v[3] * silu(bf_hi(z[1]));
;             u32x2 w = {cvtpk(o0, o1), cvtpk(o2, o3)};
;             *reinterpret_cast<u32x2*>(Cr + bj * HALF + n * 16) = w;
;           }
	v_mov_b32_e32 v140, v166
	v_mov_b32_e32 v141, v167
	v_lshlrev_b32_e32 v1, 16, v140
	v_mul_f32_e32 v2, 0xbfb8aa3b, v1
	v_exp_f32_e32 v2, v2
	s_nop 0
	v_add_f32_e32 v2, 1.0, v2
	v_div_scale_f32 v133, s[0:1], v2, v2, v1
	v_rcp_f32_e32 v142, v133
	s_nop 0
	v_fma_f32 v143, -v133, v142, 1.0
	v_fmac_f32_e32 v142, v143, v142
	v_div_scale_f32 v143, vcc, v1, v2, v1
	v_mul_f32_e32 v146, v143, v142
	v_fma_f32 v147, -v133, v146, v143
	v_fmac_f32_e32 v146, v147, v142
	v_fma_f32 v133, -v133, v146, v143
	v_div_fmas_f32 v133, v133, v142, v146
	v_div_fixup_f32 v1, v133, v2, v1
	v_and_b32_e32 v2, 0xffff0000, v140
	v_mul_f32_e32 v133, 0xbfb8aa3b, v2
	v_exp_f32_e32 v133, v133
	v_mul_f32_e32 v1, v20, v1
	v_add_f32_e32 v133, 1.0, v133
	v_div_scale_f32 v140, s[0:1], v133, v133, v2
	v_rcp_f32_e32 v142, v140
	s_nop 0
	v_fma_f32 v143, -v140, v142, 1.0
	v_fmac_f32_e32 v142, v143, v142
	v_div_scale_f32 v143, vcc, v2, v133, v2
	v_mul_f32_e32 v146, v143, v142
	v_fma_f32 v147, -v140, v146, v143
	v_fmac_f32_e32 v146, v147, v142
	v_fma_f32 v140, -v140, v146, v143
	v_div_fmas_f32 v140, v140, v142, v146
	v_div_fixup_f32 v2, v140, v133, v2
	v_lshlrev_b32_e32 v133, 16, v141
	v_mul_f32_e32 v140, 0xbfb8aa3b, v133
	v_exp_f32_e32 v140, v140
	v_mul_f32_e32 v2, v21, v2
	v_add_f32_e32 v140, 1.0, v140
	v_div_scale_f32 v142, s[0:1], v140, v140, v133
	v_rcp_f32_e32 v143, v142
	s_nop 0
	v_fma_f32 v146, -v142, v143, 1.0
	v_fmac_f32_e32 v143, v146, v143
	v_div_scale_f32 v146, vcc, v133, v140, v133
	v_mul_f32_e32 v147, v146, v143
	v_fma_f32 v148, -v142, v147, v146
	v_fmac_f32_e32 v147, v148, v143
	v_fma_f32 v142, -v142, v147, v146
	v_div_fmas_f32 v142, v142, v143, v147
	v_div_fixup_f32 v133, v142, v140, v133
	v_and_b32_e32 v140, 0xffff0000, v141
	v_mul_f32_e32 v141, 0xbfb8aa3b, v140
	v_exp_f32_e32 v141, v141
	v_mul_f32_e32 v133, v22, v133
	v_add_f32_e32 v141, 1.0, v141
	v_div_scale_f32 v142, s[0:1], v141, v141, v140
	v_rcp_f32_e32 v143, v142
	s_nop 0
	v_fma_f32 v146, -v142, v143, 1.0
	v_fmac_f32_e32 v143, v146, v143
	v_div_scale_f32 v146, vcc, v140, v141, v140
	v_mul_f32_e32 v147, v146, v143
	v_fma_f32 v148, -v142, v147, v146
	v_fmac_f32_e32 v147, v148, v143
	v_fma_f32 v142, -v142, v147, v146
	v_div_fmas_f32 v142, v142, v143, v147
	v_div_fixup_f32 v140, v142, v141, v140
	v_mul_f32_e32 v141, v23, v140
	v_cvt_pk_bf16_f32 v140, v1, v2
	v_add_u32_e32 v1, 0xb0, v0
	v_cvt_pk_bf16_f32 v141, v133, v141
	flat_store_dwordx2 v[138:139], v[140:141] offset:288
	v_mad_i64_i32 v[138:139], s[0:1], v1, s66, 0
	v_lshl_add_u64 v[136:137], v[138:139], 1, v[136:137]
	v_mad_i64_i32 v[138:139], s[0:1], v1, s67, 0
	v_lshl_add_u64 v[134:135], v[138:139], 1, v[134:135]
	s_waitcnt vmcnt(31)
	v_mov_b32_e32 v138, v168
	v_mov_b32_e32 v139, v169
	v_lshlrev_b32_e32 v1, 16, v138
	v_mul_f32_e32 v2, 0xbfb8aa3b, v1
	v_exp_f32_e32 v2, v2
	s_nop 0
	v_add_f32_e32 v2, 1.0, v2
	v_div_scale_f32 v133, s[0:1], v2, v2, v1
	v_rcp_f32_e32 v140, v133
	s_nop 0
	v_fma_f32 v141, -v133, v140, 1.0
	v_fmac_f32_e32 v140, v141, v140
	v_div_scale_f32 v141, vcc, v1, v2, v1
	v_mul_f32_e32 v142, v141, v140
	v_fma_f32 v143, -v133, v142, v141
	v_fmac_f32_e32 v142, v143, v140
	v_fma_f32 v133, -v133, v142, v141
	v_div_fmas_f32 v133, v133, v140, v142
	v_div_fixup_f32 v1, v133, v2, v1
	v_and_b32_e32 v2, 0xffff0000, v138
	v_mul_f32_e32 v133, 0xbfb8aa3b, v2
	v_exp_f32_e32 v133, v133
	v_mul_f32_e32 v1, v16, v1
	v_add_f32_e32 v133, 1.0, v133
	v_div_scale_f32 v138, s[0:1], v133, v133, v2
	v_rcp_f32_e32 v140, v138
	s_nop 0
	v_fma_f32 v141, -v138, v140, 1.0
	v_fmac_f32_e32 v140, v141, v140
	v_div_scale_f32 v141, vcc, v2, v133, v2
	v_mul_f32_e32 v142, v141, v140
	v_fma_f32 v143, -v138, v142, v141
	v_fmac_f32_e32 v142, v143, v140
	v_fma_f32 v138, -v138, v142, v141
	v_div_fmas_f32 v138, v138, v140, v142
	v_div_fixup_f32 v2, v138, v133, v2
	v_lshlrev_b32_e32 v133, 16, v139
	v_mul_f32_e32 v138, 0xbfb8aa3b, v133
	v_exp_f32_e32 v138, v138
	v_mul_f32_e32 v2, v17, v2
	v_add_f32_e32 v138, 1.0, v138
	v_div_scale_f32 v140, s[0:1], v138, v138, v133
	v_rcp_f32_e32 v141, v140
	s_nop 0
	v_fma_f32 v142, -v140, v141, 1.0
	v_fmac_f32_e32 v141, v142, v141
	v_div_scale_f32 v142, vcc, v133, v138, v133
	v_mul_f32_e32 v143, v142, v141
	v_fma_f32 v146, -v140, v143, v142
	v_fmac_f32_e32 v143, v146, v141
	v_fma_f32 v140, -v140, v143, v142
	v_div_fmas_f32 v140, v140, v141, v143
	v_div_fixup_f32 v133, v140, v138, v133
	v_and_b32_e32 v138, 0xffff0000, v139
	v_mul_f32_e32 v139, 0xbfb8aa3b, v138
	v_exp_f32_e32 v139, v139
	v_mul_f32_e32 v133, v18, v133
	v_add_f32_e32 v139, 1.0, v139
	v_div_scale_f32 v140, s[0:1], v139, v139, v138
	v_rcp_f32_e32 v141, v140
	s_nop 0
	v_fma_f32 v142, -v140, v141, 1.0
	v_fmac_f32_e32 v141, v142, v141
	v_div_scale_f32 v142, vcc, v138, v139, v138
	v_mul_f32_e32 v143, v142, v141
	v_fma_f32 v146, -v140, v143, v142
	v_fmac_f32_e32 v143, v146, v141
	v_fma_f32 v140, -v140, v143, v142
	v_div_fmas_f32 v140, v140, v141, v143
	v_div_fixup_f32 v138, v140, v139, v138
	v_mul_f32_e32 v139, v19, v138
	v_cvt_pk_bf16_f32 v138, v1, v2
	v_cvt_pk_bf16_f32 v139, v133, v139
	flat_store_dwordx2 v[136:137], v[138:139]
	s_waitcnt vmcnt(31)
; __device__ __forceinline__ float bf_lo(unsigned u) { return __uint_as_float(u << 16); }
; __device__ __forceinline__ float bf_hi(unsigned u) { return __uint_as_float(u & 0xffff0000u); }
; __device__ __forceinline__ float silu(float z) { return z / (1.f + __expf(-z)); }
; __device__ __forceinline__ void gemm_tile(const GemmArgs& g, bf16* shm, const int tid, const int wid, char* wsb, const float* gnext) {
;     ...
;     for (int ai = 0; ai < 2; ++ai)
; #pragma unroll
;       for (int m = 0; m < 4; ++m) {
;         const int row = ai * HALF + m * 16 + rbase;
;         bf16* Cr = C + (long)row * g.ldc + cbase; const bf16* Zr = Z + (long)row * g.ldx + cbase;
; #pragma unroll
;         for (int bj = 0; bj < 2; ++bj)
; #pragma unroll
;           for (int n = 0; n < 2; ++n) {
;             f32x4 v = acc[ai][bj][m][n];
;             u32x2 z = *reinterpret_cast<const u32x2*>(Zr + bj * HALF + n * 16);
;             float o0 = v[0] * silu(bf_lo(z[0])), o1 = v[1] * silu(bf_hi(z[0]));
;             float o2 = v[2] * silu(bf_lo(z[1])), o3 = v[3] * silu(bf_hi(z[1]));
;             u32x2 w = {cvtpk(o0, o1), cvtpk(o2, o3)};
;             *reinterpret_cast<u32x2*>(Cr + bj * HALF + n * 16) = w;
;           }
	v_mov_b32_e32 v138, v170
	v_mov_b32_e32 v139, v171
	v_lshlrev_b32_e32 v1, 16, v138
	v_mul_f32_e32 v2, 0xbfb8aa3b, v1
	v_exp_f32_e32 v2, v2
	s_nop 0
	v_add_f32_e32 v2, 1.0, v2
	v_div_scale_f32 v133, s[0:1], v2, v2, v1
	v_rcp_f32_e32 v140, v133
	s_nop 0
	v_fma_f32 v141, -v133, v140, 1.0
	v_fmac_f32_e32 v140, v141, v140
	v_div_scale_f32 v141, vcc, v1, v2, v1
	v_mul_f32_e32 v142, v141, v140
	v_fma_f32 v143, -v133, v142, v141
	v_fmac_f32_e32 v142, v143, v140
	v_fma_f32 v133, -v133, v142, v141
	v_div_fmas_f32 v133, v133, v140, v142
	v_div_fixup_f32 v1, v133, v2, v1
	v_and_b32_e32 v2, 0xffff0000, v138
	v_mul_f32_e32 v133, 0xbfb8aa3b, v2
	v_exp_f32_e32 v133, v133
	v_mul_f32_e32 v1, v8, v1
	v_add_f32_e32 v133, 1.0, v133
	v_div_scale_f32 v138, s[0:1], v133, v133, v2
	v_rcp_f32_e32 v140, v138
	s_nop 0
	v_fma_f32 v141, -v138, v140, 1.0
	v_fmac_f32_e32 v140, v141, v140
	v_div_scale_f32 v141, vcc, v2, v133, v2
	v_mul_f32_e32 v142, v141, v140
	v_fma_f32 v143, -v138, v142, v141
	v_fmac_f32_e32 v142, v143, v140
	v_fma_f32 v138, -v138, v142, v141
	v_div_fmas_f32 v138, v138, v140, v142
	v_div_fixup_f32 v2, v138, v133, v2
	v_lshlrev_b32_e32 v133, 16, v139
	v_mul_f32_e32 v138, 0xbfb8aa3b, v133
	v_exp_f32_e32 v138, v138
	v_mul_f32_e32 v2, v9, v2
	v_add_f32_e32 v138, 1.0, v138
	v_div_scale_f32 v140, s[0:1], v138, v138, v133
	v_rcp_f32_e32 v141, v140
	s_nop 0
	v_fma_f32 v142, -v140, v141, 1.0
	v_fmac_f32_e32 v141, v142, v141
	v_div_scale_f32 v142, vcc, v133, v138, v133
	v_mul_f32_e32 v143, v142, v141
	v_fma_f32 v146, -v140, v143, v142
	v_fmac_f32_e32 v143, v146, v141
	v_fma_f32 v140, -v140, v143, v142
	v_div_fmas_f32 v140, v140, v141, v143
	v_div_fixup_f32 v133, v140, v138, v133
	v_and_b32_e32 v138, 0xffff0000, v139
	v_mul_f32_e32 v139, 0xbfb8aa3b, v138
	v_exp_f32_e32 v139, v139
	v_mul_f32_e32 v133, v10, v133
	v_add_f32_e32 v139, 1.0, v139
	v_div_scale_f32 v140, s[0:1], v139, v139, v138
	v_rcp_f32_e32 v141, v140
	s_nop 0
	v_fma_f32 v142, -v140, v141, 1.0
	v_fmac_f32_e32 v141, v142, v141
	v_div_scale_f32 v142, vcc, v138, v139, v138
	v_mul_f32_e32 v143, v142, v141
	v_fma_f32 v146, -v140, v143, v142
	v_fmac_f32_e32 v143, v146, v141
	v_fma_f32 v140, -v140, v143, v142
	v_div_fmas_f32 v140, v140, v141, v143
	v_div_fixup_f32 v138, v140, v139, v138
	v_mul_f32_e32 v139, v11, v138
	v_cvt_pk_bf16_f32 v138, v1, v2
	v_cvt_pk_bf16_f32 v139, v133, v139
	flat_store_dwordx2 v[136:137], v[138:139] offset:32
	s_waitcnt vmcnt(31)
	v_mov_b32_e32 v138, v172
	v_mov_b32_e32 v139, v173
	v_lshlrev_b32_e32 v1, 16, v138
	v_mul_f32_e32 v2, 0xbfb8aa3b, v1
	v_exp_f32_e32 v2, v2
	s_nop 0
	v_add_f32_e32 v2, 1.0, v2
	v_div_scale_f32 v133, s[0:1], v2, v2, v1
	v_rcp_f32_e32 v140, v133
	s_nop 0
	v_fma_f32 v141, -v133, v140, 1.0
	v_fmac_f32_e32 v140, v141, v140
	v_div_scale_f32 v141, vcc, v1, v2, v1
	v_mul_f32_e32 v142, v141, v140
	v_fma_f32 v143, -v133, v142, v141
	v_fmac_f32_e32 v142, v143, v140
	v_fma_f32 v133, -v133, v142, v141
	v_div_fmas_f32 v133, v133, v140, v142
	v_div_fixup_f32 v1, v133, v2, v1
	v_and_b32_e32 v2, 0xffff0000, v138
	v_mul_f32_e32 v133, 0xbfb8aa3b, v2
	v_exp_f32_e32 v133, v133
	v_mul_f32_e32 v1, v12, v1
	v_add_f32_e32 v133, 1.0, v133
	v_div_scale_f32 v138, s[0:1], v133, v133, v2
	v_rcp_f32_e32 v140, v138
	s_nop 0
	v_fma_f32 v141, -v138, v140, 1.0
	v_fmac_f32_e32 v140, v141, v140
	v_div_scale_f32 v141, vcc, v2, v133, v2
	v_mul_f32_e32 v142, v141, v140
	v_fma_f32 v143, -v138, v142, v141
	v_fmac_f32_e32 v142, v143, v140
	v_fma_f32 v138, -v138, v142, v141
	v_div_fmas_f32 v138, v138, v140, v142
	v_div_fixup_f32 v2, v138, v133, v2
	v_lshlrev_b32_e32 v133, 16, v139
	v_mul_f32_e32 v138, 0xbfb8aa3b, v133
	v_exp_f32_e32 v138, v138
	v_mul_f32_e32 v2, v13, v2
	v_add_f32_e32 v138, 1.0, v138
	v_div_scale_f32 v140, s[0:1], v138, v138, v133
	v_rcp_f32_e32 v141, v140
	s_nop 0
	v_fma_f32 v142, -v140, v141, 1.0
	v_fmac_f32_e32 v141, v142, v141
	v_div_scale_f32 v142, vcc, v133, v138, v133
	v_mul_f32_e32 v143, v142, v141
	v_fma_f32 v146, -v140, v143, v142
	v_fmac_f32_e32 v143, v146, v141
	v_fma_f32 v140, -v140, v143, v142
	v_div_fmas_f32 v140, v140, v141, v143
	v_div_fixup_f32 v133, v140, v138, v133
	v_and_b32_e32 v138, 0xffff0000, v139
	v_mul_f32_e32 v139, 0xbfb8aa3b, v138
	v_exp_f32_e32 v139, v139
	v_mul_f32_e32 v133, v14, v133
	v_add_f32_e32 v139, 1.0, v139
	v_div_scale_f32 v140, s[0:1], v139, v139, v138
	v_rcp_f32_e32 v141, v140
	s_nop 0
	v_fma_f32 v142, -v140, v141, 1.0
	v_fmac_f32_e32 v141, v142, v141
	v_div_scale_f32 v142, vcc, v138, v139, v138
	v_mul_f32_e32 v143, v142, v141
	v_fma_f32 v146, -v140, v143, v142
	v_fmac_f32_e32 v143, v146, v141
	v_fma_f32 v140, -v140, v143, v142
	v_div_fmas_f32 v140, v140, v141, v143
	v_div_fixup_f32 v138, v140, v139, v138
	v_mul_f32_e32 v139, v15, v138
	v_cvt_pk_bf16_f32 v138, v1, v2
	v_cvt_pk_bf16_f32 v139, v133, v139
	flat_store_dwordx2 v[136:137], v[138:139] offset:256
	s_waitcnt vmcnt(31)
; __device__ __forceinline__ float bf_lo(unsigned u) { return __uint_as_float(u << 16); }
; __device__ __forceinline__ float bf_hi(unsigned u) { return __uint_as_float(u & 0xffff0000u); }
; __device__ __forceinline__ float silu(float z) { return z / (1.f + __expf(-z)); }
; __device__ __forceinline__ void gemm_tile(const GemmArgs& g, bf16* shm, const int tid, const int wid, char* wsb, const float* gnext) {
;     ...
;     for (int ai = 0; ai < 2; ++ai)
; #pragma unroll
;       for (int m = 0; m < 4; ++m) {
;         const int row = ai * HALF + m * 16 + rbase;
;         bf16* Cr = C + (long)row * g.ldc + cbase; const bf16* Zr = Z + (long)row * g.ldx + cbase;
; #pragma unroll
;         for (int bj = 0; bj < 2; ++bj)
; #pragma unroll
;           for (int n = 0; n < 2; ++n) {
;             f32x4 v = acc[ai][bj][m][n];
;             u32x2 z = *reinterpret_cast<const u32x2*>(Zr + bj * HALF + n * 16);
;             float o0 = v[0] * silu(bf_lo(z[0])), o1 = v[1] * silu(bf_hi(z[0]));
;             float o2 = v[2] * silu(bf_lo(z[1])), o3 = v[3] * silu(bf_hi(z[1]));
;             u32x2 w = {cvtpk(o0, o1), cvtpk(o2, o3)};
;             *reinterpret_cast<u32x2*>(Cr + bj * HALF + n * 16) = w;
;           }
	v_mov_b32_e32 v134, v174
	v_mov_b32_e32 v135, v175
	v_lshlrev_b32_e32 v1, 16, v134
	v_mul_f32_e32 v2, 0xbfb8aa3b, v1
	v_exp_f32_e32 v2, v2
	s_nop 0
	v_add_f32_e32 v2, 1.0, v2
	v_div_scale_f32 v133, s[0:1], v2, v2, v1
	v_rcp_f32_e32 v138, v133
	s_nop 0
	v_fma_f32 v139, -v133, v138, 1.0
	v_fmac_f32_e32 v138, v139, v138
	v_div_scale_f32 v139, vcc, v1, v2, v1
	v_mul_f32_e32 v140, v139, v138
	v_fma_f32 v141, -v133, v140, v139
	v_fmac_f32_e32 v140, v141, v138
	v_fma_f32 v133, -v133, v140, v139
	v_div_fmas_f32 v133, v133, v138, v140
	v_div_fixup_f32 v1, v133, v2, v1
	v_and_b32_e32 v2, 0xffff0000, v134
	v_mul_f32_e32 v133, 0xbfb8aa3b, v2
	v_exp_f32_e32 v133, v133
	v_mul_f32_e32 v1, v4, v1
	v_add_f32_e32 v133, 1.0, v133
	v_div_scale_f32 v134, s[0:1], v133, v133, v2
	v_rcp_f32_e32 v138, v134
	s_nop 0
	v_fma_f32 v139, -v134, v138, 1.0
	v_fmac_f32_e32 v138, v139, v138
	v_div_scale_f32 v139, vcc, v2, v133, v2
	v_mul_f32_e32 v140, v139, v138
	v_fma_f32 v141, -v134, v140, v139
	v_fmac_f32_e32 v140, v141, v138
	v_fma_f32 v134, -v134, v140, v139
	v_div_fmas_f32 v134, v134, v138, v140
	v_div_fixup_f32 v2, v134, v133, v2
	v_lshlrev_b32_e32 v133, 16, v135
	v_mul_f32_e32 v134, 0xbfb8aa3b, v133
	v_exp_f32_e32 v134, v134
	v_mul_f32_e32 v2, v5, v2
	v_add_f32_e32 v134, 1.0, v134
	v_div_scale_f32 v138, s[0:1], v134, v134, v133
	v_rcp_f32_e32 v139, v138
	s_nop 0
	v_fma_f32 v140, -v138, v139, 1.0
	v_fmac_f32_e32 v139, v140, v139
	v_div_scale_f32 v140, vcc, v133, v134, v133
	v_mul_f32_e32 v141, v140, v139
	v_fma_f32 v142, -v138, v141, v140
	v_fmac_f32_e32 v141, v142, v139
	v_fma_f32 v138, -v138, v141, v140
	v_div_fmas_f32 v138, v138, v139, v141
	v_div_fixup_f32 v133, v138, v134, v133
	v_and_b32_e32 v134, 0xffff0000, v135
	v_mul_f32_e32 v135, 0xbfb8aa3b, v134
	v_exp_f32_e32 v135, v135
	v_mul_f32_e32 v133, v6, v133
	v_add_f32_e32 v135, 1.0, v135
	v_div_scale_f32 v138, s[0:1], v135, v135, v134
	v_rcp_f32_e32 v139, v138
	s_mov_b64 s[0:1], 0
	v_fma_f32 v140, -v138, v139, 1.0
	v_fmac_f32_e32 v139, v140, v139
	v_div_scale_f32 v140, vcc, v134, v135, v134
	v_mul_f32_e32 v141, v140, v139
	v_fma_f32 v142, -v138, v141, v140
	v_fmac_f32_e32 v141, v142, v139
	v_fma_f32 v138, -v138, v141, v140
	v_div_fmas_f32 v138, v138, v139, v141
	v_div_fixup_f32 v134, v138, v135, v134
	v_mul_f32_e32 v135, v7, v134
	v_cvt_pk_bf16_f32 v134, v1, v2
	v_cvt_pk_bf16_f32 v135, v133, v135
	flat_store_dwordx2 v[136:137], v[134:135] offset:288
	s_branch .LBB0_70

; __device__ __forceinline__ float bf_lo(unsigned u) { return __uint_as_float(u << 16); }
; __device__ __forceinline__ float bf_hi(unsigned u) { return __uint_as_float(u & 0xffff0000u); }
; __global__ __launch_bounds__(512, 2)
; void hybrid_megakernel(Params p_in) {
;     ...
;         for (int tk = gw; tk < NTOK; tk += nw) {
;           const bf16* pr = proj + (long)tk * INC + OFF_Q + lane * 8;
;           u32x4 w[8];
; #pragma unroll
;           for (int i = 0; i < 8; ++i) w[i] = *reinterpret_cast<const u32x4*>(pr + i * 512);
; #pragma unroll
;           for (int i = 0; i < 8; ++i) {
;             float ss = 0.f;
; #pragma unroll
;             for (int q = 0; q < 4; ++q) { const float a = bf_lo(w[i][q]), b2 = bf_hi(w[i][q]); ss += a * a + b2 * b2; }
;             ss += __shfl_xor(ss, 1, 64); ss += __shfl_xor(ss, 2, 64); ss += __shfl_xor(ss, 4, 64); ss += __shfl_xor(ss, 8, 64);
;             mx[i] = fmaxf(mx[i], ss);
;           }
; #pragma unroll
;           for (int i = 0; i < 4; ++i) {
;             float dt = 0.f;
; #pragma unroll
;             for (int q = 0; q < 4; ++q) dt += bf_lo(w[i][q]) * bf_lo(w[i + 4][q]) + bf_hi(w[i][q]) * bf_hi(w[i + 4][q]);
;             dt += __shfl_xor(dt, 1, 64); dt += __shfl_xor(dt, 2, 64); dt += __shfl_xor(dt, 4, 64); dt += __shfl_xor(dt, 8, 64);
;             ms[i] = fmaxf(ms[i], -dt);
;           }
.LBB0_104:
	v_add_co_u32_e32 v4, vcc, 0xfffff000, v0
	v_max_f32_e32 v40, v40, v40
	s_nop 0
	v_addc_co_u32_e32 v5, vcc, -1, v1, vcc
	global_load_dwordx4 v[28:31], v[4:5], off offset:-3072
	global_load_dwordx4 v[24:27], v[4:5], off offset:-2048
	global_load_dwordx4 v[16:19], v[4:5], off offset:-1024
	global_load_dwordx4 v[8:11], v[0:1], off offset:-4096
	global_load_dwordx4 v[48:51], v[0:1], off offset:-3072
	global_load_dwordx4 v[20:23], v[0:1], off offset:-2048
	global_load_dwordx4 v[12:15], v[0:1], off offset:-1024
	s_nop 0
	global_load_dwordx4 v[4:7], v[0:1], off
	s_add_i32 s11, s10, s62
	s_cmpk_gt_i32 s11, 0x3fff
	s_cselect_b64 s[0:1], -1, 0
	s_cmpk_lt_i32 s11, 0x4000
	s_cselect_b64 s[2:3], -1, 0
	s_xor_b32 s14, s11, s10
	s_cmpk_lt_u32 s14, 0x2000
	s_cselect_b64 s[14:15], -1, 0
	v_max_f32_e32 v44, v44, v44
	s_and_b64 s[2:3], s[2:3], s[14:15]
	s_and_b64 vcc, exec, s[2:3]
	s_waitcnt vmcnt(0)
	v_lshlrev_b32_e32 v53, 16, v29
	v_lshlrev_b32_e32 v52, 16, v28
	v_and_b32_e32 v29, 0xffff0000, v29
	v_and_b32_e32 v28, 0xffff0000, v28
	v_lshlrev_b32_e32 v57, 16, v49
	v_lshlrev_b32_e32 v56, 16, v48
	v_and_b32_e32 v49, 0xffff0000, v49
	v_and_b32_e32 v48, 0xffff0000, v48
	v_pk_mul_f32 v[54:55], v[28:29], v[28:29]
	v_pk_mul_f32 v[28:29], v[28:29], v[48:49]
	v_pk_mul_f32 v[58:59], v[48:49], v[48:49]
	v_pk_fma_f32 v[28:29], v[52:53], v[56:57], v[28:29]
	v_pk_fma_f32 v[58:59], v[56:57], v[56:57], v[58:59]
	v_add_f32_e32 v28, 0, v28
	v_add_f32_e32 v56, v28, v29
	v_lshlrev_b32_e32 v29, 16, v31
	v_lshlrev_b32_e32 v28, 16, v30
	v_and_b32_e32 v31, 0xffff0000, v31
	v_and_b32_e32 v30, 0xffff0000, v30
	v_pk_fma_f32 v[54:55], v[52:53], v[52:53], v[54:55]
	v_pk_mul_f32 v[48:49], v[30:31], v[30:31]
	v_add_f32_e32 v52, v54, v55
	v_pk_fma_f32 v[48:49], v[28:29], v[28:29], v[48:49]
	v_add_f32_e32 v54, v58, v59
	v_add_f32_e32 v48, v52, v48
	v_add_f32_e32 v48, v48, v49
	s_nop 1
	v_mov_b32_dpp v49, v48 quad_perm:[1,0,3,2] row_mask:0xf bank_mask:0xf
	s_waitcnt lgkmcnt(0)
	v_add_f32_e32 v48, v48, v49
	s_nop 1
	v_mov_b32_dpp v49, v48 quad_perm:[2,3,0,1] row_mask:0xf bank_mask:0xf
	s_waitcnt lgkmcnt(0)
	v_add_f32_e32 v48, v48, v49
	s_nop 1
	v_mov_b32_dpp v49, v48 row_shl:4 row_mask:0xf bank_mask:0x5
	v_mov_b32_dpp v49, v48 row_shr:4 row_mask:0xf bank_mask:0xa
	s_waitcnt lgkmcnt(0)
	v_add_f32_e32 v48, v48, v49
	s_nop 1
	v_mov_b32_dpp v49, v48 row_ror:8 row_mask:0xf bank_mask:0xf
	s_waitcnt lgkmcnt(0)
	v_add_f32_e32 v48, v48, v49
	v_max_f32_e32 v40, v40, v48
	v_lshlrev_b32_e32 v49, 16, v51
	v_lshlrev_b32_e32 v48, 16, v50
	v_and_b32_e32 v51, 0xffff0000, v51
	v_and_b32_e32 v50, 0xffff0000, v50
	v_pk_mul_f32 v[30:31], v[30:31], v[50:51]
	v_pk_mul_f32 v[52:53], v[50:51], v[50:51]
	v_pk_fma_f32 v[28:29], v[28:29], v[48:49], v[30:31]
	v_lshlrev_b32_e32 v31, 16, v25
	v_add_f32_e32 v28, v56, v28
	v_add_f32_e32 v28, v28, v29
	s_nop 1
	v_mov_b32_dpp v29, v28 quad_perm:[1,0,3,2] row_mask:0xf bank_mask:0xf
	v_lshlrev_b32_e32 v30, 16, v24
	v_and_b32_e32 v25, 0xffff0000, v25
	v_and_b32_e32 v24, 0xffff0000, v24
	v_lshlrev_b32_e32 v51, 16, v21
	s_waitcnt lgkmcnt(0)
	v_add_f32_e32 v28, v28, v29
	s_nop 1
	v_mov_b32_dpp v29, v28 quad_perm:[2,3,0,1] row_mask:0xf bank_mask:0xf
	v_lshlrev_b32_e32 v50, 16, v20
	v_and_b32_e32 v21, 0xffff0000, v21
	v_and_b32_e32 v20, 0xffff0000, v20
	v_pk_fma_f32 v[52:53], v[48:49], v[48:49], v[52:53]
	s_waitcnt lgkmcnt(0)
	v_add_f32_e32 v28, v28, v29
	s_nop 1
	v_mov_b32_dpp v29, v28 row_shl:4 row_mask:0xf bank_mask:0x5
	v_mov_b32_dpp v29, v28 row_shr:4 row_mask:0xf bank_mask:0xa
	v_add_f32_e32 v52, v54, v52
	v_add_f32_e32 v52, v52, v53
	s_nop 1
	v_mov_b32_dpp v53, v52 quad_perm:[1,0,3,2] row_mask:0xf bank_mask:0xf
	s_waitcnt lgkmcnt(1)
	v_add_f32_e32 v28, v28, v29
	s_nop 1
	v_mov_b32_dpp v29, v28 row_ror:8 row_mask:0xf bank_mask:0xf
	s_waitcnt lgkmcnt(1)
	v_add_f32_e32 v52, v52, v53
	s_nop 1
	v_mov_b32_dpp v53, v52 quad_perm:[2,3,0,1] row_mask:0xf bank_mask:0xf
	s_waitcnt lgkmcnt(1)
	v_add_f32_e32 v28, v28, v29
	v_max_f32_e32 v29, v36, v36
	v_max_f32_e64 v36, v29, -v28
	v_pk_mul_f32 v[28:29], v[24:25], v[24:25]
	s_waitcnt lgkmcnt(0)
	v_add_f32_e32 v52, v52, v53
	v_pk_fma_f32 v[48:49], v[30:31], v[30:31], v[28:29]
	v_pk_mul_f32 v[28:29], v[20:21], v[20:21]
	v_pk_mul_f32 v[20:21], v[24:25], v[20:21]
	v_and_b32_e32 v25, 0xffff0000, v27
	v_pk_fma_f32 v[20:21], v[30:31], v[50:51], v[20:21]
	v_and_b32_e32 v24, 0xffff0000, v26
	v_add_f32_e32 v20, 0, v20
	v_add_f32_e32 v30, v20, v21
	v_lshlrev_b32_e32 v21, 16, v27
	v_lshlrev_b32_e32 v20, 16, v26
	v_pk_mul_f32 v[26:27], v[24:25], v[24:25]
	v_add_f32_e32 v31, v48, v49
	v_pk_fma_f32 v[26:27], v[20:21], v[20:21], v[26:27]
	v_pk_fma_f32 v[28:29], v[50:51], v[50:51], v[28:29]
	v_add_f32_e32 v26, v31, v26
	v_add_f32_e32 v26, v26, v27
	s_nop 1
	v_mov_b32_dpp v27, v26 quad_perm:[1,0,3,2] row_mask:0xf bank_mask:0xf
	v_add_f32_e32 v28, v28, v29
	s_nop 1
	v_mov_b32_dpp v53, v52 row_shl:4 row_mask:0xf bank_mask:0x5
	v_mov_b32_dpp v53, v52 row_shr:4 row_mask:0xf bank_mask:0xa
	s_waitcnt lgkmcnt(1)
	v_add_f32_e32 v26, v26, v27
	s_nop 1
	v_mov_b32_dpp v27, v26 quad_perm:[2,3,0,1] row_mask:0xf bank_mask:0xf
	s_waitcnt lgkmcnt(1)
	v_add_f32_e32 v52, v52, v53
	s_nop 1
	v_mov_b32_dpp v53, v52 row_ror:8 row_mask:0xf bank_mask:0xf
	s_waitcnt lgkmcnt(1)
	v_add_f32_e32 v26, v26, v27
	s_nop 1
	v_mov_b32_dpp v27, v26 row_shl:4 row_mask:0xf bank_mask:0x5
	v_mov_b32_dpp v27, v26 row_shr:4 row_mask:0xf bank_mask:0xa
	s_waitcnt lgkmcnt(1)
	v_add_f32_e32 v52, v52, v53
	v_max_f32_e32 v44, v44, v52
	s_waitcnt lgkmcnt(0)
	v_add_f32_e32 v26, v26, v27
	s_nop 1
	v_mov_b32_dpp v27, v26 row_ror:8 row_mask:0xf bank_mask:0xf
	s_waitcnt lgkmcnt(0)
; __device__ __forceinline__ float bf_lo(unsigned u) { return __uint_as_float(u << 16); }
; __device__ __forceinline__ float bf_hi(unsigned u) { return __uint_as_float(u & 0xffff0000u); }
; __global__ __launch_bounds__(512, 2)
; void hybrid_megakernel(Params p_in) {
;     ...
;           for (int i = 0; i < 8; ++i) w[i] = *reinterpret_cast<const u32x4*>(pr + i * 512);
; #pragma unroll
;           for (int i = 0; i < 8; ++i) {
;             float ss = 0.f;
; #pragma unroll
;             for (int q = 0; q < 4; ++q) { const float a = bf_lo(w[i][q]), b2 = bf_hi(w[i][q]); ss += a * a + b2 * b2; }
;             ss += __shfl_xor(ss, 1, 64); ss += __shfl_xor(ss, 2, 64); ss += __shfl_xor(ss, 4, 64); ss += __shfl_xor(ss, 8, 64);
;             mx[i] = fmaxf(mx[i], ss);
;           }
; #pragma unroll
;           for (int i = 0; i < 4; ++i) {
;             float dt = 0.f;
; #pragma unroll
;             for (int q = 0; q < 4; ++q) dt += bf_lo(w[i][q]) * bf_lo(w[i + 4][q]) + bf_hi(w[i][q]) * bf_hi(w[i + 4][q]);
;             dt += __shfl_xor(dt, 1, 64); dt += __shfl_xor(dt, 2, 64); dt += __shfl_xor(dt, 4, 64); dt += __shfl_xor(dt, 8, 64);
;             ms[i] = fmaxf(ms[i], -dt);
;           }
	v_add_f32_e32 v26, v26, v27
	v_max_f32_e32 v27, v41, v41
	v_max_f32_e32 v41, v27, v26
	v_lshlrev_b32_e32 v27, 16, v23
	v_lshlrev_b32_e32 v26, 16, v22
	v_and_b32_e32 v23, 0xffff0000, v23
	v_and_b32_e32 v22, 0xffff0000, v22
	v_pk_mul_f32 v[48:49], v[22:23], v[22:23]
	v_pk_mul_f32 v[22:23], v[24:25], v[22:23]
	v_lshlrev_b32_e32 v25, 16, v13
	v_pk_fma_f32 v[20:21], v[20:21], v[26:27], v[22:23]
	v_lshlrev_b32_e32 v24, 16, v12
	v_add_f32_e32 v20, v30, v20
	v_add_f32_e32 v20, v20, v21
	s_nop 1
	v_mov_b32_dpp v21, v20 quad_perm:[1,0,3,2] row_mask:0xf bank_mask:0xf
	v_and_b32_e32 v13, 0xffff0000, v13
	v_and_b32_e32 v12, 0xffff0000, v12
	v_pk_fma_f32 v[48:49], v[26:27], v[26:27], v[48:49]
	v_pk_mul_f32 v[26:27], v[12:13], v[12:13]
	s_waitcnt lgkmcnt(0)
	v_add_f32_e32 v20, v20, v21
	s_nop 1
	v_mov_b32_dpp v21, v20 quad_perm:[2,3,0,1] row_mask:0xf bank_mask:0xf
	v_pk_fma_f32 v[26:27], v[24:25], v[24:25], v[26:27]
	v_add_f32_e32 v28, v28, v48
	v_add_f32_e32 v28, v28, v49
	s_nop 1
	v_mov_b32_dpp v29, v28 quad_perm:[1,0,3,2] row_mask:0xf bank_mask:0xf
	s_waitcnt lgkmcnt(1)
	v_add_f32_e32 v20, v20, v21
	s_nop 1
	v_mov_b32_dpp v21, v20 row_shl:4 row_mask:0xf bank_mask:0x5
	v_mov_b32_dpp v21, v20 row_shr:4 row_mask:0xf bank_mask:0xa
	s_waitcnt lgkmcnt(1)
	v_add_f32_e32 v28, v28, v29
	s_nop 1
	v_mov_b32_dpp v29, v28 quad_perm:[2,3,0,1] row_mask:0xf bank_mask:0xf
	s_waitcnt lgkmcnt(1)
	v_add_f32_e32 v20, v20, v21
	s_nop 1
	v_mov_b32_dpp v21, v20 row_ror:8 row_mask:0xf bank_mask:0xf
	s_waitcnt lgkmcnt(1)
	v_add_f32_e32 v28, v28, v29
	s_nop 1
	v_mov_b32_dpp v29, v28 row_shl:4 row_mask:0xf bank_mask:0x5
	v_mov_b32_dpp v29, v28 row_shr:4 row_mask:0xf bank_mask:0xa
	s_waitcnt lgkmcnt(1)
	v_add_f32_e32 v20, v20, v21
	v_max_f32_e32 v21, v37, v37
	v_max_f32_e64 v37, v21, -v20
	v_lshlrev_b32_e32 v21, 16, v17
	v_lshlrev_b32_e32 v20, 16, v16
	v_and_b32_e32 v17, 0xffff0000, v17
	v_and_b32_e32 v16, 0xffff0000, v16
	v_pk_mul_f32 v[12:13], v[16:17], v[12:13]
	v_pk_mul_f32 v[22:23], v[16:17], v[16:17]
	v_pk_fma_f32 v[12:13], v[20:21], v[24:25], v[12:13]
	v_and_b32_e32 v17, 0xffff0000, v19
	v_add_f32_e32 v12, 0, v12
	v_and_b32_e32 v16, 0xffff0000, v18
	v_pk_fma_f32 v[22:23], v[20:21], v[20:21], v[22:23]
	v_add_f32_e32 v24, v12, v13
	v_lshlrev_b32_e32 v13, 16, v19
	v_lshlrev_b32_e32 v12, 16, v18
	v_pk_mul_f32 v[18:19], v[16:17], v[16:17]
	v_add_f32_e32 v20, v22, v23
	v_pk_fma_f32 v[18:19], v[12:13], v[12:13], v[18:19]
	v_add_f32_e32 v22, v26, v27
	v_add_f32_e32 v18, v20, v18
	v_add_f32_e32 v18, v18, v19
	s_nop 1
	v_mov_b32_dpp v19, v18 quad_perm:[1,0,3,2] row_mask:0xf bank_mask:0xf
	s_waitcnt lgkmcnt(1)
	v_add_f32_e32 v28, v28, v29
	s_nop 1
	v_mov_b32_dpp v29, v28 row_ror:8 row_mask:0xf bank_mask:0xf
	s_waitcnt lgkmcnt(1)
	v_add_f32_e32 v18, v18, v19
	s_nop 1
	v_mov_b32_dpp v19, v18 quad_perm:[2,3,0,1] row_mask:0xf bank_mask:0xf
	s_waitcnt lgkmcnt(1)
	v_add_f32_e32 v28, v28, v29
	v_max_f32_e32 v29, v45, v45
	v_max_f32_e32 v45, v29, v28
	s_waitcnt lgkmcnt(0)
	v_add_f32_e32 v18, v18, v19
	s_nop 1
	v_mov_b32_dpp v19, v18 row_shl:4 row_mask:0xf bank_mask:0x5
	v_mov_b32_dpp v19, v18 row_shr:4 row_mask:0xf bank_mask:0xa
	s_waitcnt lgkmcnt(0)
	v_add_f32_e32 v18, v18, v19
	s_nop 1
	v_mov_b32_dpp v19, v18 row_ror:8 row_mask:0xf bank_mask:0xf
	s_waitcnt lgkmcnt(0)
	v_add_f32_e32 v18, v18, v19
	v_max_f32_e32 v19, v42, v42
	v_max_f32_e32 v42, v19, v18
	v_lshlrev_b32_e32 v19, 16, v15
	v_lshlrev_b32_e32 v18, 16, v14
	v_and_b32_e32 v15, 0xffff0000, v15
	v_and_b32_e32 v14, 0xffff0000, v14
	v_pk_mul_f32 v[20:21], v[14:15], v[14:15]
	v_pk_mul_f32 v[14:15], v[16:17], v[14:15]
	v_lshlrev_b32_e32 v17, 16, v5
	v_pk_fma_f32 v[12:13], v[12:13], v[18:19], v[14:15]
	v_lshlrev_b32_e32 v16, 16, v4
	v_add_f32_e32 v12, v24, v12
	v_add_f32_e32 v12, v12, v13
	s_nop 1
	v_mov_b32_dpp v13, v12 quad_perm:[1,0,3,2] row_mask:0xf bank_mask:0xf
	v_and_b32_e32 v5, 0xffff0000, v5
	v_and_b32_e32 v4, 0xffff0000, v4
	v_pk_fma_f32 v[20:21], v[18:19], v[18:19], v[20:21]
	v_pk_mul_f32 v[18:19], v[4:5], v[4:5]
	s_waitcnt lgkmcnt(0)
	v_add_f32_e32 v12, v12, v13
	s_nop 1
	v_mov_b32_dpp v13, v12 quad_perm:[2,3,0,1] row_mask:0xf bank_mask:0xf
	v_pk_fma_f32 v[18:19], v[16:17], v[16:17], v[18:19]
	v_add_f32_e32 v20, v22, v20
	v_add_f32_e32 v20, v20, v21
	s_nop 1
	v_mov_b32_dpp v21, v20 quad_perm:[1,0,3,2] row_mask:0xf bank_mask:0xf
	s_waitcnt lgkmcnt(1)
	v_add_f32_e32 v12, v12, v13
	s_nop 1
	v_mov_b32_dpp v13, v12 row_shl:4 row_mask:0xf bank_mask:0x5
	v_mov_b32_dpp v13, v12 row_shr:4 row_mask:0xf bank_mask:0xa
	s_waitcnt lgkmcnt(1)
	v_add_f32_e32 v20, v20, v21
	s_nop 1
	v_mov_b32_dpp v21, v20 quad_perm:[2,3,0,1] row_mask:0xf bank_mask:0xf
	s_waitcnt lgkmcnt(1)
	v_add_f32_e32 v12, v12, v13
	s_nop 1
	v_mov_b32_dpp v13, v12 row_ror:8 row_mask:0xf bank_mask:0xf
	s_waitcnt lgkmcnt(1)
	v_add_f32_e32 v20, v20, v21
	s_nop 1
	v_mov_b32_dpp v21, v20 row_shl:4 row_mask:0xf bank_mask:0x5
	v_mov_b32_dpp v21, v20 row_shr:4 row_mask:0xf bank_mask:0xa
	s_waitcnt lgkmcnt(1)
; __device__ __forceinline__ float bf_lo(unsigned u) { return __uint_as_float(u << 16); }
; __device__ __forceinline__ float bf_hi(unsigned u) { return __uint_as_float(u & 0xffff0000u); }
; __global__ __launch_bounds__(512, 2)
; void hybrid_megakernel(Params p_in) {
;     ...
;           for (int i = 0; i < 8; ++i) w[i] = *reinterpret_cast<const u32x4*>(pr + i * 512);
; #pragma unroll
;           for (int i = 0; i < 8; ++i) {
;             float ss = 0.f;
; #pragma unroll
;             for (int q = 0; q < 4; ++q) { const float a = bf_lo(w[i][q]), b2 = bf_hi(w[i][q]); ss += a * a + b2 * b2; }
;             ss += __shfl_xor(ss, 1, 64); ss += __shfl_xor(ss, 2, 64); ss += __shfl_xor(ss, 4, 64); ss += __shfl_xor(ss, 8, 64);
;             mx[i] = fmaxf(mx[i], ss);
;           }
; #pragma unroll
;           for (int i = 0; i < 4; ++i) {
;             float dt = 0.f;
; #pragma unroll
;             for (int q = 0; q < 4; ++q) dt += bf_lo(w[i][q]) * bf_lo(w[i + 4][q]) + bf_hi(w[i][q]) * bf_hi(w[i + 4][q]);
;             dt += __shfl_xor(dt, 1, 64); dt += __shfl_xor(dt, 2, 64); dt += __shfl_xor(dt, 4, 64); dt += __shfl_xor(dt, 8, 64);
;             ms[i] = fmaxf(ms[i], -dt);
;           }
;           if (tk + nw >= NTOK || ((tk + nw) >> 13) != (tk >> 13)) {
;             if ((lane & 15) == 0) {
; #pragma unroll
;               for (int i = 0; i < 8; ++i) atomicMax(&nrm[(tk >> 13) * 32 + (lane >> 4) + 4 * i], __float_as_uint(mx[i]));
; #pragma unroll
;               for (int i = 0; i < 4; ++i) atomicMax(&nself[(tk >> 13) * 16 + (lane >> 4) + 4 * i], __float_as_uint(ms[i]));
;             }
; #pragma unroll
;             for (int i = 0; i < 8; ++i) mx[i] = 0.f;
; #pragma unroll
;             for (int i = 0; i < 4; ++i) ms[i] = 0.f;
;           }
	v_add_f32_e32 v12, v12, v13
	v_max_f32_e32 v13, v38, v38
	v_max_f32_e64 v38, v13, -v12
	v_lshlrev_b32_e32 v13, 16, v9
	v_lshlrev_b32_e32 v12, 16, v8
	v_and_b32_e32 v9, 0xffff0000, v9
	v_and_b32_e32 v8, 0xffff0000, v8
	v_pk_mul_f32 v[4:5], v[8:9], v[4:5]
	v_pk_mul_f32 v[14:15], v[8:9], v[8:9]
	v_pk_fma_f32 v[4:5], v[12:13], v[16:17], v[4:5]
	v_and_b32_e32 v9, 0xffff0000, v11
	v_add_f32_e32 v4, 0, v4
	v_and_b32_e32 v8, 0xffff0000, v10
	v_pk_fma_f32 v[14:15], v[12:13], v[12:13], v[14:15]
	v_add_f32_e32 v16, v4, v5
	v_lshlrev_b32_e32 v5, 16, v11
	v_lshlrev_b32_e32 v4, 16, v10
	v_pk_mul_f32 v[10:11], v[8:9], v[8:9]
	v_add_f32_e32 v12, v14, v15
	v_pk_fma_f32 v[10:11], v[4:5], v[4:5], v[10:11]
	v_add_f32_e32 v14, v18, v19
	v_add_f32_e32 v10, v12, v10
	v_add_f32_e32 v10, v10, v11
	s_nop 1
	v_mov_b32_dpp v11, v10 quad_perm:[1,0,3,2] row_mask:0xf bank_mask:0xf
	s_waitcnt lgkmcnt(1)
	v_add_f32_e32 v20, v20, v21
	s_nop 1
	v_mov_b32_dpp v21, v20 row_ror:8 row_mask:0xf bank_mask:0xf
	s_waitcnt lgkmcnt(1)
	v_add_f32_e32 v10, v10, v11
	s_nop 1
	v_mov_b32_dpp v11, v10 quad_perm:[2,3,0,1] row_mask:0xf bank_mask:0xf
	s_waitcnt lgkmcnt(1)
	v_add_f32_e32 v20, v20, v21
	v_max_f32_e32 v21, v46, v46
	v_max_f32_e32 v46, v21, v20
	s_waitcnt lgkmcnt(0)
	v_add_f32_e32 v10, v10, v11
	s_nop 1
	v_mov_b32_dpp v11, v10 row_shl:4 row_mask:0xf bank_mask:0x5
	v_mov_b32_dpp v11, v10 row_shr:4 row_mask:0xf bank_mask:0xa
	s_waitcnt lgkmcnt(0)
	v_add_f32_e32 v10, v10, v11
	s_nop 1
	v_mov_b32_dpp v11, v10 row_ror:8 row_mask:0xf bank_mask:0xf
	s_waitcnt lgkmcnt(0)
	v_add_f32_e32 v10, v10, v11
	v_max_f32_e32 v11, v43, v43
	v_max_f32_e32 v43, v11, v10
	v_lshlrev_b32_e32 v11, 16, v7
	v_lshlrev_b32_e32 v10, 16, v6
	v_and_b32_e32 v7, 0xffff0000, v7
	v_and_b32_e32 v6, 0xffff0000, v6
	v_pk_mul_f32 v[12:13], v[6:7], v[6:7]
	v_pk_mul_f32 v[6:7], v[8:9], v[6:7]
	v_pk_fma_f32 v[12:13], v[10:11], v[10:11], v[12:13]
	v_pk_fma_f32 v[4:5], v[4:5], v[10:11], v[6:7]
	v_add_f32_e32 v12, v14, v12
	v_add_f32_e32 v4, v16, v4
	v_add_f32_e32 v12, v12, v13
	v_add_f32_e32 v4, v4, v5
	s_nop 1
	v_mov_b32_dpp v13, v12 quad_perm:[1,0,3,2] row_mask:0xf bank_mask:0xf
	s_nop 1
	v_mov_b32_dpp v5, v4 quad_perm:[1,0,3,2] row_mask:0xf bank_mask:0xf
	s_waitcnt lgkmcnt(1)
	v_add_f32_e32 v12, v12, v13
	s_waitcnt lgkmcnt(0)
	v_add_f32_e32 v4, v4, v5
	s_nop 1
	v_mov_b32_dpp v13, v12 quad_perm:[2,3,0,1] row_mask:0xf bank_mask:0xf
	s_nop 1
	v_mov_b32_dpp v5, v4 quad_perm:[2,3,0,1] row_mask:0xf bank_mask:0xf
	s_waitcnt lgkmcnt(1)
	v_add_f32_e32 v12, v12, v13
	s_waitcnt lgkmcnt(0)
	v_add_f32_e32 v4, v4, v5
	s_nop 1
	v_mov_b32_dpp v13, v12 row_shl:4 row_mask:0xf bank_mask:0x5
	v_mov_b32_dpp v13, v12 row_shr:4 row_mask:0xf bank_mask:0xa
	s_nop 1
	v_mov_b32_dpp v5, v4 row_shl:4 row_mask:0xf bank_mask:0x5
	v_mov_b32_dpp v5, v4 row_shr:4 row_mask:0xf bank_mask:0xa
	s_waitcnt lgkmcnt(1)
	v_add_f32_e32 v12, v12, v13
	s_waitcnt lgkmcnt(0)
	v_add_f32_e32 v4, v4, v5
	s_nop 1
	v_mov_b32_dpp v13, v12 row_ror:8 row_mask:0xf bank_mask:0xf
	s_nop 1
	v_mov_b32_dpp v5, v4 row_ror:8 row_mask:0xf bank_mask:0xf
	s_waitcnt lgkmcnt(1)
	v_add_f32_e32 v12, v12, v13
	v_max_f32_e32 v13, v47, v47
	s_waitcnt lgkmcnt(0)
	v_add_f32_e32 v4, v4, v5
	v_max_f32_e32 v5, v39, v39
	v_max_f32_e32 v47, v13, v12
	v_max_f32_e64 v39, v5, -v4
	s_cbranch_vccnz .LBB0_103
	s_cmpk_lg_i32 s52, 0x100
	s_cbranch_scc1 .Lmn_old
	v_readlane_b32 s14, v255, 3
	s_mul_i32 s15, s14, 0xc0
	s_add_i32 s15, s15, 0x22000
	s_and_saveexec_b64 s[2:3], s[4:5]
	v_lshl_add_u32 v4, v35, 2, s15
	ds_write_b32 v4, v40
	ds_write_b32 v4, v41 offset:16
	ds_write_b32 v4, v42 offset:32
	ds_write_b32 v4, v43 offset:48
	ds_write_b32 v4, v44 offset:64
	ds_write_b32 v4, v45 offset:80
	ds_write_b32 v4, v46 offset:96
	ds_write_b32 v4, v47 offset:112
	ds_write_b32 v4, v36 offset:128
	ds_write_b32 v4, v37 offset:144
	ds_write_b32 v4, v38 offset:160
	ds_write_b32 v4, v39 offset:176
	s_or_b64 exec, exec, s[2:3]
	s_waitcnt lgkmcnt(0)
	s_barrier
	s_cmp_lg_u32 s14, 0
	s_cbranch_scc1 .Lmn_wait
	v_cmp_gt_u32_e32 vcc, 48, v162
	s_and_saveexec_b64 s[2:3], vcc
	v_lshlrev_b32_e32 v4, 2, v162
	v_add_u32_e32 v5, 0x22000, v4
	ds_read_b32 v6, v5
	ds_read_b32 v7, v5 offset:192
	ds_read_b32 v8, v5 offset:384
	ds_read_b32 v9, v5 offset:576
	ds_read_b32 v10, v5 offset:768
	ds_read_b32 v11, v5 offset:960
	ds_read_b32 v12, v5 offset:1152
	ds_read_b32 v13, v5 offset:1344
	s_ashr_i32 s15, s10, 13
	s_lshl_b32 s16, s15, 7
	s_lshl_b32 s17, s15, 6
	v_cmp_gt_u32_e32 vcc, 32, v162
	v_add_u32_e32 v14, s16, v4
	v_add_u32_e32 v15, s17, v4
	v_subrev_u32_e32 v15, 0x80, v15
	v_mov_b32_e32 v16, s6
	v_mov_b32_e32 v17, s7
	v_mov_b32_e32 v18, s8
	v_mov_b32_e32 v19, s9
	v_cndmask_b32_e32 v14, v15, v14, vcc
	v_cndmask_b32_e32 v16, v18, v16, vcc
	v_cndmask_b32_e32 v17, v19, v17, vcc
	v_add_co_u32_e32 v16, vcc, v16, v14
	s_nop 1
	v_addc_co_u32_e32 v17, vcc, 0, v17, vcc
	s_waitcnt lgkmcnt(0)
	v_max_u32_e32 v6, v6, v7
	v_max_u32_e32 v8, v8, v9
	v_max_u32_e32 v10, v10, v11
	v_max_u32_e32 v12, v12, v13
	v_max_u32_e32 v6, v6, v8
	v_max_u32_e32 v10, v10, v12
	v_max_u32_e32 v6, v6, v10
	global_atomic_umax v[16:17], v6, off
	s_or_b64 exec, exec, s[2:3]

; __device__ __forceinline__ float bf_lo(unsigned u) { return __uint_as_float(u << 16); }
; __device__ __forceinline__ float bf_hi(unsigned u) { return __uint_as_float(u & 0xffff0000u); }
; __device__ __forceinline__ float silu(float z) { return z / (1.f + __expf(-z)); }
; __device__ __forceinline__ float wave_sum(float v) {
; #pragma unroll
;   for (int o = 32; o > 0; o >>= 1) v += __shfl_xor(v, o, 64);
;   return v;
; }
; __global__ __launch_bounds__(512, 2)
; void hybrid_megakernel(Params p_in) {
;     ...
;           for (int u = 0; u < 4; ++u) {
;             o1[u] = *reinterpret_cast<const u32x2*>(attB + (long)tok * 2048 + (h0 + u) * 256 + lane * 4);
;             o2[u] = *reinterpret_cast<const u32x2*>(attB + (long)NTOK * 2048 + (long)tok * 2048 + (h0 + u) * 256 + lane * 4);
;             zz[u] = *reinterpret_cast<const u32x2*>(proj + (long)tok * INC + OFF_ZD + (h0 + u) * 256 + lane * 4); }
; #pragma unroll
;           for (int u = 0; u < 4; ++u) {
;             const f32x4 a1 = {bf_lo(o1[u][0]), bf_hi(o1[u][0]), bf_lo(o1[u][1]), bf_hi(o1[u][1])};
;             const f32x4 a2 = {bf_lo(o2[u][0]), bf_hi(o2[u][0]), bf_lo(o2[u][1]), bf_hi(o2[u][1])};
;             const f32x4 o = a1 - lam * a2; const u32x2 z = zz[u];
;             float ss = wave_sum(o[0] * o[0] + o[1] * o[1] + o[2] * o[2] + o[3] * o[3]);
;             const float rs = rsqrtf(ss * (1.f / 256.f) + RMS_EPS) * osc;
;             float y0 = o[0] * rs * gs[0] * silu(bf_lo(z[0])), y1 = o[1] * rs * gs[1] * silu(bf_hi(z[0]));
;             float y2 = o[2] * rs * gs[2] * silu(bf_lo(z[1])), y3 = o[3] * rs * gs[3] * silu(bf_hi(z[1]));
;             u32x2 w = {cvtpk(y0, y1), cvtpk(y2, y3)};
;             *reinterpret_cast<u32x2*>(mix + (long)tok * DM + (h0 + u) * 256 + lane * 4) = w;
.LBB0_124:
	s_ashr_i32 s2, s0, 3
	s_ashr_i32 s3, s2, 31
	s_lshl_b64 s[4:5], s[2:3], 12
	s_and_b32 s6, s0, 4
	v_lshl_add_u64 v[20:21], v[12:13], 0, s[4:5]
	v_lshl_add_u64 v[22:23], v[16:17], 0, s[4:5]
	s_mul_i32 s4, s2, 0x6000
	s_mul_hi_i32 s5, s2, 0x6000
	s_add_u32 s4, s54, s4
	s_addc_u32 s5, s55, s5
	s_lshl_b32 s38, s6, 9
	v_lshl_add_u64 v[20:21], v[20:21], 0, s[38:39]
	v_lshl_add_u64 v[22:23], v[22:23], 0, s[38:39]
	global_load_dwordx2 v[48:49], v[20:21], off
	global_load_dwordx2 v[50:51], v[22:23], off
	v_lshl_add_u64 v[24:25], v[0:1], 1, s[4:5]
	v_lshl_add_u64 v[24:25], v[24:25], 0, s[38:39]
	s_mov_b64 s[4:5], 0x14003000
	v_lshl_add_u64 v[34:35], v[24:25], 0, s[4:5]
	s_mov_b32 s4, 0x14003000
	v_add_co_u32_e32 v24, vcc, s4, v24
	v_xor_b32_e32 v19, 0x80000000, v9
	s_nop 0
	v_addc_co_u32_e32 v25, vcc, 0, v25, vcc
	global_load_dwordx2 v[40:41], v[24:25], off
	global_load_dwordx2 v[38:39], v[20:21], off offset:512
	global_load_dwordx2 v[36:37], v[22:23], off offset:512
	global_load_dwordx2 v[32:33], v[34:35], off offset:512
	global_load_dwordx2 v[30:31], v[20:21], off offset:1024
	global_load_dwordx2 v[28:29], v[22:23], off offset:1024
	global_load_dwordx2 v[26:27], v[34:35], off offset:1024
	global_load_dwordx2 v[24:25], v[20:21], off offset:1536
	s_nop 0
	global_load_dwordx2 v[22:23], v[22:23], off offset:1536
	s_nop 0
	global_load_dwordx2 v[20:21], v[34:35], off offset:1536
	s_lshl_b64 s[2:3], s[2:3], 13
	v_lshl_add_u64 v[34:35], v[10:11], 0, s[2:3]
	v_lshl_add_u64 v[34:35], v[34:35], 0, s[38:39]
	s_add_i32 s0, s0, s1
	s_cmp_gt_i32 s0, 0x1ffff
	s_waitcnt vmcnt(0)
	v_lshlrev_b32_e32 v52, 16, v48
	v_and_b32_e32 v53, 0xffff0000, v48
	v_lshlrev_b32_e32 v48, 16, v49
	v_and_b32_e32 v49, 0xffff0000, v49
	v_lshlrev_b32_e32 v54, 16, v50
	v_and_b32_e32 v55, 0xffff0000, v50
	v_lshlrev_b32_e32 v50, 16, v51
	v_and_b32_e32 v51, 0xffff0000, v51
	v_pk_fma_f32 v[48:49], v[18:19], v[50:51], v[48:49]
	v_pk_fma_f32 v[50:51], v[14:15], v[54:55], v[52:53] neg_lo:[1,0,0] neg_hi:[1,0,0]
	v_pk_mul_f32 v[52:53], v[48:49], v[48:49]
	v_pk_mul_f32 v[54:55], v[50:51], v[50:51]
	s_nop 0
	v_add_f32_e32 v47, v54, v55
	v_add_f32_e32 v47, v52, v47
	v_add_f32_e32 v47, v53, v47
	v_mov_b32_e32 v52, v47
	s_nop 1
	v_permlane32_swap_b32_e32 v52, v47
	s_waitcnt lgkmcnt(0)
	v_add_f32_e32 v47, v47, v52
	v_mov_b32_e32 v52, v47
	s_nop 1
	v_permlane16_swap_b32_e32 v52, v47
	s_waitcnt lgkmcnt(0)
	v_add_f32_e32 v47, v47, v52
	s_nop 1
	v_mov_b32_dpp v52, v47 row_ror:8 row_mask:0xf bank_mask:0xf
	s_waitcnt lgkmcnt(0)
	v_add_f32_e32 v47, v47, v52
	s_nop 1
	v_mov_b32_dpp v52, v47 row_shl:4 row_mask:0xf bank_mask:0x5
	v_mov_b32_dpp v52, v47 row_shr:4 row_mask:0xf bank_mask:0xa
	s_waitcnt lgkmcnt(0)
	v_add_f32_e32 v47, v47, v52
	s_nop 1
	v_mov_b32_dpp v52, v47 quad_perm:[2,3,0,1] row_mask:0xf bank_mask:0xf
	s_waitcnt lgkmcnt(0)
	v_add_f32_e32 v47, v47, v52
	s_nop 1
	v_mov_b32_dpp v52, v47 quad_perm:[1,0,3,2] row_mask:0xf bank_mask:0xf
	s_waitcnt lgkmcnt(0)
	v_add_f32_e32 v47, v47, v52
	v_fmamk_f32 v47, v47, 0x3b800000, v194
	v_cmp_gt_f32_e32 vcc, s23, v47
	v_mul_f32_e32 v52, 0x4b800000, v47
	s_nop 0
	v_cndmask_b32_e32 v47, v47, v52, vcc
	v_rsq_f32_e32 v47, v47
	s_nop 0
	v_mul_f32_e32 v52, 0x45800000, v47
	v_cndmask_b32_e32 v47, v47, v52, vcc
	v_lshlrev_b32_e32 v52, 16, v40
	v_mul_f32_e32 v53, 0xbfb8aa3b, v52
	v_exp_f32_e32 v53, v53
	v_mul_f32_e32 v47, v46, v47
	v_mul_f32_e32 v50, v50, v47
	v_mul_f32_e32 v50, v4, v50
	v_add_f32_e32 v53, 1.0, v53
	v_div_scale_f32 v54, s[2:3], v53, v53, v52
	v_rcp_f32_e32 v55, v54
	v_and_b32_e32 v40, 0xffff0000, v40
	v_mul_f32_e32 v51, v51, v47
	v_mul_f32_e32 v51, v5, v51
	v_fma_f32 v56, -v54, v55, 1.0
	v_fmac_f32_e32 v55, v56, v55
	v_div_scale_f32 v56, vcc, v52, v53, v52
	v_mul_f32_e32 v57, v56, v55
	v_fma_f32 v58, -v54, v57, v56
	v_fmac_f32_e32 v57, v58, v55
	v_fma_f32 v54, -v54, v57, v56
	v_div_fmas_f32 v54, v54, v55, v57
	v_div_fixup_f32 v52, v54, v53, v52
	v_mul_f32_e32 v50, v52, v50
	v_mul_f32_e32 v52, 0xbfb8aa3b, v40
	v_exp_f32_e32 v52, v52
	v_mul_f32_e32 v48, v48, v47
	v_mul_f32_e32 v47, v49, v47
	v_mul_f32_e32 v48, v6, v48
	v_add_f32_e32 v52, 1.0, v52
	v_div_scale_f32 v53, s[2:3], v52, v52, v40
	v_rcp_f32_e32 v54, v53
	v_mul_f32_e32 v47, v7, v47
	v_fma_f32 v55, -v53, v54, 1.0
	v_fmac_f32_e32 v54, v55, v54
	v_div_scale_f32 v55, vcc, v40, v52, v40
	v_mul_f32_e32 v56, v55, v54
	v_fma_f32 v57, -v53, v56, v55
	v_fmac_f32_e32 v56, v57, v54
	v_fma_f32 v53, -v53, v56, v55
	v_div_fmas_f32 v53, v53, v54, v56
	v_div_fixup_f32 v40, v53, v52, v40
	v_mul_f32_e32 v40, v40, v51
	v_lshlrev_b32_e32 v51, 16, v41
	v_mul_f32_e32 v52, 0xbfb8aa3b, v51
	v_exp_f32_e32 v52, v52
	v_and_b32_e32 v41, 0xffff0000, v41
	v_mul_f32_e32 v49, 0xbfb8aa3b, v41
	v_exp_f32_e32 v49, v49
	v_add_f32_e32 v52, 1.0, v52
	v_div_scale_f32 v53, s[2:3], v52, v52, v51
	v_rcp_f32_e32 v54, v53
	v_add_f32_e32 v49, 1.0, v49
	v_cvt_pk_bf16_f32 v40, v50, v40
	v_fma_f32 v55, -v53, v54, 1.0
	v_fmac_f32_e32 v54, v55, v54
	v_div_scale_f32 v55, vcc, v51, v52, v51
	v_mul_f32_e32 v56, v55, v54
	v_fma_f32 v57, -v53, v56, v55
	v_fmac_f32_e32 v56, v57, v54
	v_fma_f32 v53, -v53, v56, v55
	v_div_fmas_f32 v53, v53, v54, v56
	v_div_fixup_f32 v51, v53, v52, v51
	v_mul_f32_e32 v48, v51, v48
	v_div_scale_f32 v51, s[2:3], v49, v49, v41
	v_rcp_f32_e32 v52, v51
	s_nop 0
	v_fma_f32 v53, -v51, v52, 1.0
	v_fmac_f32_e32 v52, v53, v52
	v_div_scale_f32 v53, vcc, v41, v49, v41
	v_mul_f32_e32 v54, v53, v52
	v_fma_f32 v55, -v51, v54, v53
	v_fmac_f32_e32 v54, v55, v52
	v_fma_f32 v51, -v51, v54, v53
	v_div_fmas_f32 v51, v51, v52, v54
	v_div_fixup_f32 v41, v51, v49, v41
	v_mul_f32_e32 v41, v41, v47
	v_cvt_pk_bf16_f32 v41, v48, v41
	global_store_dwordx2 v[34:35], v[40:41], off
	v_lshlrev_b32_e32 v40, 16, v38
	v_and_b32_e32 v41, 0xffff0000, v38
	v_lshlrev_b32_e32 v38, 16, v39
	v_and_b32_e32 v39, 0xffff0000, v39
	v_lshlrev_b32_e32 v48, 16, v36
	v_and_b32_e32 v49, 0xffff0000, v36
	v_lshlrev_b32_e32 v36, 16, v37
	v_and_b32_e32 v37, 0xffff0000, v37
	v_pk_fma_f32 v[36:37], v[18:19], v[36:37], v[38:39]
	v_pk_fma_f32 v[38:39], v[14:15], v[48:49], v[40:41] neg_lo:[1,0,0] neg_hi:[1,0,0]
	v_pk_mul_f32 v[40:41], v[36:37], v[36:37]
	v_pk_mul_f32 v[48:49], v[38:39], v[38:39]
	s_nop 0
	v_add_f32_e32 v47, v48, v49
	v_add_f32_e32 v40, v40, v47
	v_add_f32_e32 v40, v41, v40
	v_mov_b32_e32 v41, v40
	s_nop 1
	v_permlane32_swap_b32_e32 v41, v40
	s_waitcnt lgkmcnt(0)
; __device__ __forceinline__ float bf_lo(unsigned u) { return __uint_as_float(u << 16); }
; __device__ __forceinline__ float bf_hi(unsigned u) { return __uint_as_float(u & 0xffff0000u); }
; __device__ __forceinline__ float silu(float z) { return z / (1.f + __expf(-z)); }
; __device__ __forceinline__ float wave_sum(float v) {
; #pragma unroll
;   for (int o = 32; o > 0; o >>= 1) v += __shfl_xor(v, o, 64);
;   return v;
; }
; __global__ __launch_bounds__(512, 2)
; void hybrid_megakernel(Params p_in) {
;     ...
;           for (int u = 0; u < 4; ++u) {
;             o1[u] = *reinterpret_cast<const u32x2*>(attB + (long)tok * 2048 + (h0 + u) * 256 + lane * 4);
;             o2[u] = *reinterpret_cast<const u32x2*>(attB + (long)NTOK * 2048 + (long)tok * 2048 + (h0 + u) * 256 + lane * 4);
;             zz[u] = *reinterpret_cast<const u32x2*>(proj + (long)tok * INC + OFF_ZD + (h0 + u) * 256 + lane * 4); }
; #pragma unroll
;           for (int u = 0; u < 4; ++u) {
;             const f32x4 a1 = {bf_lo(o1[u][0]), bf_hi(o1[u][0]), bf_lo(o1[u][1]), bf_hi(o1[u][1])};
;             const f32x4 a2 = {bf_lo(o2[u][0]), bf_hi(o2[u][0]), bf_lo(o2[u][1]), bf_hi(o2[u][1])};
;             const f32x4 o = a1 - lam * a2; const u32x2 z = zz[u];
;             float ss = wave_sum(o[0] * o[0] + o[1] * o[1] + o[2] * o[2] + o[3] * o[3]);
;             const float rs = rsqrtf(ss * (1.f / 256.f) + RMS_EPS) * osc;
;             float y0 = o[0] * rs * gs[0] * silu(bf_lo(z[0])), y1 = o[1] * rs * gs[1] * silu(bf_hi(z[0]));
;             float y2 = o[2] * rs * gs[2] * silu(bf_lo(z[1])), y3 = o[3] * rs * gs[3] * silu(bf_hi(z[1]));
;             u32x2 w = {cvtpk(y0, y1), cvtpk(y2, y3)};
;             *reinterpret_cast<u32x2*>(mix + (long)tok * DM + (h0 + u) * 256 + lane * 4) = w;
	v_add_f32_e32 v40, v40, v41
	v_mov_b32_e32 v41, v40
	s_nop 1
	v_permlane16_swap_b32_e32 v41, v40
	s_waitcnt lgkmcnt(0)
	v_add_f32_e32 v40, v40, v41
	s_nop 1
	v_mov_b32_dpp v41, v40 row_ror:8 row_mask:0xf bank_mask:0xf
	s_waitcnt lgkmcnt(0)
	v_add_f32_e32 v40, v40, v41
	s_nop 1
	v_mov_b32_dpp v41, v40 row_shl:4 row_mask:0xf bank_mask:0x5
	v_mov_b32_dpp v41, v40 row_shr:4 row_mask:0xf bank_mask:0xa
	s_waitcnt lgkmcnt(0)
	v_add_f32_e32 v40, v40, v41
	s_nop 1
	v_mov_b32_dpp v41, v40 quad_perm:[2,3,0,1] row_mask:0xf bank_mask:0xf
	s_waitcnt lgkmcnt(0)
	v_add_f32_e32 v40, v40, v41
	s_nop 1
	v_mov_b32_dpp v41, v40 quad_perm:[1,0,3,2] row_mask:0xf bank_mask:0xf
	s_waitcnt lgkmcnt(0)
	v_add_f32_e32 v40, v40, v41
	v_fmamk_f32 v40, v40, 0x3b800000, v194
	v_cmp_gt_f32_e32 vcc, s23, v40
	v_mul_f32_e32 v41, 0x4b800000, v40
	s_nop 0
	v_cndmask_b32_e32 v40, v40, v41, vcc
	v_rsq_f32_e32 v40, v40
	s_nop 0
	v_mul_f32_e32 v41, 0x45800000, v40
	v_cndmask_b32_e32 v40, v40, v41, vcc
	v_lshlrev_b32_e32 v41, 16, v32
	v_mul_f32_e32 v47, 0xbfb8aa3b, v41
	v_exp_f32_e32 v47, v47
	v_mul_f32_e32 v40, v46, v40
	v_mul_f32_e32 v38, v38, v40
	v_mul_f32_e32 v38, v4, v38
	v_add_f32_e32 v47, 1.0, v47
	v_div_scale_f32 v48, s[2:3], v47, v47, v41
	v_rcp_f32_e32 v49, v48
	v_and_b32_e32 v32, 0xffff0000, v32
	v_mul_f32_e32 v39, v39, v40
	v_mul_f32_e32 v39, v5, v39
	v_fma_f32 v50, -v48, v49, 1.0
	v_fmac_f32_e32 v49, v50, v49
	v_div_scale_f32 v50, vcc, v41, v47, v41
	v_mul_f32_e32 v51, v50, v49
	v_fma_f32 v52, -v48, v51, v50
	v_fmac_f32_e32 v51, v52, v49
	v_fma_f32 v48, -v48, v51, v50
	v_div_fmas_f32 v48, v48, v49, v51
	v_div_fixup_f32 v41, v48, v47, v41
	v_mul_f32_e32 v38, v41, v38
	v_mul_f32_e32 v41, 0xbfb8aa3b, v32
	v_exp_f32_e32 v41, v41
	v_mul_f32_e32 v36, v36, v40
	v_mul_f32_e32 v36, v6, v36
	v_mul_f32_e32 v37, v37, v40
	v_add_f32_e32 v41, 1.0, v41
	v_div_scale_f32 v47, s[2:3], v41, v41, v32
	v_rcp_f32_e32 v48, v47
	v_mul_f32_e32 v37, v7, v37
	v_fma_f32 v49, -v47, v48, 1.0
	v_fmac_f32_e32 v48, v49, v48
	v_div_scale_f32 v49, vcc, v32, v41, v32
	v_mul_f32_e32 v50, v49, v48
	v_fma_f32 v51, -v47, v50, v49
	v_fmac_f32_e32 v50, v51, v48
	v_fma_f32 v47, -v47, v50, v49
	v_div_fmas_f32 v47, v47, v48, v50
	v_div_fixup_f32 v32, v47, v41, v32
	v_mul_f32_e32 v32, v32, v39
	v_lshlrev_b32_e32 v39, 16, v33
	v_mul_f32_e32 v41, 0xbfb8aa3b, v39
	v_exp_f32_e32 v41, v41
	v_and_b32_e32 v33, 0xffff0000, v33
	v_cvt_pk_bf16_f32 v32, v38, v32
	v_add_f32_e32 v41, 1.0, v41
	v_div_scale_f32 v47, s[2:3], v41, v41, v39
	v_rcp_f32_e32 v48, v47
	s_nop 0
	v_fma_f32 v49, -v47, v48, 1.0
	v_fmac_f32_e32 v48, v49, v48
	v_div_scale_f32 v49, vcc, v39, v41, v39
	v_mul_f32_e32 v50, v49, v48
	v_fma_f32 v51, -v47, v50, v49
	v_fmac_f32_e32 v50, v51, v48
	v_fma_f32 v47, -v47, v50, v49
	v_div_fmas_f32 v47, v47, v48, v50
	v_div_fixup_f32 v39, v47, v41, v39
	v_mul_f32_e32 v36, v39, v36
	v_mul_f32_e32 v39, 0xbfb8aa3b, v33
	v_exp_f32_e32 v39, v39
	s_nop 0
	v_add_f32_e32 v39, 1.0, v39
	v_div_scale_f32 v40, s[2:3], v39, v39, v33
	v_rcp_f32_e32 v41, v40
	s_nop 0
	v_fma_f32 v47, -v40, v41, 1.0
	v_fmac_f32_e32 v41, v47, v41
	v_div_scale_f32 v47, vcc, v33, v39, v33
	v_mul_f32_e32 v48, v47, v41
	v_fma_f32 v49, -v40, v48, v47
	v_fmac_f32_e32 v48, v49, v41
	v_fma_f32 v40, -v40, v48, v47
	v_div_fmas_f32 v40, v40, v41, v48
	v_div_fixup_f32 v33, v40, v39, v33
	v_mul_f32_e32 v33, v33, v37
	v_cvt_pk_bf16_f32 v33, v36, v33
	global_store_dwordx2 v[34:35], v[32:33], off offset:512
	v_lshlrev_b32_e32 v32, 16, v30
	v_and_b32_e32 v33, 0xffff0000, v30
	v_lshlrev_b32_e32 v30, 16, v31
	v_and_b32_e32 v31, 0xffff0000, v31
	v_lshlrev_b32_e32 v36, 16, v28
	v_and_b32_e32 v37, 0xffff0000, v28
	v_lshlrev_b32_e32 v28, 16, v29
	v_and_b32_e32 v29, 0xffff0000, v29
	v_pk_fma_f32 v[28:29], v[18:19], v[28:29], v[30:31]
	v_pk_fma_f32 v[30:31], v[14:15], v[36:37], v[32:33] neg_lo:[1,0,0] neg_hi:[1,0,0]
	v_pk_mul_f32 v[32:33], v[28:29], v[28:29]
	v_pk_mul_f32 v[36:37], v[30:31], v[30:31]
	s_nop 0
	v_add_f32_e32 v36, v36, v37
	v_add_f32_e32 v32, v32, v36
	v_add_f32_e32 v32, v33, v32
	v_mov_b32_e32 v33, v32
	s_nop 1
	v_permlane32_swap_b32_e32 v33, v32
	s_waitcnt lgkmcnt(0)
	v_add_f32_e32 v32, v32, v33
	v_mov_b32_e32 v33, v32
	s_nop 1
	v_permlane16_swap_b32_e32 v33, v32
	s_waitcnt lgkmcnt(0)
	v_add_f32_e32 v32, v32, v33
	s_nop 1
	v_mov_b32_dpp v33, v32 row_ror:8 row_mask:0xf bank_mask:0xf
	s_waitcnt lgkmcnt(0)
	v_add_f32_e32 v32, v32, v33
	s_nop 1
	v_mov_b32_dpp v33, v32 row_shl:4 row_mask:0xf bank_mask:0x5
	v_mov_b32_dpp v33, v32 row_shr:4 row_mask:0xf bank_mask:0xa
	s_waitcnt lgkmcnt(0)
	v_add_f32_e32 v32, v32, v33
	s_nop 1
	v_mov_b32_dpp v33, v32 quad_perm:[2,3,0,1] row_mask:0xf bank_mask:0xf
	s_waitcnt lgkmcnt(0)
	v_add_f32_e32 v32, v32, v33
	s_nop 1
	v_mov_b32_dpp v33, v32 quad_perm:[1,0,3,2] row_mask:0xf bank_mask:0xf
	s_waitcnt lgkmcnt(0)
; __device__ __forceinline__ float bf_lo(unsigned u) { return __uint_as_float(u << 16); }
; __device__ __forceinline__ float bf_hi(unsigned u) { return __uint_as_float(u & 0xffff0000u); }
; __device__ __forceinline__ float silu(float z) { return z / (1.f + __expf(-z)); }
; __device__ __forceinline__ float wave_sum(float v) {
; #pragma unroll
;   for (int o = 32; o > 0; o >>= 1) v += __shfl_xor(v, o, 64);
;   return v;
; }
; __global__ __launch_bounds__(512, 2)
; void hybrid_megakernel(Params p_in) {
;     ...
;           for (int u = 0; u < 4; ++u) {
;             o1[u] = *reinterpret_cast<const u32x2*>(attB + (long)tok * 2048 + (h0 + u) * 256 + lane * 4);
;             o2[u] = *reinterpret_cast<const u32x2*>(attB + (long)NTOK * 2048 + (long)tok * 2048 + (h0 + u) * 256 + lane * 4);
;             zz[u] = *reinterpret_cast<const u32x2*>(proj + (long)tok * INC + OFF_ZD + (h0 + u) * 256 + lane * 4); }
; #pragma unroll
;           for (int u = 0; u < 4; ++u) {
;             const f32x4 a1 = {bf_lo(o1[u][0]), bf_hi(o1[u][0]), bf_lo(o1[u][1]), bf_hi(o1[u][1])};
;             const f32x4 a2 = {bf_lo(o2[u][0]), bf_hi(o2[u][0]), bf_lo(o2[u][1]), bf_hi(o2[u][1])};
;             const f32x4 o = a1 - lam * a2; const u32x2 z = zz[u];
;             float ss = wave_sum(o[0] * o[0] + o[1] * o[1] + o[2] * o[2] + o[3] * o[3]);
;             const float rs = rsqrtf(ss * (1.f / 256.f) + RMS_EPS) * osc;
;             float y0 = o[0] * rs * gs[0] * silu(bf_lo(z[0])), y1 = o[1] * rs * gs[1] * silu(bf_hi(z[0]));
;             float y2 = o[2] * rs * gs[2] * silu(bf_lo(z[1])), y3 = o[3] * rs * gs[3] * silu(bf_hi(z[1]));
;             u32x2 w = {cvtpk(y0, y1), cvtpk(y2, y3)};
;             *reinterpret_cast<u32x2*>(mix + (long)tok * DM + (h0 + u) * 256 + lane * 4) = w;
	v_add_f32_e32 v32, v32, v33
	v_fmamk_f32 v32, v32, 0x3b800000, v194
	v_cmp_gt_f32_e32 vcc, s23, v32
	v_mul_f32_e32 v33, 0x4b800000, v32
	s_nop 0
	v_cndmask_b32_e32 v32, v32, v33, vcc
	v_rsq_f32_e32 v32, v32
	s_nop 0
	v_mul_f32_e32 v33, 0x45800000, v32
	v_cndmask_b32_e32 v32, v32, v33, vcc
	v_lshlrev_b32_e32 v33, 16, v26
	v_mul_f32_e32 v36, 0xbfb8aa3b, v33
	v_exp_f32_e32 v36, v36
	v_mul_f32_e32 v32, v46, v32
	v_mul_f32_e32 v30, v30, v32
	v_mul_f32_e32 v30, v4, v30
	v_add_f32_e32 v36, 1.0, v36
	v_div_scale_f32 v37, s[2:3], v36, v36, v33
	v_rcp_f32_e32 v38, v37
	v_and_b32_e32 v26, 0xffff0000, v26
	v_mul_f32_e32 v31, v31, v32
	v_mul_f32_e32 v31, v5, v31
	v_fma_f32 v39, -v37, v38, 1.0
	v_fmac_f32_e32 v38, v39, v38
	v_div_scale_f32 v39, vcc, v33, v36, v33
	v_mul_f32_e32 v40, v39, v38
	v_fma_f32 v41, -v37, v40, v39
	v_fmac_f32_e32 v40, v41, v38
	v_fma_f32 v37, -v37, v40, v39
	v_div_fmas_f32 v37, v37, v38, v40
	v_div_fixup_f32 v33, v37, v36, v33
	v_mul_f32_e32 v30, v33, v30
	v_mul_f32_e32 v33, 0xbfb8aa3b, v26
	v_exp_f32_e32 v33, v33
	v_mul_f32_e32 v28, v28, v32
	v_mul_f32_e32 v28, v6, v28
	v_mul_f32_e32 v29, v29, v32
	v_add_f32_e32 v33, 1.0, v33
	v_div_scale_f32 v36, s[2:3], v33, v33, v26
	v_rcp_f32_e32 v37, v36
	v_mul_f32_e32 v29, v7, v29
	v_fma_f32 v38, -v36, v37, 1.0
	v_fmac_f32_e32 v37, v38, v37
	v_div_scale_f32 v38, vcc, v26, v33, v26
	v_mul_f32_e32 v39, v38, v37
	v_fma_f32 v40, -v36, v39, v38
	v_fmac_f32_e32 v39, v40, v37
	v_fma_f32 v36, -v36, v39, v38
	v_div_fmas_f32 v36, v36, v37, v39
	v_div_fixup_f32 v26, v36, v33, v26
	v_mul_f32_e32 v26, v26, v31
	v_lshlrev_b32_e32 v31, 16, v27
	v_mul_f32_e32 v33, 0xbfb8aa3b, v31
	v_exp_f32_e32 v33, v33
	v_and_b32_e32 v27, 0xffff0000, v27
	v_cvt_pk_bf16_f32 v26, v30, v26
	v_add_f32_e32 v33, 1.0, v33
	v_div_scale_f32 v36, s[2:3], v33, v33, v31
	v_rcp_f32_e32 v37, v36
	s_nop 0
	v_fma_f32 v38, -v36, v37, 1.0
	v_fmac_f32_e32 v37, v38, v37
	v_div_scale_f32 v38, vcc, v31, v33, v31
	v_mul_f32_e32 v39, v38, v37
	v_fma_f32 v40, -v36, v39, v38
	v_fmac_f32_e32 v39, v40, v37
	v_fma_f32 v36, -v36, v39, v38
	v_div_fmas_f32 v36, v36, v37, v39
	v_div_fixup_f32 v31, v36, v33, v31
	v_mul_f32_e32 v28, v31, v28
	v_mul_f32_e32 v31, 0xbfb8aa3b, v27
	v_exp_f32_e32 v31, v31
	s_nop 0
	v_add_f32_e32 v31, 1.0, v31
	v_div_scale_f32 v32, s[2:3], v31, v31, v27
	v_rcp_f32_e32 v33, v32
	s_nop 0
	v_fma_f32 v36, -v32, v33, 1.0
	v_fmac_f32_e32 v33, v36, v33
	v_div_scale_f32 v36, vcc, v27, v31, v27
	v_mul_f32_e32 v37, v36, v33
	v_fma_f32 v38, -v32, v37, v36
	v_fmac_f32_e32 v37, v38, v33
	v_fma_f32 v32, -v32, v37, v36
	v_div_fmas_f32 v32, v32, v33, v37
	v_div_fixup_f32 v27, v32, v31, v27
	v_mul_f32_e32 v27, v27, v29
	v_cvt_pk_bf16_f32 v27, v28, v27
	global_store_dwordx2 v[34:35], v[26:27], off offset:1024
	v_lshlrev_b32_e32 v26, 16, v24
	v_and_b32_e32 v27, 0xffff0000, v24
	v_lshlrev_b32_e32 v24, 16, v25
	v_and_b32_e32 v25, 0xffff0000, v25
	v_lshlrev_b32_e32 v28, 16, v22
	v_and_b32_e32 v29, 0xffff0000, v22
	v_lshlrev_b32_e32 v22, 16, v23
	v_and_b32_e32 v23, 0xffff0000, v23
	v_pk_fma_f32 v[22:23], v[18:19], v[22:23], v[24:25]
	v_pk_fma_f32 v[24:25], v[14:15], v[28:29], v[26:27] neg_lo:[1,0,0] neg_hi:[1,0,0]
	v_pk_mul_f32 v[26:27], v[22:23], v[22:23]
	v_pk_mul_f32 v[28:29], v[24:25], v[24:25]
	s_nop 0
	v_add_f32_e32 v19, v28, v29
	v_add_f32_e32 v19, v26, v19
	v_add_f32_e32 v19, v27, v19
	v_mov_b32_e32 v26, v19
	s_nop 1
	v_permlane32_swap_b32_e32 v26, v19
	s_waitcnt lgkmcnt(0)
	v_add_f32_e32 v19, v19, v26
	v_mov_b32_e32 v26, v19
	s_nop 1
	v_permlane16_swap_b32_e32 v26, v19
	s_waitcnt lgkmcnt(0)
	v_add_f32_e32 v19, v19, v26
	s_nop 1
	v_mov_b32_dpp v26, v19 row_ror:8 row_mask:0xf bank_mask:0xf
	s_waitcnt lgkmcnt(0)
	v_add_f32_e32 v19, v19, v26
	s_nop 1
	v_mov_b32_dpp v26, v19 row_shl:4 row_mask:0xf bank_mask:0x5
	v_mov_b32_dpp v26, v19 row_shr:4 row_mask:0xf bank_mask:0xa
	s_waitcnt lgkmcnt(0)
	v_add_f32_e32 v19, v19, v26
	s_nop 1
	v_mov_b32_dpp v26, v19 quad_perm:[2,3,0,1] row_mask:0xf bank_mask:0xf
	s_waitcnt lgkmcnt(0)
	v_add_f32_e32 v19, v19, v26
	s_nop 1
	v_mov_b32_dpp v26, v19 quad_perm:[1,0,3,2] row_mask:0xf bank_mask:0xf
	s_waitcnt lgkmcnt(0)
	v_add_f32_e32 v19, v19, v26
	v_fmamk_f32 v19, v19, 0x3b800000, v194
	v_cmp_gt_f32_e32 vcc, s23, v19
	v_mul_f32_e32 v26, 0x4b800000, v19
	s_nop 0
	v_cndmask_b32_e32 v19, v19, v26, vcc
	v_rsq_f32_e32 v19, v19
	s_nop 0
	v_mul_f32_e32 v26, 0x45800000, v19
	v_cndmask_b32_e32 v19, v19, v26, vcc
	v_lshlrev_b32_e32 v26, 16, v20
	v_mul_f32_e32 v27, 0xbfb8aa3b, v26
	v_exp_f32_e32 v27, v27
	v_mul_f32_e32 v19, v46, v19
	v_mul_f32_e32 v24, v24, v19
	v_mul_f32_e32 v24, v4, v24
	v_add_f32_e32 v27, 1.0, v27
	v_div_scale_f32 v28, s[2:3], v27, v27, v26
	v_rcp_f32_e32 v29, v28
	v_and_b32_e32 v20, 0xffff0000, v20
	v_mul_f32_e32 v25, v25, v19
	v_mul_f32_e32 v25, v5, v25
	v_fma_f32 v30, -v28, v29, 1.0
	v_fmac_f32_e32 v29, v30, v29
	v_div_scale_f32 v30, vcc, v26, v27, v26
	v_mul_f32_e32 v31, v30, v29
	v_fma_f32 v32, -v28, v31, v30
	v_fmac_f32_e32 v31, v32, v29
	v_fma_f32 v28, -v28, v31, v30
	v_div_fmas_f32 v28, v28, v29, v31
	v_div_fixup_f32 v26, v28, v27, v26
	v_mul_f32_e32 v24, v26, v24
	v_mul_f32_e32 v26, 0xbfb8aa3b, v20
	v_exp_f32_e32 v26, v26
	v_mul_f32_e32 v22, v22, v19
	v_mul_f32_e32 v19, v23, v19
	v_mul_f32_e32 v22, v6, v22
	v_add_f32_e32 v26, 1.0, v26
	v_div_scale_f32 v27, s[2:3], v26, v26, v20
	v_rcp_f32_e32 v28, v27
	v_mul_f32_e32 v19, v7, v19
	v_fma_f32 v29, -v27, v28, 1.0
	v_fmac_f32_e32 v28, v29, v28
	v_div_scale_f32 v29, vcc, v20, v26, v20
	v_mul_f32_e32 v30, v29, v28
	v_fma_f32 v31, -v27, v30, v29
	v_fmac_f32_e32 v30, v31, v28
	v_fma_f32 v27, -v27, v30, v29
	v_div_fmas_f32 v27, v27, v28, v30
	v_div_fixup_f32 v20, v27, v26, v20
	v_mul_f32_e32 v20, v20, v25
	v_lshlrev_b32_e32 v25, 16, v21
	v_mul_f32_e32 v26, 0xbfb8aa3b, v25
	v_exp_f32_e32 v26, v26
	v_and_b32_e32 v21, 0xffff0000, v21
	v_mul_f32_e32 v23, 0xbfb8aa3b, v21
	v_exp_f32_e32 v23, v23
	v_add_f32_e32 v26, 1.0, v26
	v_div_scale_f32 v27, s[2:3], v26, v26, v25
	v_rcp_f32_e32 v28, v27
	v_add_f32_e32 v23, 1.0, v23
	v_cvt_pk_bf16_f32 v20, v24, v20
	v_fma_f32 v29, -v27, v28, 1.0
	v_fmac_f32_e32 v28, v29, v28
	v_div_scale_f32 v29, vcc, v25, v26, v25
	v_mul_f32_e32 v30, v29, v28
	v_fma_f32 v31, -v27, v30, v29
	v_fmac_f32_e32 v30, v31, v28
	v_fma_f32 v27, -v27, v30, v29
	v_div_fmas_f32 v27, v27, v28, v30
	v_div_fixup_f32 v25, v27, v26, v25
	v_mul_f32_e32 v22, v25, v22
	v_div_scale_f32 v25, s[2:3], v23, v23, v21
	v_rcp_f32_e32 v26, v25
	s_nop 0
	v_fma_f32 v27, -v25, v26, 1.0
	v_fmac_f32_e32 v26, v27, v26
	v_div_scale_f32 v27, vcc, v21, v23, v21
	v_mul_f32_e32 v28, v27, v26
	v_fma_f32 v29, -v25, v28, v27
	v_fmac_f32_e32 v28, v29, v26
	v_fma_f32 v25, -v25, v28, v27
	v_div_fmas_f32 v25, v25, v26, v28
	v_div_fixup_f32 v21, v25, v23, v21
	v_mul_f32_e32 v19, v21, v19
	v_cvt_pk_bf16_f32 v21, v22, v19
	global_store_dwordx2 v[34:35], v[20:21], off offset:1536
	s_cbranch_scc0 .LBB0_124

; __device__ __forceinline__ float wave_sum(float v) {
; #pragma unroll
;   for (int o = 32; o > 0; o >>= 1) v += __shfl_xor(v, o, 64);
;   return v;
; }
; __device__ __forceinline__ float wave_max(float v) {
; #pragma unroll
;   for (int o = 32; o > 0; o >>= 1) v = fmaxf(v, __shfl_xor(v, o, 64));
;   return v;
; }
; __global__ __launch_bounds__(512, 2)
; void hybrid_megakernel(Params p_in) {
;     ...
;           for (int u = 0; u < 8; ++u) sv[u] = *reinterpret_cast<const f32x4*>(scb + (long)(row0 + u) * 256 + lane * 4);
; #pragma unroll
;           for (int u = 0; u < 8; ++u) {
;             const f32x4 s = sv[u] * 0.0625f;
;             float mx = wave_max(fmaxf(fmaxf(s[0], s[1]), fmaxf(s[2], s[3])));
;             float e0 = __expf(s[0] - mx), e1 = __expf(s[1] - mx), e2 = __expf(s[2] - mx), e3 = __expf(s[3] - mx);
;             float sm = wave_sum(e0 + e1 + e2 + e3);
;             float inv = 1.f / sm;
;             u32x2 w = {cvtpk(e0 * inv, e1 * inv), cvtpk(e2 * inv, e3 * inv)};
;             *reinterpret_cast<u32x2*>(pbuf + (long)(row0 + u) * 256 + lane * 4) = w;
;           }
.LBB0_195:
	v_lshl_add_u64 v[4:5], s[54:55], 0, v[32:33]
	v_add_co_u32_e32 v6, vcc, 0x59000000, v4
	s_add_i32 s4, s4, s6
	s_nop 0
	v_addc_co_u32_e32 v7, vcc, 0, v5, vcc
	global_load_dwordx4 v[34:37], v[6:7], off
	global_load_dwordx4 v[28:31], v[6:7], off offset:1024
	global_load_dwordx4 v[24:27], v[6:7], off offset:2048
	global_load_dwordx4 v[20:23], v[6:7], off offset:3072
	v_add_co_u32_e32 v4, vcc, 0x59001000, v4
	v_lshl_add_u64 v[32:33], v[32:33], 0, s[66:67]
	s_nop 0
	v_addc_co_u32_e32 v5, vcc, 0, v5, vcc
	global_load_dwordx4 v[16:19], v[4:5], off
	global_load_dwordx4 v[12:15], v[4:5], off offset:1024
	global_load_dwordx4 v[8:11], v[4:5], off offset:2048
	s_nop 0
	global_load_dwordx4 v[4:7], v[4:5], off offset:3072
	s_cmp_gt_i32 s4, 0xffff
	s_waitcnt vmcnt(0)
	v_pk_mul_f32 v[36:37], v[36:37], s[46:47] op_sel_hi:[1,0]
	v_pk_mul_f32 v[34:35], v[34:35], s[46:47] op_sel_hi:[1,0]
	v_max_f32_e32 v43, v36, v37
	v_max3_f32 v43, v34, v35, v43
	v_mov_b32_e32 v44, v43
	s_nop 1
	v_permlane32_swap_b32_e32 v44, v43
	v_pk_mul_f32 v[30:31], v[30:31], s[46:47] op_sel_hi:[1,0]
	v_pk_mul_f32 v[28:29], v[28:29], s[46:47] op_sel_hi:[1,0]
	v_pk_mul_f32 v[26:27], v[26:27], s[46:47] op_sel_hi:[1,0]
	v_pk_mul_f32 v[24:25], v[24:25], s[46:47] op_sel_hi:[1,0]
	s_waitcnt lgkmcnt(0)
	v_max_f32_e32 v44, v44, v44
	v_max_f32_e32 v43, v43, v44
	v_mov_b32_e32 v44, v43
	s_nop 1
	v_permlane16_swap_b32_e32 v44, v43
	v_pk_mul_f32 v[22:23], v[22:23], s[46:47] op_sel_hi:[1,0]
	v_pk_mul_f32 v[20:21], v[20:21], s[46:47] op_sel_hi:[1,0]
	v_pk_mul_f32 v[18:19], v[18:19], s[46:47] op_sel_hi:[1,0]
	v_pk_mul_f32 v[16:17], v[16:17], s[46:47] op_sel_hi:[1,0]
	s_waitcnt lgkmcnt(0)
	v_max_f32_e32 v44, v44, v44
	v_max_f32_e32 v43, v43, v44
	s_nop 1
	v_mov_b32_dpp v44, v43 row_ror:8 row_mask:0xf bank_mask:0xf
	v_pk_mul_f32 v[14:15], v[14:15], s[46:47] op_sel_hi:[1,0]
	v_pk_mul_f32 v[12:13], v[12:13], s[46:47] op_sel_hi:[1,0]
	v_pk_mul_f32 v[10:11], v[10:11], s[46:47] op_sel_hi:[1,0]
	v_pk_mul_f32 v[8:9], v[8:9], s[46:47] op_sel_hi:[1,0]
	s_waitcnt lgkmcnt(0)
	v_max_f32_e32 v44, v44, v44
	v_max_f32_e32 v43, v43, v44
	s_nop 1
	v_mov_b32_dpp v44, v43 row_shl:4 row_mask:0xf bank_mask:0x5
	v_mov_b32_dpp v44, v43 row_shr:4 row_mask:0xf bank_mask:0xa
	v_pk_mul_f32 v[6:7], v[6:7], s[46:47] op_sel_hi:[1,0]
	v_pk_mul_f32 v[4:5], v[4:5], s[46:47] op_sel_hi:[1,0]
	s_waitcnt lgkmcnt(0)
	v_max_f32_e32 v44, v44, v44
	v_max_f32_e32 v43, v43, v44
	s_nop 1
	v_mov_b32_dpp v44, v43 quad_perm:[2,3,0,1] row_mask:0xf bank_mask:0xf
	s_waitcnt lgkmcnt(0)
	v_max_f32_e32 v44, v44, v44
	v_max_f32_e32 v43, v43, v44
	s_nop 1
	v_mov_b32_dpp v44, v43 quad_perm:[1,0,3,2] row_mask:0xf bank_mask:0xf
	s_waitcnt lgkmcnt(0)
	v_max_f32_e32 v44, v44, v44
	v_max_f32_e32 v43, v43, v44
	v_sub_f32_e32 v34, v34, v43
	v_sub_f32_e32 v35, v35, v43
	v_sub_f32_e32 v36, v36, v43
	v_mul_f32_e32 v34, 0x3fb8aa3b, v34
	v_mul_f32_e32 v35, 0x3fb8aa3b, v35
	v_mul_f32_e32 v36, 0x3fb8aa3b, v36
	v_exp_f32_e32 v34, v34
	v_exp_f32_e32 v35, v35
	v_exp_f32_e32 v44, v36
	v_sub_f32_e32 v36, v37, v43
	v_mul_f32_e32 v36, 0x3fb8aa3b, v36
	v_exp_f32_e32 v37, v36
	v_add_f32_e32 v36, v34, v35
	v_add_f32_e32 v36, v44, v36
	v_add_f32_e32 v36, v37, v36
	v_mov_b32_e32 v43, v36
	s_nop 1
	v_permlane32_swap_b32_e32 v43, v36
	s_waitcnt lgkmcnt(0)
	v_add_f32_e32 v36, v36, v43
	v_mov_b32_e32 v43, v36
	s_nop 1
	v_permlane16_swap_b32_e32 v43, v36
	s_waitcnt lgkmcnt(0)
	v_add_f32_e32 v36, v36, v43
	s_nop 1
	v_mov_b32_dpp v43, v36 row_ror:8 row_mask:0xf bank_mask:0xf
	s_waitcnt lgkmcnt(0)
	v_add_f32_e32 v36, v36, v43
	s_nop 1
	v_mov_b32_dpp v43, v36 row_shl:4 row_mask:0xf bank_mask:0x5
	v_mov_b32_dpp v43, v36 row_shr:4 row_mask:0xf bank_mask:0xa
	s_waitcnt lgkmcnt(0)
	v_add_f32_e32 v36, v36, v43
	s_nop 1
	v_mov_b32_dpp v43, v36 quad_perm:[2,3,0,1] row_mask:0xf bank_mask:0xf
	s_waitcnt lgkmcnt(0)
	v_add_f32_e32 v36, v36, v43
	s_nop 1
	v_mov_b32_dpp v43, v36 quad_perm:[1,0,3,2] row_mask:0xf bank_mask:0xf
	s_waitcnt lgkmcnt(0)
	v_add_f32_e32 v36, v36, v43
	v_div_scale_f32 v43, s[0:1], v36, v36, 1.0
	v_rcp_f32_e32 v45, v43
	s_mov_b32 s0, 0x5d000000
	v_fma_f32 v46, -v43, v45, 1.0
	v_fmac_f32_e32 v45, v46, v45
	v_div_scale_f32 v46, vcc, 1.0, v36, 1.0
	v_mul_f32_e32 v47, v46, v45
	v_fma_f32 v48, -v43, v47, v46
	v_fmac_f32_e32 v47, v48, v45
	v_fma_f32 v43, -v43, v47, v46
	v_div_fmas_f32 v43, v43, v45, v47
	v_div_fixup_f32 v43, v43, v36, 1.0
	v_mul_f32_e32 v34, v34, v43
	v_mul_f32_e32 v35, v35, v43
	v_cvt_pk_bf16_f32 v36, v34, v35
	v_mul_f32_e32 v34, v44, v43
	v_mul_f32_e32 v35, v37, v43
	v_cvt_pk_bf16_f32 v37, v34, v35
	v_lshl_add_u64 v[34:35], s[54:55], 0, v[0:1]
	v_add_co_u32_e32 v34, vcc, s0, v34
	v_lshl_add_u64 v[0:1], v[0:1], 0, s[8:9]
	s_nop 0
	v_addc_co_u32_e32 v35, vcc, 0, v35, vcc
	global_store_dwordx2 v[34:35], v[36:37], off
	v_max_f32_e32 v36, v30, v31
	v_max3_f32 v36, v28, v29, v36
	v_mov_b32_e32 v37, v36
	s_nop 1
	v_permlane32_swap_b32_e32 v37, v36
	s_waitcnt lgkmcnt(0)
	v_max_f32_e32 v37, v37, v37
	v_max_f32_e32 v36, v36, v37
	v_mov_b32_e32 v37, v36
	s_nop 1
	v_permlane16_swap_b32_e32 v37, v36
	s_waitcnt lgkmcnt(0)
	v_max_f32_e32 v37, v37, v37
	v_max_f32_e32 v36, v36, v37
	s_nop 1
	v_mov_b32_dpp v37, v36 row_ror:8 row_mask:0xf bank_mask:0xf
	s_waitcnt lgkmcnt(0)
	v_max_f32_e32 v37, v37, v37
	v_max_f32_e32 v36, v36, v37
	s_nop 1
	v_mov_b32_dpp v37, v36 row_shl:4 row_mask:0xf bank_mask:0x5
	v_mov_b32_dpp v37, v36 row_shr:4 row_mask:0xf bank_mask:0xa
	s_waitcnt lgkmcnt(0)
	v_max_f32_e32 v37, v37, v37
	v_max_f32_e32 v36, v36, v37
	s_nop 1
	v_mov_b32_dpp v37, v36 quad_perm:[2,3,0,1] row_mask:0xf bank_mask:0xf
	s_waitcnt lgkmcnt(0)
; __device__ __forceinline__ float wave_sum(float v) {
; #pragma unroll
;   for (int o = 32; o > 0; o >>= 1) v += __shfl_xor(v, o, 64);
;   return v;
; }
; __device__ __forceinline__ float wave_max(float v) {
; #pragma unroll
;   for (int o = 32; o > 0; o >>= 1) v = fmaxf(v, __shfl_xor(v, o, 64));
;   return v;
; }
; __global__ __launch_bounds__(512, 2)
; void hybrid_megakernel(Params p_in) {
;     ...
;           for (int u = 0; u < 8; ++u) sv[u] = *reinterpret_cast<const f32x4*>(scb + (long)(row0 + u) * 256 + lane * 4);
; #pragma unroll
;           for (int u = 0; u < 8; ++u) {
;             const f32x4 s = sv[u] * 0.0625f;
;             float mx = wave_max(fmaxf(fmaxf(s[0], s[1]), fmaxf(s[2], s[3])));
;             float e0 = __expf(s[0] - mx), e1 = __expf(s[1] - mx), e2 = __expf(s[2] - mx), e3 = __expf(s[3] - mx);
;             float sm = wave_sum(e0 + e1 + e2 + e3);
;             float inv = 1.f / sm;
;             u32x2 w = {cvtpk(e0 * inv, e1 * inv), cvtpk(e2 * inv, e3 * inv)};
;             *reinterpret_cast<u32x2*>(pbuf + (long)(row0 + u) * 256 + lane * 4) = w;
;           }
	v_max_f32_e32 v37, v37, v37
	v_max_f32_e32 v36, v36, v37
	s_nop 1
	v_mov_b32_dpp v37, v36 quad_perm:[1,0,3,2] row_mask:0xf bank_mask:0xf
	s_waitcnt lgkmcnt(0)
	v_max_f32_e32 v37, v37, v37
	v_max_f32_e32 v36, v36, v37
	v_sub_f32_e32 v28, v28, v36
	v_sub_f32_e32 v29, v29, v36
	v_mul_f32_e32 v28, 0x3fb8aa3b, v28
	v_mul_f32_e32 v29, 0x3fb8aa3b, v29
	v_sub_f32_e32 v30, v30, v36
	v_exp_f32_e32 v28, v28
	v_exp_f32_e32 v29, v29
	v_mul_f32_e32 v30, 0x3fb8aa3b, v30
	v_sub_f32_e32 v31, v31, v36
	v_exp_f32_e32 v30, v30
	v_mul_f32_e32 v31, 0x3fb8aa3b, v31
	v_exp_f32_e32 v31, v31
	v_add_f32_e32 v36, v28, v29
	v_add_f32_e32 v36, v30, v36
	v_add_f32_e32 v36, v31, v36
	v_mov_b32_e32 v37, v36
	s_nop 1
	v_permlane32_swap_b32_e32 v37, v36
	s_waitcnt lgkmcnt(0)
	v_add_f32_e32 v36, v36, v37
	v_mov_b32_e32 v37, v36
	s_nop 1
	v_permlane16_swap_b32_e32 v37, v36
	s_waitcnt lgkmcnt(0)
	v_add_f32_e32 v36, v36, v37
	s_nop 1
	v_mov_b32_dpp v37, v36 row_ror:8 row_mask:0xf bank_mask:0xf
	s_waitcnt lgkmcnt(0)
	v_add_f32_e32 v36, v36, v37
	s_nop 1
	v_mov_b32_dpp v37, v36 row_shl:4 row_mask:0xf bank_mask:0x5
	v_mov_b32_dpp v37, v36 row_shr:4 row_mask:0xf bank_mask:0xa
	s_waitcnt lgkmcnt(0)
	v_add_f32_e32 v36, v36, v37
	s_nop 1
	v_mov_b32_dpp v37, v36 quad_perm:[2,3,0,1] row_mask:0xf bank_mask:0xf
	s_waitcnt lgkmcnt(0)
	v_add_f32_e32 v36, v36, v37
	s_nop 1
	v_mov_b32_dpp v37, v36 quad_perm:[1,0,3,2] row_mask:0xf bank_mask:0xf
	s_waitcnt lgkmcnt(0)
	v_add_f32_e32 v36, v36, v37
	v_div_scale_f32 v37, s[0:1], v36, v36, 1.0
	v_rcp_f32_e32 v43, v37
	s_nop 0
	v_fma_f32 v44, -v37, v43, 1.0
	v_fmac_f32_e32 v43, v44, v43
	v_div_scale_f32 v44, vcc, 1.0, v36, 1.0
	v_mul_f32_e32 v45, v44, v43
	v_fma_f32 v46, -v37, v45, v44
	v_fmac_f32_e32 v45, v46, v43
	v_fma_f32 v37, -v37, v45, v44
	v_div_fmas_f32 v37, v37, v43, v45
	v_div_fixup_f32 v36, v37, v36, 1.0
	v_mul_f32_e32 v28, v28, v36
	v_mul_f32_e32 v29, v29, v36
	v_cvt_pk_bf16_f32 v28, v28, v29
	v_mul_f32_e32 v29, v30, v36
	v_mul_f32_e32 v30, v31, v36
	v_cvt_pk_bf16_f32 v29, v29, v30
	global_store_dwordx2 v[34:35], v[28:29], off offset:512
	v_max_f32_e32 v28, v26, v27
	v_max3_f32 v28, v24, v25, v28
	v_mov_b32_e32 v29, v28
	s_nop 1
	v_permlane32_swap_b32_e32 v29, v28
	s_waitcnt lgkmcnt(0)
	v_max_f32_e32 v29, v29, v29
	v_max_f32_e32 v28, v28, v29
	v_mov_b32_e32 v29, v28
	s_nop 1
	v_permlane16_swap_b32_e32 v29, v28
	s_waitcnt lgkmcnt(0)
	v_max_f32_e32 v29, v29, v29
	v_max_f32_e32 v28, v28, v29
	s_nop 1
	v_mov_b32_dpp v29, v28 row_ror:8 row_mask:0xf bank_mask:0xf
	s_waitcnt lgkmcnt(0)
	v_max_f32_e32 v29, v29, v29
	v_max_f32_e32 v28, v28, v29
	s_nop 1
	v_mov_b32_dpp v29, v28 row_shl:4 row_mask:0xf bank_mask:0x5
	v_mov_b32_dpp v29, v28 row_shr:4 row_mask:0xf bank_mask:0xa
	s_waitcnt lgkmcnt(0)
	v_max_f32_e32 v29, v29, v29
	v_max_f32_e32 v28, v28, v29
	s_nop 1
	v_mov_b32_dpp v29, v28 quad_perm:[2,3,0,1] row_mask:0xf bank_mask:0xf
	s_waitcnt lgkmcnt(0)
	v_max_f32_e32 v29, v29, v29
	v_max_f32_e32 v28, v28, v29
	s_nop 1
	v_mov_b32_dpp v29, v28 quad_perm:[1,0,3,2] row_mask:0xf bank_mask:0xf
	s_waitcnt lgkmcnt(0)
	v_max_f32_e32 v29, v29, v29
	v_max_f32_e32 v28, v28, v29
	v_sub_f32_e32 v24, v24, v28
	v_sub_f32_e32 v25, v25, v28
	v_mul_f32_e32 v24, 0x3fb8aa3b, v24
	v_mul_f32_e32 v25, 0x3fb8aa3b, v25
	v_sub_f32_e32 v26, v26, v28
	v_exp_f32_e32 v24, v24
	v_exp_f32_e32 v25, v25
	v_mul_f32_e32 v26, 0x3fb8aa3b, v26
	v_sub_f32_e32 v27, v27, v28
	v_exp_f32_e32 v26, v26
	v_mul_f32_e32 v27, 0x3fb8aa3b, v27
	v_exp_f32_e32 v27, v27
	v_add_f32_e32 v28, v24, v25
	v_add_f32_e32 v28, v26, v28
	v_add_f32_e32 v28, v27, v28
	v_mov_b32_e32 v29, v28
	s_nop 1
	v_permlane32_swap_b32_e32 v29, v28
	s_waitcnt lgkmcnt(0)
	v_add_f32_e32 v28, v28, v29
	v_mov_b32_e32 v29, v28
	s_nop 1
	v_permlane16_swap_b32_e32 v29, v28
	s_waitcnt lgkmcnt(0)
	v_add_f32_e32 v28, v28, v29
	s_nop 1
	v_mov_b32_dpp v29, v28 row_ror:8 row_mask:0xf bank_mask:0xf
	s_waitcnt lgkmcnt(0)
	v_add_f32_e32 v28, v28, v29
	s_nop 1
	v_mov_b32_dpp v29, v28 row_shl:4 row_mask:0xf bank_mask:0x5
	v_mov_b32_dpp v29, v28 row_shr:4 row_mask:0xf bank_mask:0xa
	s_waitcnt lgkmcnt(0)
	v_add_f32_e32 v28, v28, v29
	s_nop 1
	v_mov_b32_dpp v29, v28 quad_perm:[2,3,0,1] row_mask:0xf bank_mask:0xf
	s_waitcnt lgkmcnt(0)
	v_add_f32_e32 v28, v28, v29
	s_nop 1
	v_mov_b32_dpp v29, v28 quad_perm:[1,0,3,2] row_mask:0xf bank_mask:0xf
	s_waitcnt lgkmcnt(0)
	v_add_f32_e32 v28, v28, v29
	v_div_scale_f32 v29, s[0:1], v28, v28, 1.0
	v_rcp_f32_e32 v30, v29
	s_nop 0
	v_fma_f32 v31, -v29, v30, 1.0
	v_fmac_f32_e32 v30, v31, v30
	v_div_scale_f32 v31, vcc, 1.0, v28, 1.0
	v_mul_f32_e32 v36, v31, v30
	v_fma_f32 v37, -v29, v36, v31
	v_fmac_f32_e32 v36, v37, v30
	v_fma_f32 v29, -v29, v36, v31
	v_div_fmas_f32 v29, v29, v30, v36
	v_div_fixup_f32 v28, v29, v28, 1.0
	v_mul_f32_e32 v24, v24, v28
	v_mul_f32_e32 v25, v25, v28
	v_cvt_pk_bf16_f32 v24, v24, v25
	v_mul_f32_e32 v25, v26, v28
	v_mul_f32_e32 v26, v27, v28
	v_cvt_pk_bf16_f32 v25, v25, v26
	global_store_dwordx2 v[34:35], v[24:25], off offset:1024
	v_max_f32_e32 v24, v22, v23
	v_max3_f32 v24, v20, v21, v24
	v_mov_b32_e32 v25, v24
	s_nop 1
	v_permlane32_swap_b32_e32 v25, v24
	s_waitcnt lgkmcnt(0)
	v_max_f32_e32 v25, v25, v25
	v_max_f32_e32 v24, v24, v25
	v_mov_b32_e32 v25, v24
	s_nop 1
	v_permlane16_swap_b32_e32 v25, v24
	s_waitcnt lgkmcnt(0)
	v_max_f32_e32 v25, v25, v25
	v_max_f32_e32 v24, v24, v25
	s_nop 1
	v_mov_b32_dpp v25, v24 row_ror:8 row_mask:0xf bank_mask:0xf
	s_waitcnt lgkmcnt(0)
	v_max_f32_e32 v25, v25, v25
	v_max_f32_e32 v24, v24, v25
	s_nop 1
	v_mov_b32_dpp v25, v24 row_shl:4 row_mask:0xf bank_mask:0x5
	v_mov_b32_dpp v25, v24 row_shr:4 row_mask:0xf bank_mask:0xa
	s_waitcnt lgkmcnt(0)
; __device__ __forceinline__ float wave_sum(float v) {
; #pragma unroll
;   for (int o = 32; o > 0; o >>= 1) v += __shfl_xor(v, o, 64);
;   return v;
; }
; __device__ __forceinline__ float wave_max(float v) {
; #pragma unroll
;   for (int o = 32; o > 0; o >>= 1) v = fmaxf(v, __shfl_xor(v, o, 64));
;   return v;
; }
; __global__ __launch_bounds__(512, 2)
; void hybrid_megakernel(Params p_in) {
;     ...
;           for (int u = 0; u < 8; ++u) sv[u] = *reinterpret_cast<const f32x4*>(scb + (long)(row0 + u) * 256 + lane * 4);
; #pragma unroll
;           for (int u = 0; u < 8; ++u) {
;             const f32x4 s = sv[u] * 0.0625f;
;             float mx = wave_max(fmaxf(fmaxf(s[0], s[1]), fmaxf(s[2], s[3])));
;             float e0 = __expf(s[0] - mx), e1 = __expf(s[1] - mx), e2 = __expf(s[2] - mx), e3 = __expf(s[3] - mx);
;             float sm = wave_sum(e0 + e1 + e2 + e3);
;             float inv = 1.f / sm;
;             u32x2 w = {cvtpk(e0 * inv, e1 * inv), cvtpk(e2 * inv, e3 * inv)};
;             *reinterpret_cast<u32x2*>(pbuf + (long)(row0 + u) * 256 + lane * 4) = w;
;           }
	v_max_f32_e32 v25, v25, v25
	v_max_f32_e32 v24, v24, v25
	s_nop 1
	v_mov_b32_dpp v25, v24 quad_perm:[2,3,0,1] row_mask:0xf bank_mask:0xf
	s_waitcnt lgkmcnt(0)
	v_max_f32_e32 v25, v25, v25
	v_max_f32_e32 v24, v24, v25
	s_nop 1
	v_mov_b32_dpp v25, v24 quad_perm:[1,0,3,2] row_mask:0xf bank_mask:0xf
	s_waitcnt lgkmcnt(0)
	v_max_f32_e32 v25, v25, v25
	v_max_f32_e32 v24, v24, v25
	v_sub_f32_e32 v20, v20, v24
	v_sub_f32_e32 v21, v21, v24
	v_mul_f32_e32 v20, 0x3fb8aa3b, v20
	v_mul_f32_e32 v21, 0x3fb8aa3b, v21
	v_sub_f32_e32 v22, v22, v24
	v_exp_f32_e32 v20, v20
	v_exp_f32_e32 v21, v21
	v_mul_f32_e32 v22, 0x3fb8aa3b, v22
	v_sub_f32_e32 v23, v23, v24
	v_exp_f32_e32 v22, v22
	v_mul_f32_e32 v23, 0x3fb8aa3b, v23
	v_exp_f32_e32 v23, v23
	v_add_f32_e32 v24, v20, v21
	v_add_f32_e32 v24, v22, v24
	v_add_f32_e32 v24, v23, v24
	v_mov_b32_e32 v25, v24
	s_nop 1
	v_permlane32_swap_b32_e32 v25, v24
	s_waitcnt lgkmcnt(0)
	v_add_f32_e32 v24, v24, v25
	v_mov_b32_e32 v25, v24
	s_nop 1
	v_permlane16_swap_b32_e32 v25, v24
	s_waitcnt lgkmcnt(0)
	v_add_f32_e32 v24, v24, v25
	s_nop 1
	v_mov_b32_dpp v25, v24 row_ror:8 row_mask:0xf bank_mask:0xf
	s_waitcnt lgkmcnt(0)
	v_add_f32_e32 v24, v24, v25
	s_nop 1
	v_mov_b32_dpp v25, v24 row_shl:4 row_mask:0xf bank_mask:0x5
	v_mov_b32_dpp v25, v24 row_shr:4 row_mask:0xf bank_mask:0xa
	s_waitcnt lgkmcnt(0)
	v_add_f32_e32 v24, v24, v25
	s_nop 1
	v_mov_b32_dpp v25, v24 quad_perm:[2,3,0,1] row_mask:0xf bank_mask:0xf
	s_waitcnt lgkmcnt(0)
	v_add_f32_e32 v24, v24, v25
	s_nop 1
	v_mov_b32_dpp v25, v24 quad_perm:[1,0,3,2] row_mask:0xf bank_mask:0xf
	s_waitcnt lgkmcnt(0)
	v_add_f32_e32 v24, v24, v25
	v_div_scale_f32 v25, s[0:1], v24, v24, 1.0
	v_rcp_f32_e32 v26, v25
	s_nop 0
	v_fma_f32 v27, -v25, v26, 1.0
	v_fmac_f32_e32 v26, v27, v26
	v_div_scale_f32 v27, vcc, 1.0, v24, 1.0
	v_mul_f32_e32 v28, v27, v26
	v_fma_f32 v29, -v25, v28, v27
	v_fmac_f32_e32 v28, v29, v26
	v_fma_f32 v25, -v25, v28, v27
	v_div_fmas_f32 v25, v25, v26, v28
	v_div_fixup_f32 v24, v25, v24, 1.0
	v_mul_f32_e32 v20, v20, v24
	v_mul_f32_e32 v21, v21, v24
	v_cvt_pk_bf16_f32 v20, v20, v21
	v_mul_f32_e32 v21, v22, v24
	v_mul_f32_e32 v22, v23, v24
	v_cvt_pk_bf16_f32 v21, v21, v22
	global_store_dwordx2 v[34:35], v[20:21], off offset:1536
	v_max_f32_e32 v20, v18, v19
	v_max3_f32 v20, v16, v17, v20
	v_mov_b32_e32 v21, v20
	s_nop 1
	v_permlane32_swap_b32_e32 v21, v20
	s_waitcnt lgkmcnt(0)
	v_max_f32_e32 v21, v21, v21
	v_max_f32_e32 v20, v20, v21
	v_mov_b32_e32 v21, v20
	s_nop 1
	v_permlane16_swap_b32_e32 v21, v20
	s_waitcnt lgkmcnt(0)
	v_max_f32_e32 v21, v21, v21
	v_max_f32_e32 v20, v20, v21
	s_nop 1
	v_mov_b32_dpp v21, v20 row_ror:8 row_mask:0xf bank_mask:0xf
	s_waitcnt lgkmcnt(0)
	v_max_f32_e32 v21, v21, v21
	v_max_f32_e32 v20, v20, v21
	s_nop 1
	v_mov_b32_dpp v21, v20 row_shl:4 row_mask:0xf bank_mask:0x5
	v_mov_b32_dpp v21, v20 row_shr:4 row_mask:0xf bank_mask:0xa
	s_waitcnt lgkmcnt(0)
	v_max_f32_e32 v21, v21, v21
	v_max_f32_e32 v20, v20, v21
	s_nop 1
	v_mov_b32_dpp v21, v20 quad_perm:[2,3,0,1] row_mask:0xf bank_mask:0xf
	s_waitcnt lgkmcnt(0)
	v_max_f32_e32 v21, v21, v21
	v_max_f32_e32 v20, v20, v21
	s_nop 1
	v_mov_b32_dpp v21, v20 quad_perm:[1,0,3,2] row_mask:0xf bank_mask:0xf
	s_waitcnt lgkmcnt(0)
	v_max_f32_e32 v21, v21, v21
	v_max_f32_e32 v20, v20, v21
	v_sub_f32_e32 v16, v16, v20
	v_sub_f32_e32 v17, v17, v20
	v_mul_f32_e32 v16, 0x3fb8aa3b, v16
	v_mul_f32_e32 v17, 0x3fb8aa3b, v17
	v_sub_f32_e32 v18, v18, v20
	v_exp_f32_e32 v16, v16
	v_exp_f32_e32 v17, v17
	v_mul_f32_e32 v18, 0x3fb8aa3b, v18
	v_sub_f32_e32 v19, v19, v20
	v_exp_f32_e32 v18, v18
	v_mul_f32_e32 v19, 0x3fb8aa3b, v19
	v_exp_f32_e32 v19, v19
	v_add_f32_e32 v20, v16, v17
	v_add_f32_e32 v20, v18, v20
	v_add_f32_e32 v20, v19, v20
	v_mov_b32_e32 v21, v20
	s_nop 1
	v_permlane32_swap_b32_e32 v21, v20
	s_waitcnt lgkmcnt(0)
	v_add_f32_e32 v20, v20, v21
	v_mov_b32_e32 v21, v20
	s_nop 1
	v_permlane16_swap_b32_e32 v21, v20
	s_waitcnt lgkmcnt(0)
	v_add_f32_e32 v20, v20, v21
	s_nop 1
	v_mov_b32_dpp v21, v20 row_ror:8 row_mask:0xf bank_mask:0xf
	s_waitcnt lgkmcnt(0)
	v_add_f32_e32 v20, v20, v21
	s_nop 1
	v_mov_b32_dpp v21, v20 row_shl:4 row_mask:0xf bank_mask:0x5
	v_mov_b32_dpp v21, v20 row_shr:4 row_mask:0xf bank_mask:0xa
	s_waitcnt lgkmcnt(0)
	v_add_f32_e32 v20, v20, v21
	s_nop 1
	v_mov_b32_dpp v21, v20 quad_perm:[2,3,0,1] row_mask:0xf bank_mask:0xf
	s_waitcnt lgkmcnt(0)
	v_add_f32_e32 v20, v20, v21
	s_nop 1
	v_mov_b32_dpp v21, v20 quad_perm:[1,0,3,2] row_mask:0xf bank_mask:0xf
	s_waitcnt lgkmcnt(0)
	v_add_f32_e32 v20, v20, v21
	v_div_scale_f32 v21, s[0:1], v20, v20, 1.0
	v_rcp_f32_e32 v22, v21
	s_nop 0
	v_fma_f32 v23, -v21, v22, 1.0
	v_fmac_f32_e32 v22, v23, v22
	v_div_scale_f32 v23, vcc, 1.0, v20, 1.0
	v_mul_f32_e32 v24, v23, v22
	v_fma_f32 v25, -v21, v24, v23
	v_fmac_f32_e32 v24, v25, v22
	v_fma_f32 v21, -v21, v24, v23
	v_div_fmas_f32 v21, v21, v22, v24
	v_div_fixup_f32 v20, v21, v20, 1.0
	v_mul_f32_e32 v16, v16, v20
	v_mul_f32_e32 v17, v17, v20
	v_cvt_pk_bf16_f32 v16, v16, v17
	v_mul_f32_e32 v17, v18, v20
	v_mul_f32_e32 v18, v19, v20
	v_cvt_pk_bf16_f32 v17, v17, v18
	global_store_dwordx2 v[34:35], v[16:17], off offset:2048
	v_max_f32_e32 v16, v14, v15
	v_max3_f32 v16, v12, v13, v16
	v_mov_b32_e32 v17, v16
	s_nop 1
	v_permlane32_swap_b32_e32 v17, v16
	s_waitcnt lgkmcnt(0)
	v_max_f32_e32 v17, v17, v17
	v_max_f32_e32 v16, v16, v17
	v_mov_b32_e32 v17, v16
	s_nop 1
	v_permlane16_swap_b32_e32 v17, v16
	s_waitcnt lgkmcnt(0)
	v_max_f32_e32 v17, v17, v17
	v_max_f32_e32 v16, v16, v17
	s_nop 1
	v_mov_b32_dpp v17, v16 row_ror:8 row_mask:0xf bank_mask:0xf
	s_waitcnt lgkmcnt(0)
; __device__ __forceinline__ float wave_sum(float v) {
; #pragma unroll
;   for (int o = 32; o > 0; o >>= 1) v += __shfl_xor(v, o, 64);
;   return v;
; }
; __device__ __forceinline__ float wave_max(float v) {
; #pragma unroll
;   for (int o = 32; o > 0; o >>= 1) v = fmaxf(v, __shfl_xor(v, o, 64));
;   return v;
; }
; __global__ __launch_bounds__(512, 2)
; void hybrid_megakernel(Params p_in) {
;     ...
; #pragma unroll
;           for (int u = 0; u < 8; ++u) {
;             const f32x4 s = sv[u] * 0.0625f;
;             float mx = wave_max(fmaxf(fmaxf(s[0], s[1]), fmaxf(s[2], s[3])));
;             float e0 = __expf(s[0] - mx), e1 = __expf(s[1] - mx), e2 = __expf(s[2] - mx), e3 = __expf(s[3] - mx);
;             float sm = wave_sum(e0 + e1 + e2 + e3);
;             float inv = 1.f / sm;
;             u32x2 w = {cvtpk(e0 * inv, e1 * inv), cvtpk(e2 * inv, e3 * inv)};
;             *reinterpret_cast<u32x2*>(pbuf + (long)(row0 + u) * 256 + lane * 4) = w;
;           }
	v_max_f32_e32 v17, v17, v17
	v_max_f32_e32 v16, v16, v17
	s_nop 1
	v_mov_b32_dpp v17, v16 row_shl:4 row_mask:0xf bank_mask:0x5
	v_mov_b32_dpp v17, v16 row_shr:4 row_mask:0xf bank_mask:0xa
	s_waitcnt lgkmcnt(0)
	v_max_f32_e32 v17, v17, v17
	v_max_f32_e32 v16, v16, v17
	s_nop 1
	v_mov_b32_dpp v17, v16 quad_perm:[2,3,0,1] row_mask:0xf bank_mask:0xf
	s_waitcnt lgkmcnt(0)
	v_max_f32_e32 v17, v17, v17
	v_max_f32_e32 v16, v16, v17
	s_nop 1
	v_mov_b32_dpp v17, v16 quad_perm:[1,0,3,2] row_mask:0xf bank_mask:0xf
	s_waitcnt lgkmcnt(0)
	v_max_f32_e32 v17, v17, v17
	v_max_f32_e32 v16, v16, v17
	v_sub_f32_e32 v12, v12, v16
	v_sub_f32_e32 v13, v13, v16
	v_mul_f32_e32 v12, 0x3fb8aa3b, v12
	v_mul_f32_e32 v13, 0x3fb8aa3b, v13
	v_sub_f32_e32 v14, v14, v16
	v_exp_f32_e32 v12, v12
	v_exp_f32_e32 v13, v13
	v_mul_f32_e32 v14, 0x3fb8aa3b, v14
	v_sub_f32_e32 v15, v15, v16
	v_exp_f32_e32 v14, v14
	v_mul_f32_e32 v15, 0x3fb8aa3b, v15
	v_exp_f32_e32 v15, v15
	v_add_f32_e32 v16, v12, v13
	v_add_f32_e32 v16, v14, v16
	v_add_f32_e32 v16, v15, v16
	v_mov_b32_e32 v17, v16
	s_nop 1
	v_permlane32_swap_b32_e32 v17, v16
	s_waitcnt lgkmcnt(0)
	v_add_f32_e32 v16, v16, v17
	v_mov_b32_e32 v17, v16
	s_nop 1
	v_permlane16_swap_b32_e32 v17, v16
	s_waitcnt lgkmcnt(0)
	v_add_f32_e32 v16, v16, v17
	s_nop 1
	v_mov_b32_dpp v17, v16 row_ror:8 row_mask:0xf bank_mask:0xf
	s_waitcnt lgkmcnt(0)
	v_add_f32_e32 v16, v16, v17
	s_nop 1
	v_mov_b32_dpp v17, v16 row_shl:4 row_mask:0xf bank_mask:0x5
	v_mov_b32_dpp v17, v16 row_shr:4 row_mask:0xf bank_mask:0xa
	s_waitcnt lgkmcnt(0)
	v_add_f32_e32 v16, v16, v17
	s_nop 1
	v_mov_b32_dpp v17, v16 quad_perm:[2,3,0,1] row_mask:0xf bank_mask:0xf
	s_waitcnt lgkmcnt(0)
	v_add_f32_e32 v16, v16, v17
	s_nop 1
	v_mov_b32_dpp v17, v16 quad_perm:[1,0,3,2] row_mask:0xf bank_mask:0xf
	s_waitcnt lgkmcnt(0)
	v_add_f32_e32 v16, v16, v17
	v_div_scale_f32 v17, s[0:1], v16, v16, 1.0
	v_rcp_f32_e32 v18, v17
	s_nop 0
	v_fma_f32 v19, -v17, v18, 1.0
	v_fmac_f32_e32 v18, v19, v18
	v_div_scale_f32 v19, vcc, 1.0, v16, 1.0
	v_mul_f32_e32 v20, v19, v18
	v_fma_f32 v21, -v17, v20, v19
	v_fmac_f32_e32 v20, v21, v18
	v_fma_f32 v17, -v17, v20, v19
	v_div_fmas_f32 v17, v17, v18, v20
	v_div_fixup_f32 v16, v17, v16, 1.0
	v_mul_f32_e32 v12, v12, v16
	v_mul_f32_e32 v13, v13, v16
	v_cvt_pk_bf16_f32 v12, v12, v13
	v_mul_f32_e32 v13, v14, v16
	v_mul_f32_e32 v14, v15, v16
	v_cvt_pk_bf16_f32 v13, v13, v14
	global_store_dwordx2 v[34:35], v[12:13], off offset:2560
	v_max_f32_e32 v12, v10, v11
	v_max3_f32 v12, v8, v9, v12
	v_mov_b32_e32 v13, v12
	s_nop 1
	v_permlane32_swap_b32_e32 v13, v12
	s_waitcnt lgkmcnt(0)
	v_max_f32_e32 v13, v13, v13
	v_max_f32_e32 v12, v12, v13
	v_mov_b32_e32 v13, v12
	s_nop 1
	v_permlane16_swap_b32_e32 v13, v12
	s_waitcnt lgkmcnt(0)
	v_max_f32_e32 v13, v13, v13
	v_max_f32_e32 v12, v12, v13
	s_nop 1
	v_mov_b32_dpp v13, v12 row_ror:8 row_mask:0xf bank_mask:0xf
	s_waitcnt lgkmcnt(0)
	v_max_f32_e32 v13, v13, v13
	v_max_f32_e32 v12, v12, v13
	s_nop 1
	v_mov_b32_dpp v13, v12 row_shl:4 row_mask:0xf bank_mask:0x5
	v_mov_b32_dpp v13, v12 row_shr:4 row_mask:0xf bank_mask:0xa
	s_waitcnt lgkmcnt(0)
	v_max_f32_e32 v13, v13, v13
	v_max_f32_e32 v12, v12, v13
	s_nop 1
	v_mov_b32_dpp v13, v12 quad_perm:[2,3,0,1] row_mask:0xf bank_mask:0xf
	s_waitcnt lgkmcnt(0)
	v_max_f32_e32 v13, v13, v13
	v_max_f32_e32 v12, v12, v13
	s_nop 1
	v_mov_b32_dpp v13, v12 quad_perm:[1,0,3,2] row_mask:0xf bank_mask:0xf
	s_waitcnt lgkmcnt(0)
	v_max_f32_e32 v13, v13, v13
	v_max_f32_e32 v12, v12, v13
	v_sub_f32_e32 v8, v8, v12
	v_sub_f32_e32 v9, v9, v12
	v_mul_f32_e32 v8, 0x3fb8aa3b, v8
	v_mul_f32_e32 v9, 0x3fb8aa3b, v9
	v_sub_f32_e32 v10, v10, v12
	v_exp_f32_e32 v8, v8
	v_exp_f32_e32 v9, v9
	v_mul_f32_e32 v10, 0x3fb8aa3b, v10
	v_sub_f32_e32 v11, v11, v12
	v_exp_f32_e32 v10, v10
	v_mul_f32_e32 v11, 0x3fb8aa3b, v11
	v_exp_f32_e32 v11, v11
	v_add_f32_e32 v12, v8, v9
	v_add_f32_e32 v12, v10, v12
	v_add_f32_e32 v12, v11, v12
	v_mov_b32_e32 v13, v12
	s_nop 1
	v_permlane32_swap_b32_e32 v13, v12
	s_waitcnt lgkmcnt(0)
; __device__ __forceinline__ float wave_sum(float v) {
; #pragma unroll
;   for (int o = 32; o > 0; o >>= 1) v += __shfl_xor(v, o, 64);
;   return v;
; }
; __device__ __forceinline__ float wave_max(float v) {
; #pragma unroll
;   for (int o = 32; o > 0; o >>= 1) v = fmaxf(v, __shfl_xor(v, o, 64));
;   return v;
; }
; __global__ __launch_bounds__(512, 2)
; void hybrid_megakernel(Params p_in) {
;     ...
; #pragma unroll
;           for (int u = 0; u < 8; ++u) {
;             const f32x4 s = sv[u] * 0.0625f;
;             float mx = wave_max(fmaxf(fmaxf(s[0], s[1]), fmaxf(s[2], s[3])));
;             float e0 = __expf(s[0] - mx), e1 = __expf(s[1] - mx), e2 = __expf(s[2] - mx), e3 = __expf(s[3] - mx);
;             float sm = wave_sum(e0 + e1 + e2 + e3);
;             float inv = 1.f / sm;
;             u32x2 w = {cvtpk(e0 * inv, e1 * inv), cvtpk(e2 * inv, e3 * inv)};
;             *reinterpret_cast<u32x2*>(pbuf + (long)(row0 + u) * 256 + lane * 4) = w;
;           }
	v_add_f32_e32 v12, v12, v13
	v_mov_b32_e32 v13, v12
	s_nop 1
	v_permlane16_swap_b32_e32 v13, v12
	s_waitcnt lgkmcnt(0)
	v_add_f32_e32 v12, v12, v13
	s_nop 1
	v_mov_b32_dpp v13, v12 row_ror:8 row_mask:0xf bank_mask:0xf
	s_waitcnt lgkmcnt(0)
	v_add_f32_e32 v12, v12, v13
	s_nop 1
	v_mov_b32_dpp v13, v12 row_shl:4 row_mask:0xf bank_mask:0x5
	v_mov_b32_dpp v13, v12 row_shr:4 row_mask:0xf bank_mask:0xa
	s_waitcnt lgkmcnt(0)
	v_add_f32_e32 v12, v12, v13
	s_nop 1
	v_mov_b32_dpp v13, v12 quad_perm:[2,3,0,1] row_mask:0xf bank_mask:0xf
	s_waitcnt lgkmcnt(0)
	v_add_f32_e32 v12, v12, v13
	s_nop 1
	v_mov_b32_dpp v13, v12 quad_perm:[1,0,3,2] row_mask:0xf bank_mask:0xf
	s_waitcnt lgkmcnt(0)
	v_add_f32_e32 v12, v12, v13
	v_div_scale_f32 v13, s[0:1], v12, v12, 1.0
	v_rcp_f32_e32 v14, v13
	s_nop 0
	v_fma_f32 v15, -v13, v14, 1.0
	v_fmac_f32_e32 v14, v15, v14
	v_div_scale_f32 v15, vcc, 1.0, v12, 1.0
	v_mul_f32_e32 v16, v15, v14
	v_fma_f32 v17, -v13, v16, v15
	v_fmac_f32_e32 v16, v17, v14
	v_fma_f32 v13, -v13, v16, v15
	v_div_fmas_f32 v13, v13, v14, v16
	v_div_fixup_f32 v12, v13, v12, 1.0
	v_mul_f32_e32 v8, v8, v12
	v_mul_f32_e32 v9, v9, v12
	v_cvt_pk_bf16_f32 v8, v8, v9
	v_mul_f32_e32 v9, v10, v12
	v_mul_f32_e32 v10, v11, v12
	v_cvt_pk_bf16_f32 v9, v9, v10
	global_store_dwordx2 v[34:35], v[8:9], off offset:3072
	v_max_f32_e32 v8, v6, v7
	v_max3_f32 v8, v4, v5, v8
	v_mov_b32_e32 v9, v8
	s_nop 1
	v_permlane32_swap_b32_e32 v9, v8
	s_waitcnt lgkmcnt(0)
	v_max_f32_e32 v9, v9, v9
	v_max_f32_e32 v8, v8, v9
	v_mov_b32_e32 v9, v8
	s_nop 1
	v_permlane16_swap_b32_e32 v9, v8
	s_waitcnt lgkmcnt(0)
	v_max_f32_e32 v9, v9, v9
	v_max_f32_e32 v8, v8, v9
	s_nop 1
	v_mov_b32_dpp v9, v8 row_ror:8 row_mask:0xf bank_mask:0xf
	s_waitcnt lgkmcnt(0)
	v_max_f32_e32 v9, v9, v9
	v_max_f32_e32 v8, v8, v9
	s_nop 1
	v_mov_b32_dpp v9, v8 row_shl:4 row_mask:0xf bank_mask:0x5
	v_mov_b32_dpp v9, v8 row_shr:4 row_mask:0xf bank_mask:0xa
	s_waitcnt lgkmcnt(0)
	v_max_f32_e32 v9, v9, v9
	v_max_f32_e32 v8, v8, v9
	s_nop 1
	v_mov_b32_dpp v9, v8 quad_perm:[2,3,0,1] row_mask:0xf bank_mask:0xf
	s_waitcnt lgkmcnt(0)
	v_max_f32_e32 v9, v9, v9
	v_max_f32_e32 v8, v8, v9
	s_nop 1
	v_mov_b32_dpp v9, v8 quad_perm:[1,0,3,2] row_mask:0xf bank_mask:0xf
	s_waitcnt lgkmcnt(0)
	v_max_f32_e32 v9, v9, v9
	v_max_f32_e32 v8, v8, v9
	v_sub_f32_e32 v4, v4, v8
	v_sub_f32_e32 v5, v5, v8
	v_mul_f32_e32 v4, 0x3fb8aa3b, v4
	v_mul_f32_e32 v5, 0x3fb8aa3b, v5
	v_sub_f32_e32 v6, v6, v8
	v_exp_f32_e32 v4, v4
	v_exp_f32_e32 v5, v5
	v_mul_f32_e32 v6, 0x3fb8aa3b, v6
	v_sub_f32_e32 v7, v7, v8
	v_exp_f32_e32 v6, v6
	v_mul_f32_e32 v7, 0x3fb8aa3b, v7
	v_exp_f32_e32 v7, v7
	v_add_f32_e32 v8, v4, v5
	v_add_f32_e32 v8, v6, v8
	v_add_f32_e32 v8, v7, v8
	v_mov_b32_e32 v9, v8
	s_nop 1
	v_permlane32_swap_b32_e32 v9, v8
	s_waitcnt lgkmcnt(0)
	v_add_f32_e32 v8, v8, v9
	v_mov_b32_e32 v9, v8
	s_nop 1
	v_permlane16_swap_b32_e32 v9, v8
	s_waitcnt lgkmcnt(0)
	v_add_f32_e32 v8, v8, v9
	s_nop 1
	v_mov_b32_dpp v9, v8 row_ror:8 row_mask:0xf bank_mask:0xf
	s_waitcnt lgkmcnt(0)
	v_add_f32_e32 v8, v8, v9
	s_nop 1
	v_mov_b32_dpp v9, v8 row_shl:4 row_mask:0xf bank_mask:0x5
	v_mov_b32_dpp v9, v8 row_shr:4 row_mask:0xf bank_mask:0xa
	s_waitcnt lgkmcnt(0)
	v_add_f32_e32 v8, v8, v9
	s_nop 1
	v_mov_b32_dpp v9, v8 quad_perm:[2,3,0,1] row_mask:0xf bank_mask:0xf
	s_waitcnt lgkmcnt(0)
	v_add_f32_e32 v8, v8, v9
	s_nop 1
	v_mov_b32_dpp v9, v8 quad_perm:[1,0,3,2] row_mask:0xf bank_mask:0xf
	s_waitcnt lgkmcnt(0)
	v_add_f32_e32 v8, v8, v9
	v_div_scale_f32 v9, s[0:1], v8, v8, 1.0
	v_rcp_f32_e32 v10, v9
	s_nop 0
	v_fma_f32 v11, -v9, v10, 1.0
	v_fmac_f32_e32 v10, v11, v10
	v_div_scale_f32 v11, vcc, 1.0, v8, 1.0
	v_mul_f32_e32 v12, v11, v10
	v_fma_f32 v13, -v9, v12, v11
	v_fmac_f32_e32 v12, v13, v10
	v_fma_f32 v9, -v9, v12, v11
	v_div_fmas_f32 v9, v9, v10, v12
	v_div_fixup_f32 v8, v9, v8, 1.0
	v_mul_f32_e32 v4, v4, v8
	v_mul_f32_e32 v5, v5, v8
	v_cvt_pk_bf16_f32 v4, v4, v5
	v_mul_f32_e32 v5, v6, v8
	v_mul_f32_e32 v6, v7, v8
	v_cvt_pk_bf16_f32 v5, v5, v6
	global_store_dwordx2 v[34:35], v[4:5], off offset:3584
	s_cbranch_scc0 .LBB0_195

; __device__ __forceinline__ float bf_lo(unsigned u) { return __uint_as_float(u << 16); }
; __device__ __forceinline__ float bf_hi(unsigned u) { return __uint_as_float(u & 0xffff0000u); }
; __global__ __launch_bounds__(512, 2)
; void hybrid_megakernel(Params p_in) {
;     ...
;         for (int i = bid * 512 + tid; i < 2048 * 2 * 512; i += G * 512) {
;           const int n = i >> 10, part = (i >> 9) & 1, s0 = (i & 511) * 8;
;           const bf16* row = ztp + (long)n * (2 * SEQ) + part * SEQ;
;           const u32x4 own = *reinterpret_cast<const u32x4*>(row + s0);
;           const u32x4 c1 = *reinterpret_cast<const u32x4*>(row + SEQ - s0 - 8);
;           const unsigned c2 = (s0 > 0) ? *reinterpret_cast<const unsigned*>(row + SEQ - s0) : 0u;
;           float o[8], m[8];
; #pragma unroll
;           for (int q = 0; q < 4; ++q) { o[2 * q] = bf_lo(own[q]); o[2 * q + 1] = bf_hi(own[q]); }
;           m[0] = bf_lo(c2);
;           m[1] = bf_hi(c1[3]); m[2] = bf_lo(c1[3]); m[3] = bf_hi(c1[2]); m[4] = bf_lo(c1[2]);
;           m[5] = bf_hi(c1[1]); m[6] = bf_lo(c1[1]); m[7] = bf_hi(c1[0]);
;           if (s0 == 0) m[0] = part ? o[0] : 0.f;
;           float r[8];
; #pragma unroll
;           for (int q = 0; q < 8; ++q) r[q] = part ? o[q] - m[q] : o[q] + m[q];
;           u32x4 w = {cvtpk(r[0], r[1]), cvtpk(r[2], r[3]), cvtpk(r[4], r[5]), cvtpk(r[6], r[7])};
;           *reinterpret_cast<u32x4*>(z2 + (long)n * SEQ + part * (SEQ / 2) + s0) = w;
;         }
.LBB0_197:
	s_andn2_b64 vcc, exec, s[0:1]
	s_cbranch_vccnz .LBB0_206
	s_cmp_lg_u32 s53, 2
	s_cbranch_scc1 .LBB0_206
	v_readlane_b32 s0, v255, 21
	v_readlane_b32 s1, v255, 22
	s_waitcnt lgkmcnt(0)
	v_lshl_add_u32 v14, s0, 9, v144
	s_mov_b32 s0, 0x200000
	v_cmp_gt_i32_e32 vcc, s0, v14
	s_and_saveexec_b64 s[0:1], vcc
	s_cbranch_execz .LBB0_205
	s_add_u32 s2, s54, 0x4c000000
	s_addc_u32 s3, s55, 0
	s_add_u32 s6, s54, 0x50000000
	s_addc_u32 s7, s55, 0
	s_lshl_b32 s14, s52, 9
	v_lshlrev_b32_e32 v15, 3, v14
	s_lshl_b32 s15, s52, 12
	s_mov_b64 s[8:9], 0
	s_cmpk_lg_i32 s52, 0x100
	s_cbranch_scc1 .Lsf_old
	s_lshl_b32 s28, s14, 1
	s_mul_i32 s29, s14, 3
	s_lshl_b32 s17, s14, 2
	s_mov_b32 s16, 4
.Lsf_loop:
	v_mov_b32_e32 v16, v14
	v_and_b32_e32 v17, 0x1ff, v16
	v_lshlrev_b32_e32 v17, 4, v17
	v_bfe_u32 v18, v16, 9, 1
	v_lshrrev_b32_e32 v19, 10, v16
	v_lshlrev_b32_e32 v16, 15, v19
	v_lshl_add_u32 v16, v18, 14, v16
	v_lshlrev_b32_e32 v30, 14, v19
	v_lshl_add_u32 v30, v18, 13, v30
	v_add_u32_e32 v30, v30, v17
	v_add_u32_e32 v19, v16, v17
	v_sub_u32_e32 v29, v16, v17
	v_add_u32_e32 v29, 0x3ff0, v29
	global_load_dwordx4 v[20:23], v19, s[2:3]
	global_load_dwordx4 v[24:27], v29, s[2:3]
	global_load_dword v28, v29, s[2:3] offset:16
	v_add_u32_e32 v48, s14, v14
	v_and_b32_e32 v49, 0x1ff, v48
	v_lshlrev_b32_e32 v49, 4, v49
	v_bfe_u32 v50, v48, 9, 1
	v_lshrrev_b32_e32 v51, 10, v48
	v_lshlrev_b32_e32 v48, 15, v51
	v_lshl_add_u32 v48, v50, 14, v48
	v_lshlrev_b32_e32 v62, 14, v51
	v_lshl_add_u32 v62, v50, 13, v62
	v_add_u32_e32 v62, v62, v49
	v_add_u32_e32 v51, v48, v49
	v_sub_u32_e32 v61, v48, v49
	v_add_u32_e32 v61, 0x3ff0, v61
	global_load_dwordx4 v[52:55], v51, s[2:3]
	global_load_dwordx4 v[56:59], v61, s[2:3]
	global_load_dword v60, v61, s[2:3] offset:16
	v_add_u32_e32 v80, s28, v14
	v_and_b32_e32 v81, 0x1ff, v80
	v_lshlrev_b32_e32 v81, 4, v81
	v_bfe_u32 v82, v80, 9, 1
	v_lshrrev_b32_e32 v83, 10, v80
	v_lshlrev_b32_e32 v80, 15, v83
	v_lshl_add_u32 v80, v82, 14, v80
	v_lshlrev_b32_e32 v94, 14, v83
	v_lshl_add_u32 v94, v82, 13, v94
	v_add_u32_e32 v94, v94, v81
	v_add_u32_e32 v83, v80, v81
	v_sub_u32_e32 v93, v80, v81
	v_add_u32_e32 v93, 0x3ff0, v93
	global_load_dwordx4 v[84:87], v83, s[2:3]
	global_load_dwordx4 v[88:91], v93, s[2:3]
	global_load_dword v92, v93, s[2:3] offset:16
	v_add_u32_e32 v112, s29, v14
	v_and_b32_e32 v113, 0x1ff, v112
	v_lshlrev_b32_e32 v113, 4, v113
	v_bfe_u32 v114, v112, 9, 1
	v_lshrrev_b32_e32 v115, 10, v112
	v_lshlrev_b32_e32 v112, 15, v115
	v_lshl_add_u32 v112, v114, 14, v112
	v_lshlrev_b32_e32 v126, 14, v115
	v_lshl_add_u32 v126, v114, 13, v126
	v_add_u32_e32 v126, v126, v113
	v_add_u32_e32 v115, v112, v113
	v_sub_u32_e32 v125, v112, v113
	v_add_u32_e32 v125, 0x3ff0, v125
	global_load_dwordx4 v[116:119], v115, s[2:3]
	global_load_dwordx4 v[120:123], v125, s[2:3]
	global_load_dword v124, v125, s[2:3] offset:16
	s_waitcnt vmcnt(9)
	v_lshlrev_b32_e32 v31, 31, v18
	v_cmp_ne_u32_e64 s[10:11], 0, v18
	v_cmp_eq_u32_e32 vcc, 0, v17
	v_lshlrev_b32_e32 v44, 16, v20
	v_and_b32_e32 v20, 0xffff0000, v20
	v_lshlrev_b32_e32 v45, 16, v21
	v_and_b32_e32 v21, 0xffff0000, v21
	v_lshlrev_b32_e32 v46, 16, v22
	v_and_b32_e32 v22, 0xffff0000, v22
	v_lshlrev_b32_e32 v47, 16, v23
	v_and_b32_e32 v23, 0xffff0000, v23
	v_lshlrev_b32_e32 v32, 16, v28
	v_and_b32_e32 v33, 0xffff0000, v27
	v_lshlrev_b32_e32 v34, 16, v27
	v_and_b32_e32 v35, 0xffff0000, v26
	v_lshlrev_b32_e32 v36, 16, v26
	v_and_b32_e32 v37, 0xffff0000, v25
	v_lshlrev_b32_e32 v38, 16, v25
	v_and_b32_e32 v39, 0xffff0000, v24
	v_cndmask_b32_e64 v28, 0, v44, s[10:11]
	v_cndmask_b32_e32 v32, v32, v28, vcc
	v_xor_b32_e32 v32, v31, v32
	v_xor_b32_e32 v33, v31, v33
	v_xor_b32_e32 v34, v31, v34
	v_xor_b32_e32 v35, v31, v35
	v_xor_b32_e32 v36, v31, v36
	v_xor_b32_e32 v37, v31, v37
	v_xor_b32_e32 v38, v31, v38
	v_xor_b32_e32 v39, v31, v39
	v_add_f32_e32 v32, v32, v44
	v_add_f32_e32 v33, v33, v20
	v_add_f32_e32 v34, v34, v45
	v_add_f32_e32 v35, v35, v21
	v_add_f32_e32 v36, v36, v46
	v_add_f32_e32 v37, v37, v22
	v_add_f32_e32 v38, v38, v47
	v_add_f32_e32 v39, v39, v23
	v_cvt_pk_bf16_f32 v40, v32, v33
	v_cvt_pk_bf16_f32 v41, v34, v35
	v_cvt_pk_bf16_f32 v42, v36, v37
	v_cvt_pk_bf16_f32 v43, v38, v39
	global_store_dwordx4 v30, v[40:43], s[6:7]
	s_waitcnt vmcnt(7)
	v_lshlrev_b32_e32 v63, 31, v50
	v_cmp_ne_u32_e64 s[10:11], 0, v50
	v_cmp_eq_u32_e32 vcc, 0, v49
	v_lshlrev_b32_e32 v76, 16, v52
	v_and_b32_e32 v52, 0xffff0000, v52
	v_lshlrev_b32_e32 v77, 16, v53
	v_and_b32_e32 v53, 0xffff0000, v53
	v_lshlrev_b32_e32 v78, 16, v54
	v_and_b32_e32 v54, 0xffff0000, v54
	v_lshlrev_b32_e32 v79, 16, v55
	v_and_b32_e32 v55, 0xffff0000, v55
	v_lshlrev_b32_e32 v64, 16, v60
	v_and_b32_e32 v65, 0xffff0000, v59
	v_lshlrev_b32_e32 v66, 16, v59
	v_and_b32_e32 v67, 0xffff0000, v58
	v_lshlrev_b32_e32 v68, 16, v58
	v_and_b32_e32 v69, 0xffff0000, v57
	v_lshlrev_b32_e32 v70, 16, v57
	v_and_b32_e32 v71, 0xffff0000, v56
	v_cndmask_b32_e64 v60, 0, v76, s[10:11]
	v_cndmask_b32_e32 v64, v64, v60, vcc
	v_xor_b32_e32 v64, v63, v64
	v_xor_b32_e32 v65, v63, v65
	v_xor_b32_e32 v66, v63, v66
	v_xor_b32_e32 v67, v63, v67
	v_xor_b32_e32 v68, v63, v68
	v_xor_b32_e32 v69, v63, v69
	v_xor_b32_e32 v70, v63, v70
	v_xor_b32_e32 v71, v63, v71
	v_add_f32_e32 v64, v64, v76
	v_add_f32_e32 v65, v65, v52
	v_add_f32_e32 v66, v66, v77
	v_add_f32_e32 v67, v67, v53
	v_add_f32_e32 v68, v68, v78
	v_add_f32_e32 v69, v69, v54
	v_add_f32_e32 v70, v70, v79
	v_add_f32_e32 v71, v71, v55
	v_cvt_pk_bf16_f32 v72, v64, v65
	v_cvt_pk_bf16_f32 v73, v66, v67
	v_cvt_pk_bf16_f32 v74, v68, v69
	v_cvt_pk_bf16_f32 v75, v70, v71
	global_store_dwordx4 v62, v[72:75], s[6:7]
	s_waitcnt vmcnt(5)
; __device__ __forceinline__ float bf_lo(unsigned u) { return __uint_as_float(u << 16); }
; __device__ __forceinline__ float bf_hi(unsigned u) { return __uint_as_float(u & 0xffff0000u); }
; __global__ __launch_bounds__(512, 2)
; void hybrid_megakernel(Params p_in) {
;     ...
;         for (int i = bid * 512 + tid; i < 2048 * 2 * 512; i += G * 512) {
;           const int n = i >> 10, part = (i >> 9) & 1, s0 = (i & 511) * 8;
;           const bf16* row = ztp + (long)n * (2 * SEQ) + part * SEQ;
;           const u32x4 own = *reinterpret_cast<const u32x4*>(row + s0);
;           const u32x4 c1 = *reinterpret_cast<const u32x4*>(row + SEQ - s0 - 8);
;           const unsigned c2 = (s0 > 0) ? *reinterpret_cast<const unsigned*>(row + SEQ - s0) : 0u;
;           float o[8], m[8];
; #pragma unroll
;           for (int q = 0; q < 4; ++q) { o[2 * q] = bf_lo(own[q]); o[2 * q + 1] = bf_hi(own[q]); }
;           m[0] = bf_lo(c2);
;           m[1] = bf_hi(c1[3]); m[2] = bf_lo(c1[3]); m[3] = bf_hi(c1[2]); m[4] = bf_lo(c1[2]);
;           m[5] = bf_hi(c1[1]); m[6] = bf_lo(c1[1]); m[7] = bf_hi(c1[0]);
;           if (s0 == 0) m[0] = part ? o[0] : 0.f;
;           float r[8];
; #pragma unroll
;           for (int q = 0; q < 8; ++q) r[q] = part ? o[q] - m[q] : o[q] + m[q];
;           u32x4 w = {cvtpk(r[0], r[1]), cvtpk(r[2], r[3]), cvtpk(r[4], r[5]), cvtpk(r[6], r[7])};
;           *reinterpret_cast<u32x4*>(z2 + (long)n * SEQ + part * (SEQ / 2) + s0) = w;
;         }
	v_lshlrev_b32_e32 v95, 31, v82
	v_cmp_ne_u32_e64 s[10:11], 0, v82
	v_cmp_eq_u32_e32 vcc, 0, v81
	v_lshlrev_b32_e32 v108, 16, v84
	v_and_b32_e32 v84, 0xffff0000, v84
	v_lshlrev_b32_e32 v109, 16, v85
	v_and_b32_e32 v85, 0xffff0000, v85
	v_lshlrev_b32_e32 v110, 16, v86
	v_and_b32_e32 v86, 0xffff0000, v86
	v_lshlrev_b32_e32 v111, 16, v87
	v_and_b32_e32 v87, 0xffff0000, v87
	v_lshlrev_b32_e32 v96, 16, v92
	v_and_b32_e32 v97, 0xffff0000, v91
	v_lshlrev_b32_e32 v98, 16, v91
	v_and_b32_e32 v99, 0xffff0000, v90
	v_lshlrev_b32_e32 v100, 16, v90
	v_and_b32_e32 v101, 0xffff0000, v89
	v_lshlrev_b32_e32 v102, 16, v89
	v_and_b32_e32 v103, 0xffff0000, v88
	v_cndmask_b32_e64 v92, 0, v108, s[10:11]
	v_cndmask_b32_e32 v96, v96, v92, vcc
	v_xor_b32_e32 v96, v95, v96
	v_xor_b32_e32 v97, v95, v97
	v_xor_b32_e32 v98, v95, v98
	v_xor_b32_e32 v99, v95, v99
	v_xor_b32_e32 v100, v95, v100
	v_xor_b32_e32 v101, v95, v101
	v_xor_b32_e32 v102, v95, v102
	v_xor_b32_e32 v103, v95, v103
	v_add_f32_e32 v96, v96, v108
	v_add_f32_e32 v97, v97, v84
	v_add_f32_e32 v98, v98, v109
	v_add_f32_e32 v99, v99, v85
	v_add_f32_e32 v100, v100, v110
	v_add_f32_e32 v101, v101, v86
	v_add_f32_e32 v102, v102, v111
	v_add_f32_e32 v103, v103, v87
	v_cvt_pk_bf16_f32 v104, v96, v97
	v_cvt_pk_bf16_f32 v105, v98, v99
	v_cvt_pk_bf16_f32 v106, v100, v101
	v_cvt_pk_bf16_f32 v107, v102, v103
	global_store_dwordx4 v94, v[104:107], s[6:7]
	s_waitcnt vmcnt(3)
	v_lshlrev_b32_e32 v127, 31, v114
	v_cmp_ne_u32_e64 s[10:11], 0, v114
	v_cmp_eq_u32_e32 vcc, 0, v113
	v_lshlrev_b32_e32 v140, 16, v116
	v_and_b32_e32 v116, 0xffff0000, v116
	v_lshlrev_b32_e32 v141, 16, v117
	v_and_b32_e32 v117, 0xffff0000, v117
	v_lshlrev_b32_e32 v142, 16, v118
	v_and_b32_e32 v118, 0xffff0000, v118
	v_lshlrev_b32_e32 v143, 16, v119
	v_and_b32_e32 v119, 0xffff0000, v119
	v_lshlrev_b32_e32 v128, 16, v124
	v_and_b32_e32 v129, 0xffff0000, v123
	v_lshlrev_b32_e32 v130, 16, v123
	v_and_b32_e32 v131, 0xffff0000, v122
	v_lshlrev_b32_e32 v132, 16, v122
	v_and_b32_e32 v133, 0xffff0000, v121
	v_lshlrev_b32_e32 v134, 16, v121
	v_and_b32_e32 v135, 0xffff0000, v120
	v_cndmask_b32_e64 v124, 0, v140, s[10:11]
	v_cndmask_b32_e32 v128, v128, v124, vcc
	v_xor_b32_e32 v128, v127, v128
	v_xor_b32_e32 v129, v127, v129
	v_xor_b32_e32 v130, v127, v130
	v_xor_b32_e32 v131, v127, v131
	v_xor_b32_e32 v132, v127, v132
	v_xor_b32_e32 v133, v127, v133
	v_xor_b32_e32 v134, v127, v134
	v_xor_b32_e32 v135, v127, v135
	v_add_f32_e32 v128, v128, v140
	v_add_f32_e32 v129, v129, v116
	v_add_f32_e32 v130, v130, v141
	v_add_f32_e32 v131, v131, v117
	v_add_f32_e32 v132, v132, v142
	v_add_f32_e32 v133, v133, v118
	v_add_f32_e32 v134, v134, v143
	v_add_f32_e32 v135, v135, v119
	v_cvt_pk_bf16_f32 v136, v128, v129
	v_cvt_pk_bf16_f32 v137, v130, v131
	v_cvt_pk_bf16_f32 v138, v132, v133
	v_cvt_pk_bf16_f32 v139, v134, v135
	global_store_dwordx4 v126, v[136:139], s[6:7]
	v_add_u32_e32 v14, s17, v14
	s_sub_i32 s16, s16, 1
	s_cmp_lg_u32 s16, 0
	s_cbranch_scc1 .Lsf_loop
	s_branch .LBB0_205
.Lsf_old:
	s_branch .LBB0_202
.LBB0_201:
	s_or_b64 exec, exec, s[10:11]
	s_waitcnt vmcnt(0)
	v_lshlrev_b32_e32 v12, 16, v8
	v_cmp_eq_u32_e64 s[4:5], 0, v16
	v_and_b32_e32 v20, 0xffff0000, v7
	v_lshlrev_b32_e32 v7, 16, v7
	v_cndmask_b32_e64 v23, v12, 0, s[4:5]
	v_cndmask_b32_e32 v17, v17, v23, vcc
	v_lshlrev_b32_e32 v13, 16, v9
	v_and_b32_e32 v21, 0xffff0000, v6
	v_cndmask_b32_e64 v17, -v17, v17, s[4:5]
	v_cndmask_b32_e64 v7, -v7, v7, s[4:5]
	v_and_b32_e32 v8, 0xffff0000, v8
	v_and_b32_e32 v9, 0xffff0000, v9
	v_and_b32_e32 v22, 0xffff0000, v5
	v_lshlrev_b32_e32 v5, 16, v5
	v_and_b32_e32 v4, 0xffff0000, v4
	v_add_f32_e32 v12, v17, v12
	v_cndmask_b32_e64 v17, -v20, v20, s[4:5]
	v_add_f32_e32 v7, v7, v13
	v_cndmask_b32_e64 v13, -v21, v21, s[4:5]
	v_lshlrev_b32_e32 v18, 16, v10
	v_and_b32_e32 v10, 0xffff0000, v10
	v_lshlrev_b32_e32 v19, 16, v11
	v_and_b32_e32 v11, 0xffff0000, v11
	v_lshlrev_b32_e32 v6, 16, v6
	v_add_f32_e32 v8, v17, v8
	v_add_f32_e32 v9, v13, v9
	v_cndmask_b32_e64 v13, -v22, v22, s[4:5]
	v_cndmask_b32_e64 v5, -v5, v5, s[4:5]
	v_cndmask_b32_e64 v4, -v4, v4, s[4:5]
	v_lshlrev_b64 v[0:1], 14, v[0:1]
	v_cndmask_b32_e64 v6, -v6, v6, s[4:5]
	v_add_f32_e32 v10, v13, v10
	v_add_f32_e32 v13, v5, v19
	v_add_f32_e32 v11, v4, v11
	v_cvt_pk_bf16_f32 v4, v12, v8
	v_cvt_pk_bf16_f32 v5, v7, v9
	v_lshl_add_u64 v[0:1], s[6:7], 0, v[0:1]
	v_lshlrev_b32_e32 v8, 13, v16
	v_mov_b32_e32 v9, v3
	v_add_u32_e32 v14, s14, v14
	s_mov_b32 s4, 0x1fffff
	v_lshl_add_u64 v[0:1], v[0:1], 0, v[8:9]
	v_cmp_lt_i32_e32 vcc, s4, v14
	v_add_f32_e32 v6, v6, v18
	v_lshl_add_u64 v[0:1], v[0:1], 0, v[2:3]
	s_or_b64 s[8:9], vcc, s[8:9]
	v_add_u32_e32 v15, s15, v15
	v_cvt_pk_bf16_f32 v6, v6, v10
	v_cvt_pk_bf16_f32 v7, v13, v11
	global_store_dwordx4 v[0:1], v[4:7], off
	s_andn2_b64 exec, exec, s[8:9]
	s_cbranch_execz .LBB0_205
